# HG_IN GEMM epilogue: lower-bound (LBv) loads hoisted out of the 16 store-interleaved blocks, one wait instead of 16
# speedup vs baseline: 1.0016x; 1.0016x over previous
; #define PG8_STAGE(bufoff, gbase, voff) do { _Pragma("unroll") for (int _i = 0; _i < 2; ++_i) \
;         __builtin_amdgcn_global_load_lds((const unsigned*)((const char*)(gbase) + (voff)[_i]), (LAS unsigned*)(lds + (bufoff) + ldsw + _i * 8192), 16, 0, 0); } while (0)
; #define PG8_LDA(dst, b, h) do { _Pragma("unroll") for (int m = 0; m < 4; ++m) _Pragma("unroll") for (int k = 0; k < 2; ++k) dst[m][k] = *(const LAS bf16x8*)(lds + PG8_SA(b, h) + aoff + m * 2048 + k * 1024); } while (0)
; #define PG8_WAIT_V(n) asm volatile("s_waitcnt vmcnt(" #n ")" ::: "memory")
; #define PG8_WAIT_L(n) asm volatile("s_waitcnt lgkmcnt(" #n ")" ::: "memory")
; template <class Epi>
; __device__ __forceinline__ void gemm_phase(LAS unsigned char* lds, const Gemm g, const StaticOrder& S, const Epi& E) {
;     ...
;         for (int t = 0; t < nt; t += 2) {
;             const bool last = (t == nt - 2);
;             const char* a1 = cA + (size_t)(t + 1) * kstep;
;             const char* a2 = last ? nA : cA + (size_t)(t + 2) * kstep; const char* b2 = last ? nB : cB + (size_t)(t + 2) * kstep;
;             const char* a3 = a2 + kstep; const char* b3 = b2 + kstep;
;             PG8_LDB(B0, 0, 0); PG8_SCHED; PG8_LDA(At, 0, 0); PG8_STAGE(PG8_SA(1, 1), a1 + hstep, voffA);
;             PG8_WAIT_L(8); PG8_BAR; PG8_WAIT_L(0); PG8_MMA(0, 0, At, B0); PG8_BAR; PG8_SCHED;
;             PG8_LDB(B1, 0, 1); PG8_STAGE(PG8_SB(0, 0), b2, voffB);
;             PG8_BAR; PG8_WAIT_L(0); PG8_MMA(0, 1, At, B1); PG8_BAR;
;             PG8_LDA(At, 0, 1); PG8_STAGE(PG8_SA(0, 0), a2, voffA);
;             PG8_BAR; PG8_WAIT_L(0); PG8_MMA(1, 0, At, B0); PG8_BAR; PG8_SCHED;
;             PG8_STAGE(PG8_SB(0, 1), b2 + hstep, voffB);
;             PG8_WAIT_V(6); PG8_BAR; PG8_MMA(1, 1, At, B1); PG8_BAR;
;             PG8_LDB(B0, 1, 0); PG8_SCHED; PG8_LDA(At, 1, 0); PG8_STAGE(PG8_SA(0, 1), a2 + hstep, voffA);
;             PG8_WAIT_L(8); PG8_BAR; PG8_WAIT_L(0); PG8_MMA(0, 0, At, B0); PG8_BAR; PG8_SCHED;
;             PG8_LDB(B1, 1, 1); PG8_STAGE(PG8_SB(1, 0), b3, voffB);
;             PG8_BAR; PG8_WAIT_L(0); PG8_MMA(0, 1, At, B1); PG8_BAR;
;             PG8_LDA(At, 1, 1); PG8_STAGE(PG8_SA(1, 0), a3, voffA);
;             PG8_BAR; PG8_WAIT_L(0); PG8_MMA(1, 0, At, B0); PG8_BAR; PG8_SCHED;
;             PG8_STAGE(PG8_SB(1, 1), b3 + hstep, voffB);
;             PG8_WAIT_V(6); PG8_BAR; PG8_MMA(1, 1, At, B1); PG8_BAR;
.LBB0_691:
	ds_read_b128 v[150:153], v167
	ds_read_b128 v[154:157], v167 offset:1024
	ds_read_b128 v[158:161], v167 offset:2048
	ds_read_b128 v[180:183], v167 offset:3072
	s_add_u32 s8, s6, 0xfff80080
	s_addc_u32 s9, s7, -1
	s_cmp_eq_u32 s63, 28
	s_cselect_b32 s11, s1, s9
	s_cselect_b32 s10, s5, s8
	s_cselect_b32 s9, s12, s61
	s_cselect_b32 s8, s13, s33
	v_lshl_add_u64 v[162:163], s[6:7], 0, v[140:141]
	s_add_i32 m0, s74, 0xc000
	ds_read_b128 v[184:187], v168
	ds_read_b128 v[188:191], v168 offset:1024
	ds_read_b128 v[192:195], v168 offset:2048
	ds_read_b128 v[196:199], v168 offset:3072
	ds_read_b128 v[200:203], v168 offset:4096
	ds_read_b128 v[204:207], v168 offset:5120
	ds_read_b128 v[208:211], v168 offset:6144
	ds_read_b128 v[212:215], v168 offset:7168
	global_load_lds_dwordx4 v[162:163], off
	v_lshl_add_u64 v[162:163], s[6:7], 0, v[142:143]
	s_add_i32 m0, s74, 0xe000
	s_nop 0
	global_load_lds_dwordx4 v[162:163], off
	s_waitcnt lgkmcnt(8)
	s_barrier
	s_waitcnt lgkmcnt(0)
	s_setprio 1
	s_waitcnt lgkmcnt(0)
	v_mfma_f32_16x16x32_bf16 v[124:127], v[150:153], v[184:187], v[124:127]
	v_mfma_f32_16x16x32_bf16 v[120:123], v[158:161], v[184:187], v[120:123]
	v_mfma_f32_16x16x32_bf16 v[108:111], v[150:153], v[192:195], v[108:111]
	v_mfma_f32_16x16x32_bf16 v[104:107], v[158:161], v[192:195], v[104:107]
	v_mfma_f32_16x16x32_bf16 v[92:95], v[150:153], v[200:203], v[92:95]
	v_mfma_f32_16x16x32_bf16 v[88:91], v[158:161], v[200:203], v[88:91]
	v_mfma_f32_16x16x32_bf16 v[76:79], v[150:153], v[208:211], v[76:79]
	v_mfma_f32_16x16x32_bf16 v[72:75], v[158:161], v[208:211], v[72:75]
	v_mfma_f32_16x16x32_bf16 v[124:127], v[154:157], v[188:191], v[124:127]
	v_mfma_f32_16x16x32_bf16 v[120:123], v[180:183], v[188:191], v[120:123]
	v_mfma_f32_16x16x32_bf16 v[108:111], v[154:157], v[196:199], v[108:111]
	v_mfma_f32_16x16x32_bf16 v[104:107], v[180:183], v[196:199], v[104:107]
	v_mfma_f32_16x16x32_bf16 v[92:95], v[154:157], v[204:207], v[92:95]
	v_mfma_f32_16x16x32_bf16 v[88:91], v[180:183], v[204:207], v[88:91]
	v_mfma_f32_16x16x32_bf16 v[76:79], v[154:157], v[212:215], v[76:79]
	v_mfma_f32_16x16x32_bf16 v[72:75], v[180:183], v[212:215], v[72:75]
	s_setprio 0
	s_barrier
	s_add_i32 s89, s84, s69
	v_lshl_add_u64 v[162:163], s[8:9], 0, v[130:131]
	s_mov_b32 m0, s89
	ds_read_b128 v[216:219], v169
	ds_read_b128 v[220:223], v169 offset:1024
	ds_read_b128 v[224:227], v169 offset:2048
	ds_read_b128 v[228:231], v169 offset:3072
	global_load_lds_dwordx4 v[162:163], off
	v_lshl_add_u64 v[232:233], s[8:9], 0, v[134:135]
	s_add_i32 m0, s89, 0x2000
	s_nop 0
	global_load_lds_dwordx4 v[232:233], off
	s_barrier
	s_waitcnt lgkmcnt(0)
	s_setprio 1
	s_waitcnt lgkmcnt(0)
	v_mfma_f32_16x16x32_bf16 v[116:119], v[216:219], v[184:187], v[116:119]
	v_mfma_f32_16x16x32_bf16 v[112:115], v[224:227], v[184:187], v[112:115]
	v_mfma_f32_16x16x32_bf16 v[100:103], v[216:219], v[192:195], v[100:103]
	v_mfma_f32_16x16x32_bf16 v[96:99], v[224:227], v[192:195], v[96:99]
	v_mfma_f32_16x16x32_bf16 v[84:87], v[216:219], v[200:203], v[84:87]
	v_mfma_f32_16x16x32_bf16 v[80:83], v[224:227], v[200:203], v[80:83]
	v_mfma_f32_16x16x32_bf16 v[68:71], v[216:219], v[208:211], v[68:71]
	v_mfma_f32_16x16x32_bf16 v[64:67], v[224:227], v[208:211], v[64:67]
	v_mfma_f32_16x16x32_bf16 v[116:119], v[220:223], v[188:191], v[116:119]
	v_mfma_f32_16x16x32_bf16 v[112:115], v[228:231], v[188:191], v[112:115]
	v_mfma_f32_16x16x32_bf16 v[100:103], v[220:223], v[196:199], v[100:103]
	v_mfma_f32_16x16x32_bf16 v[96:99], v[228:231], v[196:199], v[96:99]
	v_mfma_f32_16x16x32_bf16 v[84:87], v[220:223], v[204:207], v[84:87]
	v_mfma_f32_16x16x32_bf16 v[80:83], v[228:231], v[204:207], v[80:83]
	v_mfma_f32_16x16x32_bf16 v[68:71], v[220:223], v[212:215], v[68:71]
	v_mfma_f32_16x16x32_bf16 v[64:67], v[228:231], v[212:215], v[64:67]
	s_setprio 0
	s_mov_b32 m0, s74
	v_lshl_add_u64 v[234:235], s[10:11], 0, v[128:129]
	s_barrier
	ds_read_b128 v[184:187], v168 offset:16384
	ds_read_b128 v[188:191], v168 offset:17408
	ds_read_b128 v[192:195], v168 offset:18432
	ds_read_b128 v[196:199], v168 offset:19456
	ds_read_b128 v[200:203], v168 offset:20480
	ds_read_b128 v[204:207], v168 offset:21504
	ds_read_b128 v[208:211], v168 offset:22528
	ds_read_b128 v[212:215], v168 offset:23552
	global_load_lds_dwordx4 v[234:235], off
	v_lshl_add_u64 v[236:237], s[10:11], 0, v[132:133]
	s_mov_b32 m0, s75
	s_nop 0
	global_load_lds_dwordx4 v[236:237], off
	s_barrier
	s_waitcnt lgkmcnt(0)
	s_setprio 1
	s_waitcnt lgkmcnt(0)
	v_mfma_f32_16x16x32_bf16 v[60:63], v[150:153], v[184:187], v[60:63]
	v_mfma_f32_16x16x32_bf16 v[56:59], v[158:161], v[184:187], v[56:59]
	v_mfma_f32_16x16x32_bf16 v[44:47], v[150:153], v[192:195], v[44:47]
	v_mfma_f32_16x16x32_bf16 v[40:43], v[158:161], v[192:195], v[40:43]
	v_mfma_f32_16x16x32_bf16 v[28:31], v[150:153], v[200:203], v[28:31]
	v_mfma_f32_16x16x32_bf16 v[24:27], v[158:161], v[200:203], v[24:27]
	v_mfma_f32_16x16x32_bf16 v[12:15], v[150:153], v[208:211], v[12:15]
	v_mfma_f32_16x16x32_bf16 v[8:11], v[158:161], v[208:211], v[8:11]
	v_mfma_f32_16x16x32_bf16 v[60:63], v[154:157], v[188:191], v[60:63]
	v_mfma_f32_16x16x32_bf16 v[56:59], v[180:183], v[188:191], v[56:59]
	v_mfma_f32_16x16x32_bf16 v[44:47], v[154:157], v[196:199], v[44:47]
	v_mfma_f32_16x16x32_bf16 v[40:43], v[180:183], v[196:199], v[40:43]
	v_mfma_f32_16x16x32_bf16 v[28:31], v[154:157], v[204:207], v[28:31]
	v_mfma_f32_16x16x32_bf16 v[24:27], v[180:183], v[204:207], v[24:27]
	v_mfma_f32_16x16x32_bf16 v[12:15], v[154:157], v[212:215], v[12:15]
	v_mfma_f32_16x16x32_bf16 v[8:11], v[180:183], v[212:215], v[8:11]
	s_setprio 0
	s_barrier
; #define PG8_STAGE(bufoff, gbase, voff) do { _Pragma("unroll") for (int _i = 0; _i < 2; ++_i) \
;         __builtin_amdgcn_global_load_lds((const unsigned*)((const char*)(gbase) + (voff)[_i]), (LAS unsigned*)(lds + (bufoff) + ldsw + _i * 8192), 16, 0, 0); } while (0)
; #define PG8_LDA(dst, b, h) do { _Pragma("unroll") for (int m = 0; m < 4; ++m) _Pragma("unroll") for (int k = 0; k < 2; ++k) dst[m][k] = *(const LAS bf16x8*)(lds + PG8_SA(b, h) + aoff + m * 2048 + k * 1024); } while (0)
; #define PG8_LDB(dst, b, h) do { _Pragma("unroll") for (int n = 0; n < 2; ++n) _Pragma("unroll") for (int k = 0; k < 2; ++k) dst[n][k] = *(const LAS bf16x8*)(lds + PG8_SB(b, h) + boff + n * 2048 + k * 1024); } while (0)
; #define PG8_MMA(ai, bj, At, Bt) do { __builtin_amdgcn_s_setprio(1); _Pragma("unroll") for (int m = 0; m < 4; ++m) _Pragma("unroll") for (int n = 0; n < 2; ++n) _Pragma("unroll") for (int k = 0; k < 2; ++k) \
;         acc[ai][bj][m][n] = __builtin_amdgcn_mfma_f32_16x16x32_bf16(Bt[n][k], At[m][k], acc[ai][bj][m][n], 0, 0, 0); __builtin_amdgcn_s_setprio(0); } while (0)
; #define PG8_WAIT_V(n) asm volatile("s_waitcnt vmcnt(" #n ")" ::: "memory")
; #define PG8_WAIT_L(n) asm volatile("s_waitcnt lgkmcnt(" #n ")" ::: "memory")
; #define PG8_BAR __builtin_amdgcn_s_barrier()
; template <class Epi>
; __device__ __forceinline__ void gemm_phase(LAS unsigned char* lds, const Gemm g, const StaticOrder& S, const Epi& E) {
;     ...
;             PG8_LDB(B0, 0, 0); PG8_SCHED; PG8_LDA(At, 0, 0); PG8_STAGE(PG8_SA(1, 1), a1 + hstep, voffA);
;             PG8_WAIT_L(8); PG8_BAR; PG8_WAIT_L(0); PG8_MMA(0, 0, At, B0); PG8_BAR; PG8_SCHED;
;             PG8_LDB(B1, 0, 1); PG8_STAGE(PG8_SB(0, 0), b2, voffB);
;             PG8_BAR; PG8_WAIT_L(0); PG8_MMA(0, 1, At, B1); PG8_BAR;
;             PG8_LDA(At, 0, 1); PG8_STAGE(PG8_SA(0, 0), a2, voffA);
;             PG8_BAR; PG8_WAIT_L(0); PG8_MMA(1, 0, At, B0); PG8_BAR; PG8_SCHED;
;             PG8_STAGE(PG8_SB(0, 1), b2 + hstep, voffB);
;             PG8_WAIT_V(6); PG8_BAR; PG8_MMA(1, 1, At, B1); PG8_BAR;
;             PG8_LDB(B0, 1, 0); PG8_SCHED; PG8_LDA(At, 1, 0); PG8_STAGE(PG8_SA(0, 1), a2 + hstep, voffA);
;             PG8_WAIT_L(8); PG8_BAR; PG8_WAIT_L(0); PG8_MMA(0, 0, At, B0); PG8_BAR; PG8_SCHED;
;             PG8_LDB(B1, 1, 1); PG8_STAGE(PG8_SB(1, 0), b3, voffB);
;             PG8_BAR; PG8_WAIT_L(0); PG8_MMA(0, 1, At, B1); PG8_BAR;
	s_add_u32 s90, s8, 0x80000
	s_addc_u32 s91, s9, 0
	s_add_i32 s89, s85, s69
	v_lshl_add_u64 v[150:151], s[90:91], 0, v[130:131]
	s_mov_b32 m0, s89
	s_nop 0
	global_load_lds_dwordx4 v[150:151], off
	v_lshl_add_u64 v[150:151], s[90:91], 0, v[134:135]
	s_add_i32 m0, s89, 0x2000
	s_nop 0
	global_load_lds_dwordx4 v[150:151], off
	s_waitcnt vmcnt(6)
	s_barrier
	s_setprio 1
	v_mfma_f32_16x16x32_bf16 v[52:55], v[216:219], v[184:187], v[52:55]
	v_mfma_f32_16x16x32_bf16 v[48:51], v[224:227], v[184:187], v[48:51]
	v_mfma_f32_16x16x32_bf16 v[36:39], v[216:219], v[192:195], v[36:39]
	v_mfma_f32_16x16x32_bf16 v[32:35], v[224:227], v[192:195], v[32:35]
	v_mfma_f32_16x16x32_bf16 v[20:23], v[216:219], v[200:203], v[20:23]
	v_mfma_f32_16x16x32_bf16 v[16:19], v[224:227], v[200:203], v[16:19]
	v_mfma_f32_16x16x32_bf16 v[4:7], v[216:219], v[208:211], v[4:7]
	v_mfma_f32_16x16x32_bf16 v[0:3], v[224:227], v[208:211], v[0:3]
	v_mfma_f32_16x16x32_bf16 v[52:55], v[220:223], v[188:191], v[52:55]
	v_mfma_f32_16x16x32_bf16 v[48:51], v[228:231], v[188:191], v[48:51]
	v_mfma_f32_16x16x32_bf16 v[36:39], v[220:223], v[196:199], v[36:39]
	v_mfma_f32_16x16x32_bf16 v[32:35], v[228:231], v[196:199], v[32:35]
	v_mfma_f32_16x16x32_bf16 v[20:23], v[220:223], v[204:207], v[20:23]
	v_mfma_f32_16x16x32_bf16 v[16:19], v[228:231], v[204:207], v[16:19]
	v_mfma_f32_16x16x32_bf16 v[4:7], v[220:223], v[212:215], v[4:7]
	v_mfma_f32_16x16x32_bf16 v[0:3], v[228:231], v[212:215], v[0:3]
	s_setprio 0
	s_add_i32 s89, 0, 0x18000
	v_add_u32_e32 v138, s89, v165
	s_barrier
	ds_read_b128 v[150:153], v138
	ds_read_b128 v[154:157], v138 offset:1024
	ds_read_b128 v[158:161], v138 offset:2048
	ds_read_b128 v[180:183], v138 offset:3072
	s_add_u32 s10, s10, 0x80000
	s_addc_u32 s11, s11, 0
	s_mov_b32 m0, s76
	v_lshl_add_u64 v[216:217], s[10:11], 0, v[128:129]
	ds_read_b128 v[184:187], v168 offset:32768
	ds_read_b128 v[188:191], v168 offset:33792
	ds_read_b128 v[192:195], v168 offset:34816
	ds_read_b128 v[196:199], v168 offset:35840
	ds_read_b128 v[200:203], v168 offset:36864
	ds_read_b128 v[204:207], v168 offset:37888
	ds_read_b128 v[208:211], v168 offset:38912
	ds_read_b128 v[212:215], v168 offset:39936
	global_load_lds_dwordx4 v[216:217], off
	v_lshl_add_u64 v[216:217], s[10:11], 0, v[132:133]
	s_mov_b32 m0, s77
	s_nop 0
	global_load_lds_dwordx4 v[216:217], off
	s_waitcnt lgkmcnt(8)
	s_barrier
	s_waitcnt lgkmcnt(0)
	s_setprio 1
	s_waitcnt lgkmcnt(0)
	v_mfma_f32_16x16x32_bf16 v[124:127], v[150:153], v[184:187], v[124:127]
	v_mfma_f32_16x16x32_bf16 v[120:123], v[158:161], v[184:187], v[120:123]
	v_mfma_f32_16x16x32_bf16 v[108:111], v[150:153], v[192:195], v[108:111]
	v_mfma_f32_16x16x32_bf16 v[104:107], v[158:161], v[192:195], v[104:107]
	v_mfma_f32_16x16x32_bf16 v[92:95], v[150:153], v[200:203], v[92:95]
	v_mfma_f32_16x16x32_bf16 v[88:91], v[158:161], v[200:203], v[88:91]
	v_mfma_f32_16x16x32_bf16 v[76:79], v[150:153], v[208:211], v[76:79]
	v_mfma_f32_16x16x32_bf16 v[72:75], v[158:161], v[208:211], v[72:75]
	v_mfma_f32_16x16x32_bf16 v[124:127], v[154:157], v[188:191], v[124:127]
	v_mfma_f32_16x16x32_bf16 v[120:123], v[180:183], v[188:191], v[120:123]
	v_mfma_f32_16x16x32_bf16 v[108:111], v[154:157], v[196:199], v[108:111]
	v_mfma_f32_16x16x32_bf16 v[104:107], v[180:183], v[196:199], v[104:107]
	v_mfma_f32_16x16x32_bf16 v[92:95], v[154:157], v[204:207], v[92:95]
	v_mfma_f32_16x16x32_bf16 v[88:91], v[180:183], v[204:207], v[88:91]
	v_mfma_f32_16x16x32_bf16 v[76:79], v[154:157], v[212:215], v[76:79]
	v_mfma_f32_16x16x32_bf16 v[72:75], v[180:183], v[212:215], v[72:75]
	s_setprio 0
	s_barrier
	s_add_i32 s10, 0, 0x1c000
	s_add_i32 s11, s89, s69
	v_add_u32_e32 v138, s10, v165
	v_lshl_add_u64 v[162:163], v[162:163], 0, s[34:35]
	s_mov_b32 m0, s11
	ds_read_b128 v[216:219], v138
	ds_read_b128 v[220:223], v138 offset:1024
	ds_read_b128 v[224:227], v138 offset:2048
	ds_read_b128 v[228:231], v138 offset:3072
	global_load_lds_dwordx4 v[162:163], off
	v_lshl_add_u64 v[162:163], v[232:233], 0, s[34:35]
	s_add_i32 m0, s11, 0x2000
	s_nop 0
	global_load_lds_dwordx4 v[162:163], off
	s_barrier
	s_waitcnt lgkmcnt(0)
	s_setprio 1
	s_waitcnt lgkmcnt(0)
	v_mfma_f32_16x16x32_bf16 v[116:119], v[216:219], v[184:187], v[116:119]
	v_mfma_f32_16x16x32_bf16 v[112:115], v[224:227], v[184:187], v[112:115]
	v_mfma_f32_16x16x32_bf16 v[100:103], v[216:219], v[192:195], v[100:103]
	v_mfma_f32_16x16x32_bf16 v[96:99], v[224:227], v[192:195], v[96:99]
	v_mfma_f32_16x16x32_bf16 v[84:87], v[216:219], v[200:203], v[84:87]
	v_mfma_f32_16x16x32_bf16 v[80:83], v[224:227], v[200:203], v[80:83]
	v_mfma_f32_16x16x32_bf16 v[68:71], v[216:219], v[208:211], v[68:71]
	v_mfma_f32_16x16x32_bf16 v[64:67], v[224:227], v[208:211], v[64:67]
	v_mfma_f32_16x16x32_bf16 v[116:119], v[220:223], v[188:191], v[116:119]
	v_mfma_f32_16x16x32_bf16 v[112:115], v[228:231], v[188:191], v[112:115]
	v_mfma_f32_16x16x32_bf16 v[100:103], v[220:223], v[196:199], v[100:103]
	v_mfma_f32_16x16x32_bf16 v[96:99], v[228:231], v[196:199], v[96:99]
	v_mfma_f32_16x16x32_bf16 v[84:87], v[220:223], v[204:207], v[84:87]
	v_mfma_f32_16x16x32_bf16 v[80:83], v[228:231], v[204:207], v[80:83]
	v_mfma_f32_16x16x32_bf16 v[68:71], v[220:223], v[212:215], v[68:71]
	v_mfma_f32_16x16x32_bf16 v[64:67], v[228:231], v[212:215], v[64:67]
	s_setprio 0
	s_mov_b32 m0, s79
	v_lshl_add_u64 v[162:163], v[234:235], 0, s[34:35]
	s_barrier
; __device__ __forceinline__ float sigmoidf_(float x) { return __builtin_amdgcn_rcpf(1.0f + fexp(-x)); }
; #define PG8_STAGE(bufoff, gbase, voff) do { _Pragma("unroll") for (int _i = 0; _i < 2; ++_i) \
;         __builtin_amdgcn_global_load_lds((const unsigned*)((const char*)(gbase) + (voff)[_i]), (LAS unsigned*)(lds + (bufoff) + ldsw + _i * 8192), 16, 0, 0); } while (0)
; #define PG8_LDA(dst, b, h) do { _Pragma("unroll") for (int m = 0; m < 4; ++m) _Pragma("unroll") for (int k = 0; k < 2; ++k) dst[m][k] = *(const LAS bf16x8*)(lds + PG8_SA(b, h) + aoff + m * 2048 + k * 1024); } while (0)
; #define PG8_WAIT_V(n) asm volatile("s_waitcnt vmcnt(" #n ")" ::: "memory")
; #define PG8_WAIT_L(n) asm volatile("s_waitcnt lgkmcnt(" #n ")" ::: "memory")
; template <class Epi>
; __device__ __forceinline__ void gemm_phase(LAS unsigned char* lds, const Gemm g, const StaticOrder& S, const Epi& E) {
;     ...
;             PG8_LDA(At, 1, 1); PG8_STAGE(PG8_SA(1, 0), a3, voffA);
;             PG8_BAR; PG8_WAIT_L(0); PG8_MMA(1, 0, At, B0); PG8_BAR; PG8_SCHED;
;             PG8_STAGE(PG8_SB(1, 1), b3 + hstep, voffB);
;             PG8_WAIT_V(6); PG8_BAR; PG8_MMA(1, 1, At, B1); PG8_BAR;
;     __device__ __forceinline__ void operator()(const f32x4 (&acc)[2][2][4][2], const Unit& u, int wr, int wc, int fr, int fq, const Pre& P) const {
;         const int sec = u.pn >> 3, row0 = ROW_X + u.pm * BM + wr * 64 + fr, colb = (u.pn & 7) * BM + wc * 32 + 8 * fq;
; #pragma unroll
;         for (int ai = 0; ai < 2; ++ai)
; #pragma unroll
;             for (int m = 0; m < 4; ++m) { const int r = row0 + ai * HALF + m * 16; const float rs = __builtin_amdgcn_rsqf(P.rs[ai * 4 + m] * (1.0f / DM) + RMS_EPS);
; #pragma unroll
;                 for (int bj = 0; bj < 2; ++bj) { const int c = colb + bj * HALF; const size_t off = (size_t)r * DM + c; float x[8], y[8];
; #pragma unroll
;                     for (int n = 0; n < 2; ++n)
; #pragma unroll
;                         for (int j = 0; j < 4; ++j) x[n * 4 + j] = acc[ai][bj][m][n][j] * rs;
;                     bf16_t* dst;
;                     if (sec == 0) { dst = QB;
; #pragma unroll
;                         for (int j = 0; j < 8; ++j) y[j] = x[j] * sigmoidf_(x[j]); }
;                     else if (sec == 1) { dst = KB; const f32x4 l0 = *(const f32x4*)(LBv + c), l1 = *(const f32x4*)(LBv + c + 4); float lf[8];
	ds_read_b128 v[184:187], v168 offset:49152
	ds_read_b128 v[188:191], v168 offset:50176
	ds_read_b128 v[192:195], v168 offset:51200
	ds_read_b128 v[196:199], v168 offset:52224
	ds_read_b128 v[200:203], v168 offset:53248
	ds_read_b128 v[204:207], v168 offset:54272
	ds_read_b128 v[208:211], v168 offset:55296
	ds_read_b128 v[212:215], v168 offset:56320
	global_load_lds_dwordx4 v[162:163], off
	v_lshl_add_u64 v[162:163], v[236:237], 0, s[34:35]
	s_mov_b32 m0, s80
	s_nop 0
	global_load_lds_dwordx4 v[162:163], off
	s_barrier
	s_waitcnt lgkmcnt(0)
	s_setprio 1
	s_waitcnt lgkmcnt(0)
	v_mfma_f32_16x16x32_bf16 v[60:63], v[150:153], v[184:187], v[60:63]
	v_mfma_f32_16x16x32_bf16 v[56:59], v[158:161], v[184:187], v[56:59]
	v_mfma_f32_16x16x32_bf16 v[44:47], v[150:153], v[192:195], v[44:47]
	v_mfma_f32_16x16x32_bf16 v[40:43], v[158:161], v[192:195], v[40:43]
	v_mfma_f32_16x16x32_bf16 v[28:31], v[150:153], v[200:203], v[28:31]
	v_mfma_f32_16x16x32_bf16 v[24:27], v[158:161], v[200:203], v[24:27]
	v_mfma_f32_16x16x32_bf16 v[12:15], v[150:153], v[208:211], v[12:15]
	v_mfma_f32_16x16x32_bf16 v[8:11], v[158:161], v[208:211], v[8:11]
	v_mfma_f32_16x16x32_bf16 v[60:63], v[154:157], v[188:191], v[60:63]
	v_mfma_f32_16x16x32_bf16 v[56:59], v[180:183], v[188:191], v[56:59]
	v_mfma_f32_16x16x32_bf16 v[44:47], v[154:157], v[196:199], v[44:47]
	v_mfma_f32_16x16x32_bf16 v[40:43], v[180:183], v[196:199], v[40:43]
	v_mfma_f32_16x16x32_bf16 v[28:31], v[154:157], v[204:207], v[28:31]
	v_mfma_f32_16x16x32_bf16 v[24:27], v[180:183], v[204:207], v[24:27]
	v_mfma_f32_16x16x32_bf16 v[12:15], v[154:157], v[212:215], v[12:15]
	v_mfma_f32_16x16x32_bf16 v[8:11], v[180:183], v[212:215], v[8:11]
	s_setprio 0
	s_barrier
	s_add_u32 s8, s8, 0x80080
	s_addc_u32 s9, s9, 0
	s_add_i32 s10, s10, s69
	v_lshl_add_u64 v[150:151], s[8:9], 0, v[130:131]
	s_mov_b32 m0, s10
	s_nop 0
	global_load_lds_dwordx4 v[150:151], off
	v_lshl_add_u64 v[150:151], s[8:9], 0, v[134:135]
	s_add_i32 m0, s10, 0x2000
	s_nop 0
	global_load_lds_dwordx4 v[150:151], off
	s_waitcnt vmcnt(6)
	s_barrier
	s_setprio 1
	v_mfma_f32_16x16x32_bf16 v[52:55], v[216:219], v[184:187], v[52:55]
	v_mfma_f32_16x16x32_bf16 v[48:51], v[224:227], v[184:187], v[48:51]
	v_mfma_f32_16x16x32_bf16 v[36:39], v[216:219], v[192:195], v[36:39]
	v_mfma_f32_16x16x32_bf16 v[32:35], v[224:227], v[192:195], v[32:35]
	v_mfma_f32_16x16x32_bf16 v[20:23], v[216:219], v[200:203], v[20:23]
	v_mfma_f32_16x16x32_bf16 v[16:19], v[224:227], v[200:203], v[16:19]
	v_mfma_f32_16x16x32_bf16 v[4:7], v[216:219], v[208:211], v[4:7]
	v_mfma_f32_16x16x32_bf16 v[0:3], v[224:227], v[208:211], v[0:3]
	v_mfma_f32_16x16x32_bf16 v[52:55], v[220:223], v[188:191], v[52:55]
	v_mfma_f32_16x16x32_bf16 v[48:51], v[228:231], v[188:191], v[48:51]
	v_mfma_f32_16x16x32_bf16 v[36:39], v[220:223], v[196:199], v[36:39]
	v_mfma_f32_16x16x32_bf16 v[32:35], v[228:231], v[196:199], v[32:35]
	v_mfma_f32_16x16x32_bf16 v[20:23], v[220:223], v[204:207], v[20:23]
	v_mfma_f32_16x16x32_bf16 v[16:19], v[228:231], v[204:207], v[16:19]
	v_mfma_f32_16x16x32_bf16 v[4:7], v[220:223], v[212:215], v[4:7]
	v_mfma_f32_16x16x32_bf16 v[0:3], v[228:231], v[212:215], v[0:3]
	s_setprio 0
	s_add_i32 s63, s63, 2
	s_add_u32 s6, s6, 0x100
	s_addc_u32 s7, s7, 0
	s_add_u32 s33, s33, 0x100
	s_addc_u32 s61, s61, 0
	s_cmp_gt_u32 s63, 29
	s_barrier
	s_cbranch_scc0 .LBB0_691
	v_fmamk_f32 v149, v149, 0x3a000000, v170
	s_lshl_b32 s1, s0, 8
	v_rsq_f32_e32 v152, v149
	s_ashr_i32 s61, s0, 3
	v_lshl_add_u32 v148, s4, 8, v137
	s_and_b32 s1, s1, 0x700
	s_cmp_gt_u32 s0, 7
	v_ashrrev_i32_e32 v149, 31, v148
	v_or_b32_e32 v138, s1, v166
	v_lshlrev_b32_e32 v254, 2, v138
	global_load_dwordx4 v[238:241], v254, s[24:25]
	global_load_dwordx4 v[242:245], v254, s[24:25] offset:16
	global_load_dwordx4 v[246:249], v254, s[24:25] offset:512
	global_load_dwordx4 v[250:253], v254, s[24:25] offset:528
	s_cselect_b64 s[12:13], -1, 0
	v_lshlrev_b64 v[150:151], 11, v[148:149]
	v_pk_mul_f32 v[124:125], v[152:153], v[124:125] op_sel_hi:[0,1]
	v_pk_mul_f32 v[126:127], v[152:153], v[126:127] op_sel_hi:[0,1]
	v_pk_mul_f32 v[154:155], v[152:153], v[120:121] op_sel_hi:[0,1]
	v_pk_mul_f32 v[122:123], v[152:153], v[122:123] op_sel_hi:[0,1]
	v_or_b32_e32 v120, v150, v138
	v_mov_b32_e32 v121, v151
	s_mov_b64 s[0:1], -1
	s_and_b64 vcc, exec, s[12:13]
	s_cbranch_vccz .LBB0_704
	s_mov_b64 s[6:7], -1
	s_mov_b64 s[0:1], 0
	s_cmp_lt_i32 s61, 2
	s_mov_b64 s[4:5], 0
	s_cbranch_scc1 .LBB0_699
	s_cmp_eq_u32 s61, 2
	s_mov_b64 s[4:5], -1
	s_cbranch_scc0 .LBB0_696
	s_mov_b64 s[4:5], 0
	v_mov_b32_e32 v161, v123
	v_mov_b32_e32 v160, v122
	v_mov_b32_e32 v163, v155
	v_mov_b32_e32 v162, v154
	v_mov_b32_e32 v157, v127
	v_mov_b32_e32 v156, v126
	v_mov_b32_e32 v159, v125
	v_mov_b32_e32 v158, v124

;     __device__ __forceinline__ void operator()(const f32x4 (&acc)[2][2][4][2], const Unit& u, int wr, int wc, int fr, int fq, const Pre& P) const {
;     ...
;                     else if (sec == 1) { dst = KB; const f32x4 l0 = *(const f32x4*)(LBv + c), l1 = *(const f32x4*)(LBv + c + 4); float lf[8];
.LBB0_702:
	v_lshlrev_b32_e32 v153, 2, v138
	s_waitcnt vmcnt(0)
	v_mov_b32_e32 v156, v238
	v_mov_b32_e32 v157, v239
	v_mov_b32_e32 v158, v240
	v_mov_b32_e32 v159, v241
	v_mov_b32_e32 v160, v242
	v_mov_b32_e32 v161, v243
	v_mov_b32_e32 v162, v244
	v_mov_b32_e32 v163, v245

; __device__ __forceinline__ float sigmoidf_(float x) { return __builtin_amdgcn_rcpf(1.0f + fexp(-x)); }
;     __device__ __forceinline__ void operator()(const f32x4 (&acc)[2][2][4][2], const Unit& u, int wr, int wc, int fr, int fq, const Pre& P) const {
;     ...
;                         for (int j = 0; j < 8; ++j) { const float lb = j < 4 ? l0[j] : l1[j - 4]; const float fg = lb + (1.0f - lb) * sigmoidf_(x[j]); y[j] = 1.0f - fg; lf[j] = __logf(fg); }
	v_mul_f32_e32 v153, 0xbfb8aa3b, v124
	v_mul_f32_e32 v180, 0xbfb8aa3b, v125
	v_mul_f32_e32 v181, 0xbfb8aa3b, v126
	v_exp_f32_e32 v153, v153
	v_exp_f32_e32 v180, v180
	v_mul_f32_e32 v182, 0xbfb8aa3b, v127
	v_exp_f32_e32 v181, v181
	v_mul_f32_e32 v183, 0xbfb8aa3b, v154
	v_exp_f32_e32 v182, v182
	v_mul_f32_e32 v184, 0xbfb8aa3b, v155
	v_exp_f32_e32 v183, v183
	v_exp_f32_e32 v184, v184
	v_add_f32_e32 v153, 1.0, v153
	v_add_f32_e32 v185, 1.0, v180
	v_add_f32_e32 v186, 1.0, v181
	v_rcp_f32_e32 v180, v153
	v_rcp_f32_e32 v181, v185
	v_add_f32_e32 v187, 1.0, v182
	v_add_f32_e32 v188, 1.0, v183
	v_rcp_f32_e32 v182, v186
	v_rcp_f32_e32 v183, v187
	v_add_f32_e32 v189, 1.0, v184
	v_rcp_f32_e32 v184, v188
	v_rcp_f32_e32 v185, v189

; __device__ __forceinline__ float sigmoidf_(float x) { return __builtin_amdgcn_rcpf(1.0f + fexp(-x)); }
;     __device__ __forceinline__ void operator()(const f32x4 (&acc)[2][2][4][2], const Unit& u, int wr, int wc, int fr, int fq, const Pre& P) const {
;     ...
;                         for (int j = 0; j < 8; ++j) { const float lb = j < 4 ? l0[j] : l1[j - 4]; const float fg = lb + (1.0f - lb) * sigmoidf_(x[j]); y[j] = 1.0f - fg; lf[j] = __logf(fg); }
;                         *(f32x4*)(LF + off) = (f32x4){lf[0], lf[1], lf[2], lf[3]}; *(f32x4*)(LF + off + 4) = (f32x4){lf[4], lf[5], lf[6], lf[7]}; }
	v_pk_add_f32 v[186:187], v[156:157], 1.0 op_sel_hi:[1,0] neg_lo:[1,0] neg_hi:[1,0]
	s_nop 0
	v_pk_fma_f32 v[192:193], v[180:181], v[186:187], v[156:157]
	v_pk_add_f32 v[188:189], v[158:159], 1.0 op_sel_hi:[1,0] neg_lo:[1,0] neg_hi:[1,0]
	v_cmp_gt_f32_e32 vcc, s86, v192
	v_pk_fma_f32 v[156:157], v[182:183], v[188:189], v[158:159]
	v_cmp_gt_f32_e64 s[0:1], s86, v193
	v_cndmask_b32_e64 v153, 0, 32, vcc
	v_pk_add_f32 v[190:191], v[160:161], 1.0 op_sel_hi:[1,0] neg_lo:[1,0] neg_hi:[1,0]
	v_cndmask_b32_e64 v158, 0, 32, s[0:1]
	v_cmp_gt_f32_e64 s[4:5], s86, v156
	v_ldexp_f32 v153, v192, v153
	v_pk_fma_f32 v[188:189], v[184:185], v[190:191], v[160:161]
	v_cndmask_b32_e64 v159, 0, 32, s[4:5]
	v_ldexp_f32 v158, v193, v158
	v_log_f32_e32 v153, v153
	v_cmp_gt_f32_e64 s[10:11], s86, v189
	v_ldexp_f32 v159, v156, v159
	v_log_f32_e32 v158, v158
	v_cndmask_b32_e64 v180, 0, 32, s[10:11]
	v_log_f32_e32 v159, v159
	v_ldexp_f32 v180, v189, v180
	v_log_f32_e32 v185, v180
	v_mul_f32_e32 v180, 0x3f317217, v153
	v_mul_f32_e32 v186, 0x3f317217, v158
	v_fma_f32 v180, v153, s87, -v180
	v_mul_f32_e32 v187, 0x3f317217, v159
	v_fma_f32 v186, v158, s87, -v186
	v_fmac_f32_e32 v180, 0x3377d1cf, v153
	v_cmp_gt_f32_e64 s[6:7], s86, v157
	v_cndmask_b32_e32 v181, 0, v171, vcc
	v_fma_f32 v187, v159, s87, -v187
	v_fmac_f32_e32 v186, 0x3377d1cf, v158
	v_fmac_f32_e32 v180, 0x3f317217, v153
	v_cmp_lt_f32_e64 vcc, |v153|, s88
	v_cndmask_b32_e64 v160, 0, 32, s[6:7]
	v_cmp_gt_f32_e64 s[8:9], s86, v188
	v_fmac_f32_e32 v187, 0x3377d1cf, v159
	v_fmac_f32_e32 v186, 0x3f317217, v158
	v_cndmask_b32_e32 v153, v153, v180, vcc
	v_cmp_lt_f32_e64 vcc, |v158|, s88
	v_cndmask_b32_e64 v161, 0, 32, s[8:9]
	v_ldexp_f32 v160, v157, v160
	v_fmac_f32_e32 v187, 0x3f317217, v159
	v_cndmask_b32_e32 v158, v158, v186, vcc
	v_cmp_lt_f32_e64 vcc, |v159|, s88
	v_cndmask_b32_e64 v182, 0, v171, s[0:1]
	v_cndmask_b32_e64 v183, 0, v171, s[4:5]
	v_ldexp_f32 v161, v188, v161
	v_log_f32_e32 v160, v160
	v_cndmask_b32_e32 v159, v159, v187, vcc
	v_log_f32_e32 v161, v161
	v_sub_f32_e32 v180, v153, v181
	v_sub_f32_e32 v181, v158, v182
	v_sub_f32_e32 v182, v159, v183
	v_mul_f32_e32 v158, 0xbfb8aa3b, v122
	v_mul_f32_e32 v159, 0xbfb8aa3b, v123
	v_exp_f32_e32 v158, v158
	v_exp_f32_e32 v159, v159
	v_mul_f32_e32 v190, 0x3f317217, v160
	v_mul_f32_e32 v191, 0x3f317217, v161
	v_fma_f32 v190, v160, s87, -v190
	v_fma_f32 v191, v161, s87, -v191
	v_fmac_f32_e32 v190, 0x3377d1cf, v160
	v_add_f32_e32 v158, 1.0, v158
	v_add_f32_e32 v159, 1.0, v159
	v_fmac_f32_e32 v191, 0x3377d1cf, v161
	v_fmac_f32_e32 v190, 0x3f317217, v160
	v_cmp_lt_f32_e64 vcc, |v160|, s88
	v_rcp_f32_e32 v158, v158
	v_rcp_f32_e32 v159, v159
	v_fmac_f32_e32 v191, 0x3f317217, v161
	v_cndmask_b32_e32 v160, v160, v190, vcc
	v_cmp_lt_f32_e64 vcc, |v161|, s88
	v_cndmask_b32_e64 v184, 0, v171, s[6:7]
	v_cndmask_b32_e64 v153, 0, v171, s[8:9]
	v_cndmask_b32_e32 v161, v161, v191, vcc
	v_sub_f32_e32 v183, v160, v184
	v_sub_f32_e32 v184, v161, v153
	v_pk_add_f32 v[160:161], v[162:163], 1.0 op_sel_hi:[1,0] neg_lo:[1,0] neg_hi:[1,0]
	v_mul_f32_e32 v153, 0x3f317217, v185
	v_pk_fma_f32 v[158:159], v[158:159], v[160:161], v[162:163]
	v_fma_f32 v153, v185, s87, -v153
	v_cmp_gt_f32_e32 vcc, s86, v158
	v_fmac_f32_e32 v153, 0x3377d1cf, v185
	v_fmac_f32_e32 v153, 0x3f317217, v185
	v_cndmask_b32_e64 v160, 0, 32, vcc
	v_ldexp_f32 v160, v158, v160
	v_log_f32_e32 v160, v160
	v_cmp_lt_f32_e64 s[0:1], |v185|, s88
	v_cndmask_b32_e64 v161, 0, v171, s[10:11]
	v_sub_f32_e32 v156, 1.0, v156
	v_cndmask_b32_e64 v153, v185, v153, s[0:1]
	v_sub_f32_e32 v185, v153, v161
	v_mul_f32_e32 v153, 0x3f317217, v160
	v_fma_f32 v153, v160, s87, -v153
	v_fmac_f32_e32 v153, 0x3377d1cf, v160
	v_fmac_f32_e32 v153, 0x3f317217, v160
	v_cmp_lt_f32_e64 s[0:1], |v160|, s88
	v_sub_f32_e32 v157, 1.0, v157
	v_sub_f32_e32 v161, 1.0, v159
	v_cndmask_b32_e64 v153, v160, v153, s[0:1]
	v_cndmask_b32_e32 v160, 0, v171, vcc
	v_cmp_gt_f32_e32 vcc, s86, v159
	v_sub_f32_e32 v186, v153, v160
	v_sub_f32_e32 v160, 1.0, v158
	v_cndmask_b32_e64 v153, 0, 32, vcc
	v_ldexp_f32 v153, v159, v153
	v_log_f32_e32 v153, v153
	v_sub_f32_e32 v158, 1.0, v192
	v_sub_f32_e32 v159, 1.0, v193
	v_sub_f32_e32 v162, 1.0, v188
	v_mul_f32_e32 v187, 0x3f317217, v153
	v_fma_f32 v187, v153, s87, -v187
	v_fmac_f32_e32 v187, 0x3377d1cf, v153
	v_fmac_f32_e32 v187, 0x3f317217, v153
	v_cmp_lt_f32_e64 s[0:1], |v153|, s88
	v_sub_f32_e32 v163, 1.0, v189
	v_lshl_add_u64 v[188:189], v[120:121], 2, s[22:23]
	v_cndmask_b32_e64 v153, v153, v187, s[0:1]
	v_cndmask_b32_e32 v187, 0, v171, vcc
	s_mov_b64 s[4:5], s[16:17]
	v_sub_f32_e32 v187, v153, v187
	global_store_dwordx4 v[188:189], v[180:183], off
	global_store_dwordx4 v[188:189], v[184:187], off offset:16

;     __device__ __forceinline__ void operator()(const f32x4 (&acc)[2][2][4][2], const Unit& u, int wr, int wc, int fr, int fq, const Pre& P) const {
;     ...
;                     else if (sec == 1) { dst = KB; const f32x4 l0 = *(const f32x4*)(LBv + c), l1 = *(const f32x4*)(LBv + c + 4); float lf[8];
.LBB0_716:
	v_lshlrev_b32_e32 v124, 2, v154
	v_mov_b32_e32 v120, v246
	v_mov_b32_e32 v121, v247
	v_mov_b32_e32 v122, v248
	v_mov_b32_e32 v123, v249
	v_mov_b32_e32 v156, v250
	v_mov_b32_e32 v157, v251
	v_mov_b32_e32 v158, v252
	v_mov_b32_e32 v159, v253

; __device__ __forceinline__ float sigmoidf_(float x) { return __builtin_amdgcn_rcpf(1.0f + fexp(-x)); }
;     __device__ __forceinline__ void operator()(const f32x4 (&acc)[2][2][4][2], const Unit& u, int wr, int wc, int fr, int fq, const Pre& P) const {
;     ...
;                         for (int j = 0; j < 8; ++j) { const float lb = j < 4 ? l0[j] : l1[j - 4]; const float fg = lb + (1.0f - lb) * sigmoidf_(x[j]); y[j] = 1.0f - fg; lf[j] = __logf(fg); }
;                         *(f32x4*)(LF + off) = (f32x4){lf[0], lf[1], lf[2], lf[3]}; *(f32x4*)(LF + off + 4) = (f32x4){lf[4], lf[5], lf[6], lf[7]}; }
	v_mul_f32_e32 v124, 0xbfb8aa3b, v116
	v_mul_f32_e32 v125, 0xbfb8aa3b, v117
	v_exp_f32_e32 v124, v124
	v_exp_f32_e32 v125, v125
	v_mul_f32_e32 v152, 0xbfb8aa3b, v118
	v_mul_f32_e32 v153, 0xbfb8aa3b, v119
	v_exp_f32_e32 v152, v152
	v_exp_f32_e32 v153, v153
	v_mul_f32_e32 v155, 0xbfb8aa3b, v112
	v_mul_f32_e32 v160, 0xbfb8aa3b, v113
	v_exp_f32_e32 v155, v155
	v_exp_f32_e32 v160, v160
	v_add_f32_e32 v124, 1.0, v124
	v_add_f32_e32 v125, 1.0, v125
	v_rcp_f32_e32 v124, v124
	v_rcp_f32_e32 v125, v125
	v_add_f32_e32 v152, 1.0, v152
	v_add_f32_e32 v153, 1.0, v153
	v_rcp_f32_e32 v152, v152
	v_rcp_f32_e32 v153, v153
	v_add_f32_e32 v155, 1.0, v155
	v_add_f32_e32 v161, 1.0, v160
	v_rcp_f32_e32 v160, v155
	v_rcp_f32_e32 v161, v161
	v_or_b32_e32 v126, v150, v154
	v_mov_b32_e32 v127, v151
	v_lshl_add_u64 v[126:127], v[126:127], 2, s[22:23]

; __device__ __forceinline__ float sigmoidf_(float x) { return __builtin_amdgcn_rcpf(1.0f + fexp(-x)); }
;     __device__ __forceinline__ void operator()(const f32x4 (&acc)[2][2][4][2], const Unit& u, int wr, int wc, int fr, int fq, const Pre& P) const {
;     ...
;                         for (int j = 0; j < 8; ++j) { const float lb = j < 4 ? l0[j] : l1[j - 4]; const float fg = lb + (1.0f - lb) * sigmoidf_(x[j]); y[j] = 1.0f - fg; lf[j] = __logf(fg); }
;                         *(f32x4*)(LF + off) = (f32x4){lf[0], lf[1], lf[2], lf[3]}; *(f32x4*)(LF + off + 4) = (f32x4){lf[4], lf[5], lf[6], lf[7]}; }
	v_pk_add_f32 v[162:163], v[120:121], 1.0 op_sel_hi:[1,0] neg_lo:[1,0] neg_hi:[1,0]
	s_nop 0
	v_pk_fma_f32 v[184:185], v[124:125], v[162:163], v[120:121]
	v_pk_add_f32 v[180:181], v[122:123], 1.0 op_sel_hi:[1,0] neg_lo:[1,0] neg_hi:[1,0]
	v_cmp_gt_f32_e32 vcc, s86, v184
	v_pk_fma_f32 v[120:121], v[152:153], v[180:181], v[122:123]
	v_cmp_gt_f32_e64 s[0:1], s86, v185
	v_cndmask_b32_e64 v122, 0, 32, vcc
	v_pk_add_f32 v[182:183], v[156:157], 1.0 op_sel_hi:[1,0] neg_lo:[1,0] neg_hi:[1,0]
	v_cndmask_b32_e64 v123, 0, 32, s[0:1]
	v_cmp_gt_f32_e64 s[6:7], s86, v120
	v_ldexp_f32 v122, v184, v122
	v_pk_fma_f32 v[152:153], v[160:161], v[182:183], v[156:157]
	v_cndmask_b32_e64 v124, 0, 32, s[6:7]
	v_cmp_gt_f32_e64 s[8:9], s86, v121
	v_ldexp_f32 v123, v185, v123
	v_log_f32_e32 v122, v122
	v_cndmask_b32_e64 v125, 0, 32, s[8:9]
	v_cmp_gt_f32_e64 s[10:11], s86, v152
	v_cmp_gt_f32_e64 s[12:13], s86, v153
	v_ldexp_f32 v124, v120, v124
	v_log_f32_e32 v123, v123
	v_cndmask_b32_e64 v155, 0, 32, s[10:11]
	v_cndmask_b32_e64 v156, 0, 32, s[12:13]
	v_ldexp_f32 v125, v121, v125
	v_log_f32_e32 v124, v124
	v_ldexp_f32 v155, v152, v155
	v_ldexp_f32 v156, v153, v156
	v_log_f32_e32 v125, v125
	v_log_f32_e32 v155, v155
	v_log_f32_e32 v180, v156
	v_mul_f32_e32 v156, 0x3f317217, v122
	v_mul_f32_e32 v160, 0x3f317217, v123
	v_fma_f32 v156, v122, s87, -v156
	v_mul_f32_e32 v181, 0x3f317217, v124
	v_fma_f32 v160, v123, s87, -v160
	v_fmac_f32_e32 v156, 0x3377d1cf, v122
	v_cndmask_b32_e32 v157, 0, v171, vcc
	v_mul_f32_e32 v182, 0x3f317217, v125
	v_fma_f32 v181, v124, s87, -v181
	v_fmac_f32_e32 v160, 0x3377d1cf, v123
	v_fmac_f32_e32 v156, 0x3f317217, v122
	v_cmp_lt_f32_e64 vcc, |v122|, s88
	v_mul_f32_e32 v183, 0x3f317217, v155
	v_fma_f32 v182, v125, s87, -v182
	v_fmac_f32_e32 v181, 0x3377d1cf, v124
	v_fmac_f32_e32 v160, 0x3f317217, v123
	v_cndmask_b32_e32 v122, v122, v156, vcc
	v_cmp_lt_f32_e64 vcc, |v123|, s88
	v_fma_f32 v183, v155, s87, -v183
	v_fmac_f32_e32 v182, 0x3377d1cf, v125
	v_fmac_f32_e32 v181, 0x3f317217, v124
	v_cndmask_b32_e32 v123, v123, v160, vcc
	v_cmp_lt_f32_e64 vcc, |v124|, s88
	v_fmac_f32_e32 v183, 0x3377d1cf, v155
	v_fmac_f32_e32 v182, 0x3f317217, v125
	v_cndmask_b32_e32 v124, v124, v181, vcc
	v_cmp_lt_f32_e64 vcc, |v125|, s88
	v_cndmask_b32_e64 v161, 0, v171, s[0:1]
	v_fmac_f32_e32 v183, 0x3f317217, v155
	v_cndmask_b32_e32 v125, v125, v182, vcc
	v_cmp_lt_f32_e64 vcc, |v155|, s88
	v_cndmask_b32_e64 v162, 0, v171, s[6:7]
	v_sub_f32_e32 v160, v122, v157
	v_sub_f32_e32 v161, v123, v161
	v_cndmask_b32_e32 v122, v155, v183, vcc
	v_cndmask_b32_e64 v123, 0, v171, s[10:11]
	v_sub_f32_e32 v162, v124, v162
	v_sub_f32_e32 v156, v122, v123
	v_mul_f32_e32 v123, 0xbfb8aa3b, v114
	v_mul_f32_e32 v124, 0xbfb8aa3b, v115
	v_exp_f32_e32 v123, v123
	v_exp_f32_e32 v124, v124
	v_mul_f32_e32 v122, 0x3f317217, v180
	v_fma_f32 v155, v180, s87, -v122
	v_add_f32_e32 v122, 1.0, v123
	v_add_f32_e32 v123, 1.0, v124
	v_rcp_f32_e32 v122, v122
	v_rcp_f32_e32 v123, v123
	v_cndmask_b32_e64 v163, 0, v171, s[8:9]
	v_sub_f32_e32 v163, v125, v163
	v_pk_add_f32 v[124:125], v[158:159], 1.0 op_sel_hi:[1,0] neg_lo:[1,0] neg_hi:[1,0]
	v_fmac_f32_e32 v155, 0x3377d1cf, v180
	v_pk_fma_f32 v[122:123], v[122:123], v[124:125], v[158:159]
	v_fmac_f32_e32 v155, 0x3f317217, v180
	v_cmp_gt_f32_e32 vcc, s86, v122
	v_cmp_lt_f32_e64 s[0:1], |v180|, s88
	v_sub_f32_e32 v120, 1.0, v120
	v_cndmask_b32_e64 v124, 0, 32, vcc
	v_ldexp_f32 v124, v122, v124
	v_log_f32_e32 v124, v124
	v_cndmask_b32_e64 v125, v180, v155, s[0:1]
	v_cndmask_b32_e64 v155, 0, v171, s[12:13]
	v_sub_f32_e32 v157, v125, v155
	v_mul_f32_e32 v125, 0x3f317217, v124
	v_fma_f32 v125, v124, s87, -v125
	v_fmac_f32_e32 v125, 0x3377d1cf, v124
	v_fmac_f32_e32 v125, 0x3f317217, v124
	v_cmp_lt_f32_e64 s[0:1], |v124|, s88
	v_sub_f32_e32 v121, 1.0, v121
	v_sub_f32_e32 v152, 1.0, v152
	v_cndmask_b32_e64 v124, v124, v125, s[0:1]
	v_cndmask_b32_e32 v125, 0, v171, vcc
	v_cmp_gt_f32_e32 vcc, s86, v123
	v_sub_f32_e32 v158, v124, v125
	v_sub_f32_e32 v125, 1.0, v123
	v_cndmask_b32_e64 v155, 0, 32, vcc
	v_ldexp_f32 v123, v123, v155
	v_log_f32_e32 v155, v123
	v_sub_f32_e32 v124, 1.0, v122
	v_sub_f32_e32 v122, 1.0, v184
	v_sub_f32_e32 v123, 1.0, v185
	v_mul_f32_e32 v159, 0x3f317217, v155
	v_fma_f32 v159, v155, s87, -v159
	v_fmac_f32_e32 v159, 0x3377d1cf, v155
	v_fmac_f32_e32 v159, 0x3f317217, v155
	v_cmp_lt_f32_e64 s[0:1], |v155|, s88
	v_sub_f32_e32 v153, 1.0, v153
	s_mov_b64 s[6:7], s[16:17]
	v_cndmask_b32_e64 v155, v155, v159, s[0:1]
	v_cndmask_b32_e32 v159, 0, v171, vcc
	v_sub_f32_e32 v159, v155, v159
	global_store_dwordx4 v[126:127], v[160:163], off
	global_store_dwordx4 v[126:127], v[156:159], off offset:16

;     __device__ __forceinline__ void operator()(const f32x4 (&acc)[2][2][4][2], const Unit& u, int wr, int wc, int fr, int fq, const Pre& P) const {
;     ...
;                     else if (sec == 1) { dst = KB; const f32x4 l0 = *(const f32x4*)(LBv + c), l1 = *(const f32x4*)(LBv + c + 4); float lf[8];
.LBB0_730:
	v_lshlrev_b32_e32 v115, 2, v138
	v_mov_b32_e32 v118, v238
	v_mov_b32_e32 v119, v239
	v_mov_b32_e32 v120, v240
	v_mov_b32_e32 v121, v241
	v_mov_b32_e32 v122, v242
	v_mov_b32_e32 v123, v243
	v_mov_b32_e32 v124, v244
	v_mov_b32_e32 v125, v245

; __device__ __forceinline__ float sigmoidf_(float x) { return __builtin_amdgcn_rcpf(1.0f + fexp(-x)); }
;     __device__ __forceinline__ void operator()(const f32x4 (&acc)[2][2][4][2], const Unit& u, int wr, int wc, int fr, int fq, const Pre& P) const {
;     ...
;                         for (int j = 0; j < 8; ++j) { const float lb = j < 4 ? l0[j] : l1[j - 4]; const float fg = lb + (1.0f - lb) * sigmoidf_(x[j]); y[j] = 1.0f - fg; lf[j] = __logf(fg); }
	v_mul_f32_e32 v115, 0xbfb8aa3b, v108
	v_mul_f32_e32 v126, 0xbfb8aa3b, v109
	v_mul_f32_e32 v127, 0xbfb8aa3b, v110
	v_exp_f32_e32 v115, v115
	v_exp_f32_e32 v126, v126
	v_mul_f32_e32 v150, 0xbfb8aa3b, v111
	v_exp_f32_e32 v127, v127
	v_mul_f32_e32 v151, 0xbfb8aa3b, v116
	v_exp_f32_e32 v150, v150
	v_mul_f32_e32 v152, 0xbfb8aa3b, v117
	v_exp_f32_e32 v151, v151
	v_exp_f32_e32 v152, v152
	v_add_f32_e32 v115, 1.0, v115
	v_add_f32_e32 v153, 1.0, v126
	v_add_f32_e32 v155, 1.0, v127
	v_rcp_f32_e32 v126, v115
	v_rcp_f32_e32 v127, v153
	v_add_f32_e32 v156, 1.0, v150
	v_add_f32_e32 v157, 1.0, v151
	v_rcp_f32_e32 v150, v155
	v_rcp_f32_e32 v151, v156
	v_add_f32_e32 v158, 1.0, v152
	v_rcp_f32_e32 v152, v157
	v_rcp_f32_e32 v153, v158

; __device__ __forceinline__ float sigmoidf_(float x) { return __builtin_amdgcn_rcpf(1.0f + fexp(-x)); }
;     __device__ __forceinline__ void operator()(const f32x4 (&acc)[2][2][4][2], const Unit& u, int wr, int wc, int fr, int fq, const Pre& P) const {
;     ...
;                         for (int j = 0; j < 8; ++j) { const float lb = j < 4 ? l0[j] : l1[j - 4]; const float fg = lb + (1.0f - lb) * sigmoidf_(x[j]); y[j] = 1.0f - fg; lf[j] = __logf(fg); }
;                         *(f32x4*)(LF + off) = (f32x4){lf[0], lf[1], lf[2], lf[3]}; *(f32x4*)(LF + off + 4) = (f32x4){lf[4], lf[5], lf[6], lf[7]}; }
	v_pk_add_f32 v[156:157], v[118:119], 1.0 op_sel_hi:[1,0] neg_lo:[1,0] neg_hi:[1,0]
	s_nop 0
	v_pk_fma_f32 v[126:127], v[126:127], v[156:157], v[118:119]
	v_pk_add_f32 v[158:159], v[120:121], 1.0 op_sel_hi:[1,0] neg_lo:[1,0] neg_hi:[1,0]
	v_cmp_gt_f32_e32 vcc, s86, v126
	v_pk_fma_f32 v[118:119], v[150:151], v[158:159], v[120:121]
	v_cmp_gt_f32_e64 s[0:1], s86, v127
	v_cndmask_b32_e64 v115, 0, 32, vcc
	v_pk_add_f32 v[160:161], v[122:123], 1.0 op_sel_hi:[1,0] neg_lo:[1,0] neg_hi:[1,0]
	v_cndmask_b32_e64 v120, 0, 32, s[0:1]
	v_cmp_gt_f32_e64 s[6:7], s86, v118
	v_ldexp_f32 v115, v126, v115
	v_pk_fma_f32 v[160:161], v[152:153], v[160:161], v[122:123]
	v_cndmask_b32_e64 v121, 0, 32, s[6:7]
	v_ldexp_f32 v120, v127, v120
	v_log_f32_e32 v115, v115
	v_cmp_gt_f32_e64 s[12:13], s86, v161
	v_ldexp_f32 v121, v118, v121
	v_log_f32_e32 v120, v120
	v_cndmask_b32_e64 v150, 0, 32, s[12:13]
	v_log_f32_e32 v121, v121
	v_ldexp_f32 v150, v161, v150
	v_log_f32_e32 v157, v150
	v_mul_f32_e32 v150, 0x3f317217, v115
	v_mul_f32_e32 v156, 0x3f317217, v120
	v_fma_f32 v150, v115, s87, -v150
	v_mul_f32_e32 v158, 0x3f317217, v121
	v_fma_f32 v156, v120, s87, -v156
	v_fmac_f32_e32 v150, 0x3377d1cf, v115
	v_cmp_gt_f32_e64 s[8:9], s86, v119
	v_cndmask_b32_e32 v151, 0, v171, vcc
	v_fma_f32 v158, v121, s87, -v158
	v_fmac_f32_e32 v156, 0x3377d1cf, v120
	v_fmac_f32_e32 v150, 0x3f317217, v115
	v_cmp_lt_f32_e64 vcc, |v115|, s88
	v_cndmask_b32_e64 v122, 0, 32, s[8:9]
	v_cmp_gt_f32_e64 s[10:11], s86, v160
	v_fmac_f32_e32 v158, 0x3377d1cf, v121
	v_fmac_f32_e32 v156, 0x3f317217, v120
	v_cndmask_b32_e32 v115, v115, v150, vcc
	v_cmp_lt_f32_e64 vcc, |v120|, s88
	v_cndmask_b32_e64 v123, 0, 32, s[10:11]
	v_ldexp_f32 v122, v119, v122
	v_fmac_f32_e32 v158, 0x3f317217, v121
	v_cndmask_b32_e32 v120, v120, v156, vcc
	v_cmp_lt_f32_e64 vcc, |v121|, s88
	v_cndmask_b32_e64 v152, 0, v171, s[0:1]
	v_cndmask_b32_e64 v153, 0, v171, s[6:7]
	v_ldexp_f32 v123, v160, v123
	v_log_f32_e32 v122, v122
	v_cndmask_b32_e32 v121, v121, v158, vcc
	v_log_f32_e32 v123, v123
	v_sub_f32_e32 v150, v115, v151
	v_sub_f32_e32 v151, v120, v152
	v_sub_f32_e32 v152, v121, v153
	v_mul_f32_e32 v120, 0xbfb8aa3b, v106
	v_mul_f32_e32 v121, 0xbfb8aa3b, v107
	v_exp_f32_e32 v120, v120
	v_exp_f32_e32 v121, v121
	v_mul_f32_e32 v159, 0x3f317217, v122
	v_mul_f32_e32 v162, 0x3f317217, v123
	v_fma_f32 v159, v122, s87, -v159
	v_fma_f32 v162, v123, s87, -v162
	v_fmac_f32_e32 v159, 0x3377d1cf, v122
	v_add_f32_e32 v120, 1.0, v120
	v_add_f32_e32 v121, 1.0, v121
	v_fmac_f32_e32 v162, 0x3377d1cf, v123
	v_fmac_f32_e32 v159, 0x3f317217, v122
	v_cmp_lt_f32_e64 vcc, |v122|, s88
	v_rcp_f32_e32 v120, v120
	v_rcp_f32_e32 v121, v121
	v_fmac_f32_e32 v162, 0x3f317217, v123
	v_cndmask_b32_e32 v122, v122, v159, vcc
	v_cmp_lt_f32_e64 vcc, |v123|, s88
	v_cndmask_b32_e64 v155, 0, v171, s[8:9]
	v_cndmask_b32_e64 v115, 0, v171, s[10:11]
	v_cndmask_b32_e32 v123, v123, v162, vcc
	v_sub_f32_e32 v153, v122, v155
	v_sub_f32_e32 v156, v123, v115
	v_pk_add_f32 v[122:123], v[124:125], 1.0 op_sel_hi:[1,0] neg_lo:[1,0] neg_hi:[1,0]
	v_mul_f32_e32 v115, 0x3f317217, v157
	v_pk_fma_f32 v[120:121], v[120:121], v[122:123], v[124:125]
	v_fma_f32 v115, v157, s87, -v115
	v_cmp_gt_f32_e32 vcc, s86, v120
	v_fmac_f32_e32 v115, 0x3377d1cf, v157
	v_fmac_f32_e32 v115, 0x3f317217, v157
	v_cndmask_b32_e64 v122, 0, 32, vcc
	v_ldexp_f32 v122, v120, v122
	v_log_f32_e32 v122, v122
	v_cmp_lt_f32_e64 s[0:1], |v157|, s88
	v_cndmask_b32_e64 v123, 0, v171, s[12:13]
	v_sub_f32_e32 v118, 1.0, v118
	v_cndmask_b32_e64 v115, v157, v115, s[0:1]
	v_sub_f32_e32 v157, v115, v123
	v_mul_f32_e32 v115, 0x3f317217, v122
	v_fma_f32 v115, v122, s87, -v115
	v_fmac_f32_e32 v115, 0x3377d1cf, v122
	v_fmac_f32_e32 v115, 0x3f317217, v122
	v_cmp_lt_f32_e64 s[0:1], |v122|, s88
	v_sub_f32_e32 v119, 1.0, v119
	v_sub_f32_e32 v123, 1.0, v121
	v_cndmask_b32_e64 v115, v122, v115, s[0:1]
	v_cndmask_b32_e32 v122, 0, v171, vcc
	v_cmp_gt_f32_e32 vcc, s86, v121
	v_sub_f32_e32 v158, v115, v122
	v_sub_f32_e32 v122, 1.0, v120
	v_cndmask_b32_e64 v115, 0, 32, vcc
	v_ldexp_f32 v115, v121, v115
	v_log_f32_e32 v115, v115
	v_sub_f32_e32 v120, 1.0, v126
	v_sub_f32_e32 v121, 1.0, v127
	v_sub_f32_e32 v124, 1.0, v160
	v_mul_f32_e32 v126, 0x3f317217, v115
	v_fma_f32 v126, v115, s87, -v126
	v_fmac_f32_e32 v126, 0x3377d1cf, v115
	v_fmac_f32_e32 v126, 0x3f317217, v115
	v_cmp_lt_f32_e64 s[0:1], |v115|, s88
	v_sub_f32_e32 v125, 1.0, v161
	s_mov_b64 s[6:7], s[16:17]
	v_cndmask_b32_e64 v115, v115, v126, s[0:1]
	v_cndmask_b32_e32 v126, 0, v171, vcc
	v_sub_f32_e32 v159, v115, v126
	v_lshl_add_u64 v[126:127], v[104:105], 2, s[22:23]
	global_store_dwordx4 v[126:127], v[150:153], off
	global_store_dwordx4 v[126:127], v[156:159], off offset:16

;     __device__ __forceinline__ void operator()(const f32x4 (&acc)[2][2][4][2], const Unit& u, int wr, int wc, int fr, int fq, const Pre& P) const {
;     ...
;                     else if (sec == 1) { dst = KB; const f32x4 l0 = *(const f32x4*)(LBv + c), l1 = *(const f32x4*)(LBv + c + 4); float lf[8];
.LBB0_744:
	v_lshlrev_b32_e32 v108, 2, v154
	v_mov_b32_e32 v104, v246
	v_mov_b32_e32 v105, v247
	v_mov_b32_e32 v106, v248
	v_mov_b32_e32 v107, v249
	v_mov_b32_e32 v114, v250
	v_mov_b32_e32 v115, v251
	v_mov_b32_e32 v116, v252
	v_mov_b32_e32 v117, v253

; __device__ __forceinline__ float sigmoidf_(float x) { return __builtin_amdgcn_rcpf(1.0f + fexp(-x)); }
;     __device__ __forceinline__ void operator()(const f32x4 (&acc)[2][2][4][2], const Unit& u, int wr, int wc, int fr, int fq, const Pre& P) const {
;     ...
;                         for (int j = 0; j < 8; ++j) { const float lb = j < 4 ? l0[j] : l1[j - 4]; const float fg = lb + (1.0f - lb) * sigmoidf_(x[j]); y[j] = 1.0f - fg; lf[j] = __logf(fg); }
;                         *(f32x4*)(LF + off) = (f32x4){lf[0], lf[1], lf[2], lf[3]}; *(f32x4*)(LF + off + 4) = (f32x4){lf[4], lf[5], lf[6], lf[7]}; }
	v_mul_f32_e32 v108, 0xbfb8aa3b, v100
	v_mul_f32_e32 v109, 0xbfb8aa3b, v101
	v_exp_f32_e32 v108, v108
	v_exp_f32_e32 v109, v109
	v_mul_f32_e32 v118, 0xbfb8aa3b, v102
	v_mul_f32_e32 v119, 0xbfb8aa3b, v103
	v_exp_f32_e32 v118, v118
	v_exp_f32_e32 v119, v119
	v_mul_f32_e32 v120, 0xbfb8aa3b, v96
	v_mul_f32_e32 v121, 0xbfb8aa3b, v97
	v_exp_f32_e32 v120, v120
	v_exp_f32_e32 v121, v121
	v_add_f32_e32 v108, 1.0, v108
	v_add_f32_e32 v109, 1.0, v109
	v_rcp_f32_e32 v108, v108
	v_rcp_f32_e32 v109, v109
	v_add_f32_e32 v118, 1.0, v118
	v_add_f32_e32 v119, 1.0, v119
	v_rcp_f32_e32 v118, v118
	v_rcp_f32_e32 v119, v119
	v_add_f32_e32 v120, 1.0, v120
	v_add_f32_e32 v121, 1.0, v121
	v_rcp_f32_e32 v120, v120
	v_rcp_f32_e32 v121, v121
	v_or_b32_e32 v110, v112, v154
	v_mov_b32_e32 v111, v113
	v_lshl_add_u64 v[110:111], v[110:111], 2, s[22:23]

; __device__ __forceinline__ float sigmoidf_(float x) { return __builtin_amdgcn_rcpf(1.0f + fexp(-x)); }
;     __device__ __forceinline__ void operator()(const f32x4 (&acc)[2][2][4][2], const Unit& u, int wr, int wc, int fr, int fq, const Pre& P) const {
;     ...
;                         for (int j = 0; j < 8; ++j) { const float lb = j < 4 ? l0[j] : l1[j - 4]; const float fg = lb + (1.0f - lb) * sigmoidf_(x[j]); y[j] = 1.0f - fg; lf[j] = __logf(fg); }
;                         *(f32x4*)(LF + off) = (f32x4){lf[0], lf[1], lf[2], lf[3]}; *(f32x4*)(LF + off + 4) = (f32x4){lf[4], lf[5], lf[6], lf[7]}; }
	v_pk_add_f32 v[122:123], v[104:105], 1.0 op_sel_hi:[1,0] neg_lo:[1,0] neg_hi:[1,0]
	s_nop 0
	v_pk_fma_f32 v[150:151], v[108:109], v[122:123], v[104:105]
	v_pk_add_f32 v[124:125], v[106:107], 1.0 op_sel_hi:[1,0] neg_lo:[1,0] neg_hi:[1,0]
	v_cmp_gt_f32_e32 vcc, s86, v150
	v_pk_fma_f32 v[104:105], v[118:119], v[124:125], v[106:107]
	v_cmp_gt_f32_e64 s[0:1], s86, v151
	v_cndmask_b32_e64 v106, 0, 32, vcc
	v_pk_add_f32 v[126:127], v[114:115], 1.0 op_sel_hi:[1,0] neg_lo:[1,0] neg_hi:[1,0]
	v_cndmask_b32_e64 v107, 0, 32, s[0:1]
	v_cmp_gt_f32_e64 s[6:7], s86, v104
	v_ldexp_f32 v106, v150, v106
	v_pk_fma_f32 v[114:115], v[120:121], v[126:127], v[114:115]
	v_cndmask_b32_e64 v108, 0, 32, s[6:7]
	v_cmp_gt_f32_e64 s[8:9], s86, v105
	v_ldexp_f32 v107, v151, v107
	v_log_f32_e32 v106, v106
	v_cndmask_b32_e64 v109, 0, 32, s[8:9]
	v_cmp_gt_f32_e64 s[10:11], s86, v114
	v_ldexp_f32 v108, v104, v108
	v_log_f32_e32 v107, v107
	v_cndmask_b32_e64 v118, 0, 32, s[10:11]
	v_cmp_gt_f32_e64 s[12:13], s86, v115
	v_ldexp_f32 v109, v105, v109
	v_log_f32_e32 v108, v108
	v_cndmask_b32_e64 v119, 0, 32, s[12:13]
	v_ldexp_f32 v118, v114, v118
	v_log_f32_e32 v109, v109
	v_ldexp_f32 v119, v115, v119
	v_log_f32_e32 v124, v118
	v_mul_f32_e32 v118, 0x3f317217, v106
	v_log_f32_e32 v125, v119
	v_mul_f32_e32 v119, 0x3f317217, v107
	v_fma_f32 v118, v106, s87, -v118
	v_mul_f32_e32 v126, 0x3f317217, v108
	v_fma_f32 v119, v107, s87, -v119
	v_fmac_f32_e32 v118, 0x3377d1cf, v106
	v_cndmask_b32_e32 v120, 0, v171, vcc
	v_mul_f32_e32 v127, 0x3f317217, v109
	v_fma_f32 v126, v108, s87, -v126
	v_fmac_f32_e32 v119, 0x3377d1cf, v107
	v_fmac_f32_e32 v118, 0x3f317217, v106
	v_cmp_lt_f32_e64 vcc, |v106|, s88
	v_mul_f32_e32 v152, 0x3f317217, v124
	v_fma_f32 v127, v109, s87, -v127
	v_fmac_f32_e32 v126, 0x3377d1cf, v108
	v_fmac_f32_e32 v119, 0x3f317217, v107
	v_cndmask_b32_e32 v106, v106, v118, vcc
	v_cmp_lt_f32_e64 vcc, |v107|, s88
	v_fma_f32 v152, v124, s87, -v152
	v_fmac_f32_e32 v127, 0x3377d1cf, v109
	v_fmac_f32_e32 v126, 0x3f317217, v108
	v_cndmask_b32_e32 v107, v107, v119, vcc
	v_cmp_lt_f32_e64 vcc, |v108|, s88
	v_fmac_f32_e32 v152, 0x3377d1cf, v124
	v_fmac_f32_e32 v127, 0x3f317217, v109
	v_cndmask_b32_e32 v108, v108, v126, vcc
	v_cmp_lt_f32_e64 vcc, |v109|, s88
	v_cndmask_b32_e64 v121, 0, v171, s[0:1]
	v_fmac_f32_e32 v152, 0x3f317217, v124
	v_cndmask_b32_e32 v109, v109, v127, vcc
	v_cmp_lt_f32_e64 vcc, |v124|, s88
	v_cndmask_b32_e64 v122, 0, v171, s[6:7]
	v_sub_f32_e32 v118, v106, v120
	v_sub_f32_e32 v119, v107, v121
	v_cndmask_b32_e32 v106, v124, v152, vcc
	v_cndmask_b32_e64 v107, 0, v171, s[10:11]
	v_sub_f32_e32 v120, v108, v122
	v_sub_f32_e32 v122, v106, v107
	v_mul_f32_e32 v107, 0xbfb8aa3b, v98
	v_mul_f32_e32 v108, 0xbfb8aa3b, v99
	v_exp_f32_e32 v107, v107
	v_exp_f32_e32 v108, v108
	v_cndmask_b32_e64 v123, 0, v171, s[8:9]
	v_mul_f32_e32 v106, 0x3f317217, v125
	v_sub_f32_e32 v121, v109, v123
	v_fma_f32 v123, v125, s87, -v106
	v_add_f32_e32 v106, 1.0, v107
	v_add_f32_e32 v107, 1.0, v108
	v_rcp_f32_e32 v106, v106
	v_rcp_f32_e32 v107, v107
	v_pk_add_f32 v[108:109], v[116:117], 1.0 op_sel_hi:[1,0] neg_lo:[1,0] neg_hi:[1,0]
	v_fmac_f32_e32 v123, 0x3377d1cf, v125
	v_fmac_f32_e32 v123, 0x3f317217, v125
	v_pk_fma_f32 v[106:107], v[106:107], v[108:109], v[116:117]
	v_cmp_lt_f32_e64 s[0:1], |v125|, s88
	v_cmp_gt_f32_e32 vcc, s86, v106
	v_cndmask_b32_e64 v116, 0, v171, s[12:13]
	v_cndmask_b32_e64 v109, v125, v123, s[0:1]
	v_cndmask_b32_e64 v108, 0, 32, vcc
	v_ldexp_f32 v108, v106, v108
	v_log_f32_e32 v108, v108
	v_sub_f32_e32 v123, v109, v116
	v_sub_f32_e32 v104, 1.0, v104
	v_sub_f32_e32 v105, 1.0, v105
	v_mul_f32_e32 v109, 0x3f317217, v108
	v_fma_f32 v109, v108, s87, -v109
	v_fmac_f32_e32 v109, 0x3377d1cf, v108
	v_fmac_f32_e32 v109, 0x3f317217, v108
	v_cmp_lt_f32_e64 s[0:1], |v108|, s88
	v_sub_f32_e32 v114, 1.0, v114
	v_sub_f32_e32 v115, 1.0, v115
	v_cndmask_b32_e64 v108, v108, v109, s[0:1]
	v_cndmask_b32_e32 v109, 0, v171, vcc
	v_cmp_gt_f32_e32 vcc, s86, v107
	v_sub_f32_e32 v124, v108, v109
	v_sub_f32_e32 v109, 1.0, v107
	v_cndmask_b32_e64 v116, 0, 32, vcc
	v_ldexp_f32 v107, v107, v116
	v_log_f32_e32 v116, v107
	v_sub_f32_e32 v108, 1.0, v106
	v_sub_f32_e32 v106, 1.0, v150
	v_sub_f32_e32 v107, 1.0, v151
	v_mul_f32_e32 v117, 0x3f317217, v116
	v_fma_f32 v117, v116, s87, -v117
	v_fmac_f32_e32 v117, 0x3377d1cf, v116
	v_fmac_f32_e32 v117, 0x3f317217, v116
	v_cmp_lt_f32_e64 s[0:1], |v116|, s88
	s_mov_b64 s[6:7], s[16:17]
	s_nop 0
	v_cndmask_b32_e64 v116, v116, v117, s[0:1]
	v_cndmask_b32_e32 v117, 0, v171, vcc
	v_sub_f32_e32 v125, v116, v117
	global_store_dwordx4 v[110:111], v[118:121], off
	global_store_dwordx4 v[110:111], v[122:125], off offset:16

;     __device__ __forceinline__ void operator()(const f32x4 (&acc)[2][2][4][2], const Unit& u, int wr, int wc, int fr, int fq, const Pre& P) const {
;     ...
;                     else if (sec == 1) { dst = KB; const f32x4 l0 = *(const f32x4*)(LBv + c), l1 = *(const f32x4*)(LBv + c + 4); float lf[8];
.LBB0_758:
	v_lshlrev_b32_e32 v99, 2, v138
	v_mov_b32_e32 v102, v238
	v_mov_b32_e32 v103, v239
	v_mov_b32_e32 v104, v240
	v_mov_b32_e32 v105, v241
	v_mov_b32_e32 v106, v242
	v_mov_b32_e32 v107, v243
	v_mov_b32_e32 v108, v244
	v_mov_b32_e32 v109, v245

; __device__ __forceinline__ float sigmoidf_(float x) { return __builtin_amdgcn_rcpf(1.0f + fexp(-x)); }
;     __device__ __forceinline__ void operator()(const f32x4 (&acc)[2][2][4][2], const Unit& u, int wr, int wc, int fr, int fq, const Pre& P) const {
;     ...
;                         for (int j = 0; j < 8; ++j) { const float lb = j < 4 ? l0[j] : l1[j - 4]; const float fg = lb + (1.0f - lb) * sigmoidf_(x[j]); y[j] = 1.0f - fg; lf[j] = __logf(fg); }
	v_mul_f32_e32 v99, 0xbfb8aa3b, v92
	v_mul_f32_e32 v110, 0xbfb8aa3b, v93
	v_mul_f32_e32 v111, 0xbfb8aa3b, v94
	v_exp_f32_e32 v99, v99
	v_exp_f32_e32 v110, v110
	v_mul_f32_e32 v112, 0xbfb8aa3b, v95
	v_exp_f32_e32 v111, v111
	v_mul_f32_e32 v113, 0xbfb8aa3b, v100
	v_exp_f32_e32 v112, v112
	v_mul_f32_e32 v114, 0xbfb8aa3b, v101
	v_exp_f32_e32 v113, v113
	v_exp_f32_e32 v114, v114
	v_add_f32_e32 v99, 1.0, v99
	v_add_f32_e32 v115, 1.0, v110
	v_add_f32_e32 v116, 1.0, v111
	v_rcp_f32_e32 v110, v99
	v_rcp_f32_e32 v111, v115
	v_add_f32_e32 v117, 1.0, v112
	v_add_f32_e32 v118, 1.0, v113
	v_rcp_f32_e32 v112, v116
	v_rcp_f32_e32 v113, v117
	v_add_f32_e32 v119, 1.0, v114
	v_rcp_f32_e32 v114, v118
	v_rcp_f32_e32 v115, v119

; __device__ __forceinline__ float sigmoidf_(float x) { return __builtin_amdgcn_rcpf(1.0f + fexp(-x)); }
;     __device__ __forceinline__ void operator()(const f32x4 (&acc)[2][2][4][2], const Unit& u, int wr, int wc, int fr, int fq, const Pre& P) const {
;     ...
;                         for (int j = 0; j < 8; ++j) { const float lb = j < 4 ? l0[j] : l1[j - 4]; const float fg = lb + (1.0f - lb) * sigmoidf_(x[j]); y[j] = 1.0f - fg; lf[j] = __logf(fg); }
;                         *(f32x4*)(LF + off) = (f32x4){lf[0], lf[1], lf[2], lf[3]}; *(f32x4*)(LF + off + 4) = (f32x4){lf[4], lf[5], lf[6], lf[7]}; }
	v_pk_add_f32 v[116:117], v[102:103], 1.0 op_sel_hi:[1,0] neg_lo:[1,0] neg_hi:[1,0]
	s_nop 0
	v_pk_fma_f32 v[122:123], v[110:111], v[116:117], v[102:103]
	v_pk_add_f32 v[118:119], v[104:105], 1.0 op_sel_hi:[1,0] neg_lo:[1,0] neg_hi:[1,0]
	v_cmp_gt_f32_e32 vcc, s86, v122
	v_pk_fma_f32 v[102:103], v[112:113], v[118:119], v[104:105]
	v_cmp_gt_f32_e64 s[0:1], s86, v123
	v_cndmask_b32_e64 v99, 0, 32, vcc
	v_pk_add_f32 v[120:121], v[106:107], 1.0 op_sel_hi:[1,0] neg_lo:[1,0] neg_hi:[1,0]
	v_cndmask_b32_e64 v104, 0, 32, s[0:1]
	v_cmp_gt_f32_e64 s[6:7], s86, v102
	v_ldexp_f32 v99, v122, v99
	v_pk_fma_f32 v[118:119], v[114:115], v[120:121], v[106:107]
	v_cndmask_b32_e64 v105, 0, 32, s[6:7]
	v_ldexp_f32 v104, v123, v104
	v_log_f32_e32 v99, v99
	v_cmp_gt_f32_e64 s[12:13], s86, v119
	v_ldexp_f32 v105, v102, v105
	v_log_f32_e32 v104, v104
	v_cndmask_b32_e64 v110, 0, 32, s[12:13]
	v_log_f32_e32 v105, v105
	v_ldexp_f32 v110, v119, v110
	v_log_f32_e32 v115, v110
	v_mul_f32_e32 v110, 0x3f317217, v99
	v_mul_f32_e32 v116, 0x3f317217, v104
	v_fma_f32 v110, v99, s87, -v110
	v_mul_f32_e32 v117, 0x3f317217, v105
	v_fma_f32 v116, v104, s87, -v116
	v_fmac_f32_e32 v110, 0x3377d1cf, v99
	v_cmp_gt_f32_e64 s[8:9], s86, v103
	v_cndmask_b32_e32 v111, 0, v171, vcc
	v_fma_f32 v117, v105, s87, -v117
	v_fmac_f32_e32 v116, 0x3377d1cf, v104
	v_fmac_f32_e32 v110, 0x3f317217, v99
	v_cmp_lt_f32_e64 vcc, |v99|, s88
	v_cndmask_b32_e64 v106, 0, 32, s[8:9]
	v_cmp_gt_f32_e64 s[10:11], s86, v118
	v_fmac_f32_e32 v117, 0x3377d1cf, v105
	v_fmac_f32_e32 v116, 0x3f317217, v104
	v_cndmask_b32_e32 v99, v99, v110, vcc
	v_cmp_lt_f32_e64 vcc, |v104|, s88
	v_cndmask_b32_e64 v107, 0, 32, s[10:11]
	v_ldexp_f32 v106, v103, v106
	v_fmac_f32_e32 v117, 0x3f317217, v105
	v_cndmask_b32_e32 v104, v104, v116, vcc
	v_cmp_lt_f32_e64 vcc, |v105|, s88
	v_cndmask_b32_e64 v112, 0, v171, s[0:1]
	v_cndmask_b32_e64 v113, 0, v171, s[6:7]
	v_ldexp_f32 v107, v118, v107
	v_log_f32_e32 v106, v106
	v_cndmask_b32_e32 v105, v105, v117, vcc
	v_log_f32_e32 v107, v107
	v_sub_f32_e32 v110, v99, v111
	v_sub_f32_e32 v111, v104, v112
	v_sub_f32_e32 v112, v105, v113
	v_mul_f32_e32 v104, 0xbfb8aa3b, v90
	v_mul_f32_e32 v105, 0xbfb8aa3b, v91
	v_exp_f32_e32 v104, v104
	v_exp_f32_e32 v105, v105
	v_mul_f32_e32 v120, 0x3f317217, v106
	v_mul_f32_e32 v121, 0x3f317217, v107
	v_fma_f32 v120, v106, s87, -v120
	v_fma_f32 v121, v107, s87, -v121
	v_fmac_f32_e32 v120, 0x3377d1cf, v106
	v_add_f32_e32 v104, 1.0, v104
	v_add_f32_e32 v105, 1.0, v105
	v_fmac_f32_e32 v121, 0x3377d1cf, v107
	v_fmac_f32_e32 v120, 0x3f317217, v106
	v_cmp_lt_f32_e64 vcc, |v106|, s88
	v_rcp_f32_e32 v104, v104
	v_rcp_f32_e32 v105, v105
	v_fmac_f32_e32 v121, 0x3f317217, v107
	v_cndmask_b32_e32 v106, v106, v120, vcc
	v_cmp_lt_f32_e64 vcc, |v107|, s88
	v_cndmask_b32_e64 v114, 0, v171, s[8:9]
	v_cndmask_b32_e64 v99, 0, v171, s[10:11]
	v_cndmask_b32_e32 v107, v107, v121, vcc
	v_sub_f32_e32 v113, v106, v114
	v_sub_f32_e32 v114, v107, v99
	v_pk_add_f32 v[106:107], v[108:109], 1.0 op_sel_hi:[1,0] neg_lo:[1,0] neg_hi:[1,0]
	v_mul_f32_e32 v99, 0x3f317217, v115
	v_pk_fma_f32 v[104:105], v[104:105], v[106:107], v[108:109]
	v_fma_f32 v99, v115, s87, -v99
	v_cmp_gt_f32_e32 vcc, s86, v104
	v_fmac_f32_e32 v99, 0x3377d1cf, v115
	v_fmac_f32_e32 v99, 0x3f317217, v115
	v_cndmask_b32_e64 v106, 0, 32, vcc
	v_ldexp_f32 v106, v104, v106
	v_log_f32_e32 v106, v106
	v_cmp_lt_f32_e64 s[0:1], |v115|, s88
	v_cndmask_b32_e64 v107, 0, v171, s[12:13]
	v_sub_f32_e32 v102, 1.0, v102
	v_cndmask_b32_e64 v99, v115, v99, s[0:1]
	v_sub_f32_e32 v115, v99, v107
	v_mul_f32_e32 v99, 0x3f317217, v106
	v_fma_f32 v99, v106, s87, -v99
	v_fmac_f32_e32 v99, 0x3377d1cf, v106
	v_fmac_f32_e32 v99, 0x3f317217, v106
	v_cmp_lt_f32_e64 s[0:1], |v106|, s88
	v_sub_f32_e32 v103, 1.0, v103
	v_sub_f32_e32 v107, 1.0, v105
	v_cndmask_b32_e64 v99, v106, v99, s[0:1]
	v_cndmask_b32_e32 v106, 0, v171, vcc
	v_cmp_gt_f32_e32 vcc, s86, v105
	v_sub_f32_e32 v116, v99, v106
	v_sub_f32_e32 v106, 1.0, v104
	v_cndmask_b32_e64 v99, 0, 32, vcc
	v_ldexp_f32 v99, v105, v99
	v_log_f32_e32 v99, v99
	v_sub_f32_e32 v104, 1.0, v122
	v_sub_f32_e32 v105, 1.0, v123
	v_sub_f32_e32 v108, 1.0, v118
	v_mul_f32_e32 v117, 0x3f317217, v99
	v_fma_f32 v117, v99, s87, -v117
	v_fmac_f32_e32 v117, 0x3377d1cf, v99
	v_fmac_f32_e32 v117, 0x3f317217, v99
	v_cmp_lt_f32_e64 s[0:1], |v99|, s88
	v_sub_f32_e32 v109, 1.0, v119
	v_lshl_add_u64 v[118:119], v[88:89], 2, s[22:23]
	v_cndmask_b32_e64 v99, v99, v117, s[0:1]
	v_cndmask_b32_e32 v117, 0, v171, vcc
	s_mov_b64 s[6:7], s[16:17]
	v_sub_f32_e32 v117, v99, v117
	global_store_dwordx4 v[118:119], v[110:113], off
	global_store_dwordx4 v[118:119], v[114:117], off offset:16

;     __device__ __forceinline__ void operator()(const f32x4 (&acc)[2][2][4][2], const Unit& u, int wr, int wc, int fr, int fq, const Pre& P) const {
;     ...
;                     else if (sec == 1) { dst = KB; const f32x4 l0 = *(const f32x4*)(LBv + c), l1 = *(const f32x4*)(LBv + c + 4); float lf[8];
.LBB0_772:
	v_lshlrev_b32_e32 v92, 2, v154
	v_mov_b32_e32 v88, v246
	v_mov_b32_e32 v89, v247
	v_mov_b32_e32 v90, v248
	v_mov_b32_e32 v91, v249
	v_mov_b32_e32 v98, v250
	v_mov_b32_e32 v99, v251
	v_mov_b32_e32 v100, v252
	v_mov_b32_e32 v101, v253

; __device__ __forceinline__ float sigmoidf_(float x) { return __builtin_amdgcn_rcpf(1.0f + fexp(-x)); }
;     __device__ __forceinline__ void operator()(const f32x4 (&acc)[2][2][4][2], const Unit& u, int wr, int wc, int fr, int fq, const Pre& P) const {
;     ...
;                         for (int j = 0; j < 8; ++j) { const float lb = j < 4 ? l0[j] : l1[j - 4]; const float fg = lb + (1.0f - lb) * sigmoidf_(x[j]); y[j] = 1.0f - fg; lf[j] = __logf(fg); }
;                         *(f32x4*)(LF + off) = (f32x4){lf[0], lf[1], lf[2], lf[3]}; *(f32x4*)(LF + off + 4) = (f32x4){lf[4], lf[5], lf[6], lf[7]}; }
	v_mul_f32_e32 v92, 0xbfb8aa3b, v84
	v_mul_f32_e32 v93, 0xbfb8aa3b, v85
	v_exp_f32_e32 v92, v92
	v_exp_f32_e32 v93, v93
	v_mul_f32_e32 v102, 0xbfb8aa3b, v86
	v_mul_f32_e32 v103, 0xbfb8aa3b, v87
	v_exp_f32_e32 v102, v102
	v_exp_f32_e32 v103, v103
	v_mul_f32_e32 v104, 0xbfb8aa3b, v80
	v_mul_f32_e32 v105, 0xbfb8aa3b, v81
	v_exp_f32_e32 v104, v104
	v_exp_f32_e32 v105, v105
	v_add_f32_e32 v92, 1.0, v92
	v_add_f32_e32 v93, 1.0, v93
	v_rcp_f32_e32 v92, v92
	v_rcp_f32_e32 v93, v93
	v_add_f32_e32 v102, 1.0, v102
	v_add_f32_e32 v103, 1.0, v103
	v_rcp_f32_e32 v102, v102
	v_rcp_f32_e32 v103, v103
	v_add_f32_e32 v104, 1.0, v104
	v_add_f32_e32 v105, 1.0, v105
	v_rcp_f32_e32 v104, v104
	v_rcp_f32_e32 v105, v105
	v_or_b32_e32 v94, v96, v154
	v_mov_b32_e32 v95, v97
	v_lshl_add_u64 v[94:95], v[94:95], 2, s[22:23]

; __device__ __forceinline__ float sigmoidf_(float x) { return __builtin_amdgcn_rcpf(1.0f + fexp(-x)); }
;     __device__ __forceinline__ void operator()(const f32x4 (&acc)[2][2][4][2], const Unit& u, int wr, int wc, int fr, int fq, const Pre& P) const {
;     ...
;                         for (int j = 0; j < 8; ++j) { const float lb = j < 4 ? l0[j] : l1[j - 4]; const float fg = lb + (1.0f - lb) * sigmoidf_(x[j]); y[j] = 1.0f - fg; lf[j] = __logf(fg); }
;                         *(f32x4*)(LF + off) = (f32x4){lf[0], lf[1], lf[2], lf[3]}; *(f32x4*)(LF + off + 4) = (f32x4){lf[4], lf[5], lf[6], lf[7]}; }
	v_pk_add_f32 v[106:107], v[88:89], 1.0 op_sel_hi:[1,0] neg_lo:[1,0] neg_hi:[1,0]
	s_nop 0
	v_pk_fma_f32 v[112:113], v[92:93], v[106:107], v[88:89]
	v_pk_add_f32 v[108:109], v[90:91], 1.0 op_sel_hi:[1,0] neg_lo:[1,0] neg_hi:[1,0]
	v_cmp_gt_f32_e32 vcc, s86, v112
	v_pk_fma_f32 v[88:89], v[102:103], v[108:109], v[90:91]
	v_cmp_gt_f32_e64 s[0:1], s86, v113
	v_cndmask_b32_e64 v90, 0, 32, vcc
	v_pk_add_f32 v[110:111], v[98:99], 1.0 op_sel_hi:[1,0] neg_lo:[1,0] neg_hi:[1,0]
	v_cndmask_b32_e64 v91, 0, 32, s[0:1]
	v_cmp_gt_f32_e64 s[6:7], s86, v88
	v_ldexp_f32 v90, v112, v90
	v_pk_fma_f32 v[98:99], v[104:105], v[110:111], v[98:99]
	v_cndmask_b32_e64 v92, 0, 32, s[6:7]
	v_cmp_gt_f32_e64 s[8:9], s86, v89
	v_ldexp_f32 v91, v113, v91
	v_log_f32_e32 v90, v90
	v_cndmask_b32_e64 v93, 0, 32, s[8:9]
	v_cmp_gt_f32_e64 s[10:11], s86, v98
	v_ldexp_f32 v92, v88, v92
	v_log_f32_e32 v91, v91
	v_cndmask_b32_e64 v102, 0, 32, s[10:11]
	v_cmp_gt_f32_e64 s[12:13], s86, v99
	v_ldexp_f32 v93, v89, v93
	v_log_f32_e32 v92, v92
	v_cndmask_b32_e64 v103, 0, 32, s[12:13]
	v_ldexp_f32 v102, v98, v102
	v_log_f32_e32 v93, v93
	v_ldexp_f32 v103, v99, v103
	v_log_f32_e32 v108, v102
	v_mul_f32_e32 v102, 0x3f317217, v90
	v_log_f32_e32 v109, v103
	v_mul_f32_e32 v103, 0x3f317217, v91
	v_fma_f32 v102, v90, s87, -v102
	v_mul_f32_e32 v110, 0x3f317217, v92
	v_fma_f32 v103, v91, s87, -v103
	v_fmac_f32_e32 v102, 0x3377d1cf, v90
	v_cndmask_b32_e32 v104, 0, v171, vcc
	v_mul_f32_e32 v111, 0x3f317217, v93
	v_fma_f32 v110, v92, s87, -v110
	v_fmac_f32_e32 v103, 0x3377d1cf, v91
	v_fmac_f32_e32 v102, 0x3f317217, v90
	v_cmp_lt_f32_e64 vcc, |v90|, s88
	v_mul_f32_e32 v114, 0x3f317217, v108
	v_fma_f32 v111, v93, s87, -v111
	v_fmac_f32_e32 v110, 0x3377d1cf, v92
	v_fmac_f32_e32 v103, 0x3f317217, v91
	v_cndmask_b32_e32 v90, v90, v102, vcc
	v_cmp_lt_f32_e64 vcc, |v91|, s88
	v_fma_f32 v114, v108, s87, -v114
	v_fmac_f32_e32 v111, 0x3377d1cf, v93
	v_fmac_f32_e32 v110, 0x3f317217, v92
	v_cndmask_b32_e32 v91, v91, v103, vcc
	v_cmp_lt_f32_e64 vcc, |v92|, s88
	v_fmac_f32_e32 v114, 0x3377d1cf, v108
	v_fmac_f32_e32 v111, 0x3f317217, v93
	v_cndmask_b32_e32 v92, v92, v110, vcc
	v_cmp_lt_f32_e64 vcc, |v93|, s88
	v_cndmask_b32_e64 v105, 0, v171, s[0:1]
	v_fmac_f32_e32 v114, 0x3f317217, v108
	v_cndmask_b32_e32 v93, v93, v111, vcc
	v_cmp_lt_f32_e64 vcc, |v108|, s88
	v_cndmask_b32_e64 v106, 0, v171, s[6:7]
	v_sub_f32_e32 v102, v90, v104
	v_sub_f32_e32 v103, v91, v105
	v_cndmask_b32_e32 v90, v108, v114, vcc
	v_cndmask_b32_e64 v91, 0, v171, s[10:11]
	v_sub_f32_e32 v104, v92, v106
	v_sub_f32_e32 v106, v90, v91
	v_mul_f32_e32 v91, 0xbfb8aa3b, v82
	v_mul_f32_e32 v92, 0xbfb8aa3b, v83
	v_exp_f32_e32 v91, v91
	v_exp_f32_e32 v92, v92
	v_cndmask_b32_e64 v107, 0, v171, s[8:9]
	v_mul_f32_e32 v90, 0x3f317217, v109
	v_sub_f32_e32 v105, v93, v107
	v_fma_f32 v107, v109, s87, -v90
	v_add_f32_e32 v90, 1.0, v91
	v_add_f32_e32 v91, 1.0, v92
	v_rcp_f32_e32 v90, v90
	v_rcp_f32_e32 v91, v91
	v_pk_add_f32 v[92:93], v[100:101], 1.0 op_sel_hi:[1,0] neg_lo:[1,0] neg_hi:[1,0]
	v_fmac_f32_e32 v107, 0x3377d1cf, v109
	v_fmac_f32_e32 v107, 0x3f317217, v109
	v_pk_fma_f32 v[90:91], v[90:91], v[92:93], v[100:101]
	v_cmp_lt_f32_e64 s[0:1], |v109|, s88
	v_cmp_gt_f32_e32 vcc, s86, v90
	v_cndmask_b32_e64 v100, 0, v171, s[12:13]
	v_cndmask_b32_e64 v93, v109, v107, s[0:1]
	v_cndmask_b32_e64 v92, 0, 32, vcc
	v_ldexp_f32 v92, v90, v92
	v_log_f32_e32 v92, v92
	v_sub_f32_e32 v107, v93, v100
	v_sub_f32_e32 v88, 1.0, v88
	v_sub_f32_e32 v89, 1.0, v89
	v_mul_f32_e32 v93, 0x3f317217, v92
	v_fma_f32 v93, v92, s87, -v93
	v_fmac_f32_e32 v93, 0x3377d1cf, v92
	v_fmac_f32_e32 v93, 0x3f317217, v92
	v_cmp_lt_f32_e64 s[0:1], |v92|, s88
	v_sub_f32_e32 v98, 1.0, v98
	v_sub_f32_e32 v99, 1.0, v99
	v_cndmask_b32_e64 v92, v92, v93, s[0:1]
	v_cndmask_b32_e32 v93, 0, v171, vcc
	v_cmp_gt_f32_e32 vcc, s86, v91
	v_sub_f32_e32 v108, v92, v93
	v_sub_f32_e32 v93, 1.0, v91
	v_cndmask_b32_e64 v100, 0, 32, vcc
	v_ldexp_f32 v91, v91, v100
	v_log_f32_e32 v100, v91
	v_sub_f32_e32 v92, 1.0, v90
	v_sub_f32_e32 v90, 1.0, v112
	v_sub_f32_e32 v91, 1.0, v113
	v_mul_f32_e32 v101, 0x3f317217, v100
	v_fma_f32 v101, v100, s87, -v101
	v_fmac_f32_e32 v101, 0x3377d1cf, v100
	v_fmac_f32_e32 v101, 0x3f317217, v100
	v_cmp_lt_f32_e64 s[0:1], |v100|, s88
	s_mov_b64 s[6:7], s[16:17]
	s_nop 0
	v_cndmask_b32_e64 v100, v100, v101, s[0:1]
	v_cndmask_b32_e32 v101, 0, v171, vcc
	v_sub_f32_e32 v109, v100, v101
	global_store_dwordx4 v[94:95], v[102:105], off
	global_store_dwordx4 v[94:95], v[106:109], off offset:16

;     __device__ __forceinline__ void operator()(const f32x4 (&acc)[2][2][4][2], const Unit& u, int wr, int wc, int fr, int fq, const Pre& P) const {
;     ...
;                     else if (sec == 1) { dst = KB; const f32x4 l0 = *(const f32x4*)(LBv + c), l1 = *(const f32x4*)(LBv + c + 4); float lf[8];
.LBB0_786:
	v_lshlrev_b32_e32 v83, 2, v138
	v_mov_b32_e32 v86, v238
	v_mov_b32_e32 v87, v239
	v_mov_b32_e32 v88, v240
	v_mov_b32_e32 v89, v241
	v_mov_b32_e32 v90, v242
	v_mov_b32_e32 v91, v243
	v_mov_b32_e32 v92, v244
	v_mov_b32_e32 v93, v245

; __device__ __forceinline__ float sigmoidf_(float x) { return __builtin_amdgcn_rcpf(1.0f + fexp(-x)); }
;     __device__ __forceinline__ void operator()(const f32x4 (&acc)[2][2][4][2], const Unit& u, int wr, int wc, int fr, int fq, const Pre& P) const {
;     ...
;                         for (int j = 0; j < 8; ++j) { const float lb = j < 4 ? l0[j] : l1[j - 4]; const float fg = lb + (1.0f - lb) * sigmoidf_(x[j]); y[j] = 1.0f - fg; lf[j] = __logf(fg); }
	v_mul_f32_e32 v83, 0xbfb8aa3b, v76
	v_mul_f32_e32 v94, 0xbfb8aa3b, v77
	v_mul_f32_e32 v95, 0xbfb8aa3b, v78
	v_exp_f32_e32 v83, v83
	v_exp_f32_e32 v94, v94
	v_mul_f32_e32 v96, 0xbfb8aa3b, v79
	v_exp_f32_e32 v95, v95
	v_mul_f32_e32 v97, 0xbfb8aa3b, v84
	v_exp_f32_e32 v96, v96
	v_mul_f32_e32 v98, 0xbfb8aa3b, v85
	v_exp_f32_e32 v97, v97
	v_exp_f32_e32 v98, v98
	v_add_f32_e32 v83, 1.0, v83
	v_add_f32_e32 v99, 1.0, v94
	v_add_f32_e32 v100, 1.0, v95
	v_rcp_f32_e32 v94, v83
	v_rcp_f32_e32 v95, v99
	v_add_f32_e32 v101, 1.0, v96
	v_add_f32_e32 v102, 1.0, v97
	v_rcp_f32_e32 v96, v100
	v_rcp_f32_e32 v97, v101
	v_add_f32_e32 v103, 1.0, v98
	v_rcp_f32_e32 v98, v102
	v_rcp_f32_e32 v99, v103

; __device__ __forceinline__ float sigmoidf_(float x) { return __builtin_amdgcn_rcpf(1.0f + fexp(-x)); }
;     __device__ __forceinline__ void operator()(const f32x4 (&acc)[2][2][4][2], const Unit& u, int wr, int wc, int fr, int fq, const Pre& P) const {
;     ...
;                         for (int j = 0; j < 8; ++j) { const float lb = j < 4 ? l0[j] : l1[j - 4]; const float fg = lb + (1.0f - lb) * sigmoidf_(x[j]); y[j] = 1.0f - fg; lf[j] = __logf(fg); }
;                         *(f32x4*)(LF + off) = (f32x4){lf[0], lf[1], lf[2], lf[3]}; *(f32x4*)(LF + off + 4) = (f32x4){lf[4], lf[5], lf[6], lf[7]}; }
	v_pk_add_f32 v[100:101], v[86:87], 1.0 op_sel_hi:[1,0] neg_lo:[1,0] neg_hi:[1,0]
	s_nop 0
	v_pk_fma_f32 v[106:107], v[94:95], v[100:101], v[86:87]
	v_pk_add_f32 v[102:103], v[88:89], 1.0 op_sel_hi:[1,0] neg_lo:[1,0] neg_hi:[1,0]
	v_cmp_gt_f32_e32 vcc, s86, v106
	v_pk_fma_f32 v[86:87], v[96:97], v[102:103], v[88:89]
	v_cmp_gt_f32_e64 s[0:1], s86, v107
	v_cndmask_b32_e64 v83, 0, 32, vcc
	v_pk_add_f32 v[104:105], v[90:91], 1.0 op_sel_hi:[1,0] neg_lo:[1,0] neg_hi:[1,0]
	v_cndmask_b32_e64 v88, 0, 32, s[0:1]
	v_cmp_gt_f32_e64 s[6:7], s86, v86
	v_ldexp_f32 v83, v106, v83
	v_pk_fma_f32 v[102:103], v[98:99], v[104:105], v[90:91]
	v_cndmask_b32_e64 v89, 0, 32, s[6:7]
	v_ldexp_f32 v88, v107, v88
	v_log_f32_e32 v83, v83
	v_cmp_gt_f32_e64 s[12:13], s86, v103
	v_ldexp_f32 v89, v86, v89
	v_log_f32_e32 v88, v88
	v_cndmask_b32_e64 v94, 0, 32, s[12:13]
	v_log_f32_e32 v89, v89
	v_ldexp_f32 v94, v103, v94
	v_log_f32_e32 v99, v94
	v_mul_f32_e32 v94, 0x3f317217, v83
	v_mul_f32_e32 v100, 0x3f317217, v88
	v_fma_f32 v94, v83, s87, -v94
	v_mul_f32_e32 v101, 0x3f317217, v89
	v_fma_f32 v100, v88, s87, -v100
	v_fmac_f32_e32 v94, 0x3377d1cf, v83
	v_cmp_gt_f32_e64 s[8:9], s86, v87
	v_cndmask_b32_e32 v95, 0, v171, vcc
	v_fma_f32 v101, v89, s87, -v101
	v_fmac_f32_e32 v100, 0x3377d1cf, v88
	v_fmac_f32_e32 v94, 0x3f317217, v83
	v_cmp_lt_f32_e64 vcc, |v83|, s88
	v_cndmask_b32_e64 v90, 0, 32, s[8:9]
	v_cmp_gt_f32_e64 s[10:11], s86, v102
	v_fmac_f32_e32 v101, 0x3377d1cf, v89
	v_fmac_f32_e32 v100, 0x3f317217, v88
	v_cndmask_b32_e32 v83, v83, v94, vcc
	v_cmp_lt_f32_e64 vcc, |v88|, s88
	v_cndmask_b32_e64 v91, 0, 32, s[10:11]
	v_ldexp_f32 v90, v87, v90
	v_fmac_f32_e32 v101, 0x3f317217, v89
	v_cndmask_b32_e32 v88, v88, v100, vcc
	v_cmp_lt_f32_e64 vcc, |v89|, s88
	v_cndmask_b32_e64 v96, 0, v171, s[0:1]
	v_cndmask_b32_e64 v97, 0, v171, s[6:7]
	v_ldexp_f32 v91, v102, v91
	v_log_f32_e32 v90, v90
	v_cndmask_b32_e32 v89, v89, v101, vcc
	v_log_f32_e32 v91, v91
	v_sub_f32_e32 v94, v83, v95
	v_sub_f32_e32 v95, v88, v96
	v_sub_f32_e32 v96, v89, v97
	v_mul_f32_e32 v88, 0xbfb8aa3b, v74
	v_mul_f32_e32 v89, 0xbfb8aa3b, v75
	v_exp_f32_e32 v88, v88
	v_exp_f32_e32 v89, v89
	v_mul_f32_e32 v104, 0x3f317217, v90
	v_mul_f32_e32 v105, 0x3f317217, v91
	v_fma_f32 v104, v90, s87, -v104
	v_fma_f32 v105, v91, s87, -v105
	v_fmac_f32_e32 v104, 0x3377d1cf, v90
	v_add_f32_e32 v88, 1.0, v88
	v_add_f32_e32 v89, 1.0, v89
	v_fmac_f32_e32 v105, 0x3377d1cf, v91
	v_fmac_f32_e32 v104, 0x3f317217, v90
	v_cmp_lt_f32_e64 vcc, |v90|, s88
	v_rcp_f32_e32 v88, v88
	v_rcp_f32_e32 v89, v89
	v_fmac_f32_e32 v105, 0x3f317217, v91
	v_cndmask_b32_e32 v90, v90, v104, vcc
	v_cmp_lt_f32_e64 vcc, |v91|, s88
	v_cndmask_b32_e64 v98, 0, v171, s[8:9]
	v_cndmask_b32_e64 v83, 0, v171, s[10:11]
	v_cndmask_b32_e32 v91, v91, v105, vcc
	v_sub_f32_e32 v97, v90, v98
	v_sub_f32_e32 v98, v91, v83
	v_pk_add_f32 v[90:91], v[92:93], 1.0 op_sel_hi:[1,0] neg_lo:[1,0] neg_hi:[1,0]
	v_mul_f32_e32 v83, 0x3f317217, v99
	v_pk_fma_f32 v[88:89], v[88:89], v[90:91], v[92:93]
	v_fma_f32 v83, v99, s87, -v83
	v_cmp_gt_f32_e32 vcc, s86, v88
	v_fmac_f32_e32 v83, 0x3377d1cf, v99
	v_fmac_f32_e32 v83, 0x3f317217, v99
	v_cndmask_b32_e64 v90, 0, 32, vcc
	v_ldexp_f32 v90, v88, v90
	v_log_f32_e32 v90, v90
	v_cmp_lt_f32_e64 s[0:1], |v99|, s88
	v_cndmask_b32_e64 v91, 0, v171, s[12:13]
	v_sub_f32_e32 v86, 1.0, v86
	v_cndmask_b32_e64 v83, v99, v83, s[0:1]
	v_sub_f32_e32 v99, v83, v91
	v_mul_f32_e32 v83, 0x3f317217, v90
	v_fma_f32 v83, v90, s87, -v83
	v_fmac_f32_e32 v83, 0x3377d1cf, v90
	v_fmac_f32_e32 v83, 0x3f317217, v90
	v_cmp_lt_f32_e64 s[0:1], |v90|, s88
	v_sub_f32_e32 v87, 1.0, v87
	v_sub_f32_e32 v91, 1.0, v89
	v_cndmask_b32_e64 v83, v90, v83, s[0:1]
	v_cndmask_b32_e32 v90, 0, v171, vcc
	v_cmp_gt_f32_e32 vcc, s86, v89
	v_sub_f32_e32 v100, v83, v90
	v_sub_f32_e32 v90, 1.0, v88
	v_cndmask_b32_e64 v83, 0, 32, vcc
	v_ldexp_f32 v83, v89, v83
	v_log_f32_e32 v83, v83
	v_sub_f32_e32 v88, 1.0, v106
	v_sub_f32_e32 v89, 1.0, v107
	v_sub_f32_e32 v92, 1.0, v102
	v_mul_f32_e32 v101, 0x3f317217, v83
	v_fma_f32 v101, v83, s87, -v101
	v_fmac_f32_e32 v101, 0x3377d1cf, v83
	v_fmac_f32_e32 v101, 0x3f317217, v83
	v_cmp_lt_f32_e64 s[0:1], |v83|, s88
	v_sub_f32_e32 v93, 1.0, v103
	v_lshl_add_u64 v[102:103], v[72:73], 2, s[22:23]
	v_cndmask_b32_e64 v83, v83, v101, s[0:1]
	v_cndmask_b32_e32 v101, 0, v171, vcc
	s_mov_b64 s[6:7], s[16:17]
	v_sub_f32_e32 v101, v83, v101
	global_store_dwordx4 v[102:103], v[94:97], off
	global_store_dwordx4 v[102:103], v[98:101], off offset:16

;     __device__ __forceinline__ void operator()(const f32x4 (&acc)[2][2][4][2], const Unit& u, int wr, int wc, int fr, int fq, const Pre& P) const {
;     ...
;                     else if (sec == 1) { dst = KB; const f32x4 l0 = *(const f32x4*)(LBv + c), l1 = *(const f32x4*)(LBv + c + 4); float lf[8];
.LBB0_800:
	v_lshlrev_b32_e32 v76, 2, v154
	v_mov_b32_e32 v72, v246
	v_mov_b32_e32 v73, v247
	v_mov_b32_e32 v74, v248
	v_mov_b32_e32 v75, v249
	v_mov_b32_e32 v82, v250
	v_mov_b32_e32 v83, v251
	v_mov_b32_e32 v84, v252
	v_mov_b32_e32 v85, v253

; __device__ __forceinline__ float sigmoidf_(float x) { return __builtin_amdgcn_rcpf(1.0f + fexp(-x)); }
;     __device__ __forceinline__ void operator()(const f32x4 (&acc)[2][2][4][2], const Unit& u, int wr, int wc, int fr, int fq, const Pre& P) const {
;     ...
;                         for (int j = 0; j < 8; ++j) { const float lb = j < 4 ? l0[j] : l1[j - 4]; const float fg = lb + (1.0f - lb) * sigmoidf_(x[j]); y[j] = 1.0f - fg; lf[j] = __logf(fg); }
;                         *(f32x4*)(LF + off) = (f32x4){lf[0], lf[1], lf[2], lf[3]}; *(f32x4*)(LF + off + 4) = (f32x4){lf[4], lf[5], lf[6], lf[7]}; }
	v_mul_f32_e32 v76, 0xbfb8aa3b, v68
	v_mul_f32_e32 v77, 0xbfb8aa3b, v69
	v_exp_f32_e32 v76, v76
	v_exp_f32_e32 v77, v77
	v_mul_f32_e32 v86, 0xbfb8aa3b, v70
	v_mul_f32_e32 v87, 0xbfb8aa3b, v71
	v_exp_f32_e32 v86, v86
	v_exp_f32_e32 v87, v87
	v_mul_f32_e32 v88, 0xbfb8aa3b, v64
	v_mul_f32_e32 v89, 0xbfb8aa3b, v65
	v_exp_f32_e32 v88, v88
	v_exp_f32_e32 v89, v89
	v_add_f32_e32 v76, 1.0, v76
	v_add_f32_e32 v77, 1.0, v77
	v_rcp_f32_e32 v76, v76
	v_rcp_f32_e32 v77, v77
	v_add_f32_e32 v86, 1.0, v86
	v_add_f32_e32 v87, 1.0, v87
	v_rcp_f32_e32 v86, v86
	v_rcp_f32_e32 v87, v87
	v_add_f32_e32 v88, 1.0, v88
	v_add_f32_e32 v89, 1.0, v89
	v_rcp_f32_e32 v88, v88
	v_rcp_f32_e32 v89, v89
	v_or_b32_e32 v78, v80, v154
	v_mov_b32_e32 v79, v81
	v_lshl_add_u64 v[78:79], v[78:79], 2, s[22:23]

; __device__ __forceinline__ float sigmoidf_(float x) { return __builtin_amdgcn_rcpf(1.0f + fexp(-x)); }
;     __device__ __forceinline__ void operator()(const f32x4 (&acc)[2][2][4][2], const Unit& u, int wr, int wc, int fr, int fq, const Pre& P) const {
;     ...
;                         for (int j = 0; j < 8; ++j) { const float lb = j < 4 ? l0[j] : l1[j - 4]; const float fg = lb + (1.0f - lb) * sigmoidf_(x[j]); y[j] = 1.0f - fg; lf[j] = __logf(fg); }
;                         *(f32x4*)(LF + off) = (f32x4){lf[0], lf[1], lf[2], lf[3]}; *(f32x4*)(LF + off + 4) = (f32x4){lf[4], lf[5], lf[6], lf[7]}; }
	v_pk_add_f32 v[90:91], v[72:73], 1.0 op_sel_hi:[1,0] neg_lo:[1,0] neg_hi:[1,0]
	s_nop 0
	v_pk_fma_f32 v[96:97], v[76:77], v[90:91], v[72:73]
	v_pk_add_f32 v[92:93], v[74:75], 1.0 op_sel_hi:[1,0] neg_lo:[1,0] neg_hi:[1,0]
	v_cmp_gt_f32_e32 vcc, s86, v96
	v_pk_fma_f32 v[72:73], v[86:87], v[92:93], v[74:75]
	v_cmp_gt_f32_e64 s[0:1], s86, v97
	v_cndmask_b32_e64 v74, 0, 32, vcc
	v_pk_add_f32 v[94:95], v[82:83], 1.0 op_sel_hi:[1,0] neg_lo:[1,0] neg_hi:[1,0]
	v_cndmask_b32_e64 v75, 0, 32, s[0:1]
	v_cmp_gt_f32_e64 s[6:7], s86, v72
	v_ldexp_f32 v74, v96, v74
	v_pk_fma_f32 v[82:83], v[88:89], v[94:95], v[82:83]
	v_cndmask_b32_e64 v76, 0, 32, s[6:7]
	v_cmp_gt_f32_e64 s[8:9], s86, v73
	v_ldexp_f32 v75, v97, v75
	v_log_f32_e32 v74, v74
	v_cndmask_b32_e64 v77, 0, 32, s[8:9]
	v_cmp_gt_f32_e64 s[10:11], s86, v82
	v_ldexp_f32 v76, v72, v76
	v_log_f32_e32 v75, v75
	v_cndmask_b32_e64 v86, 0, 32, s[10:11]
	v_cmp_gt_f32_e64 s[12:13], s86, v83
	v_ldexp_f32 v77, v73, v77
	v_log_f32_e32 v76, v76
	v_cndmask_b32_e64 v87, 0, 32, s[12:13]
	v_ldexp_f32 v86, v82, v86
	v_log_f32_e32 v77, v77
	v_ldexp_f32 v87, v83, v87
	v_log_f32_e32 v92, v86
	v_mul_f32_e32 v86, 0x3f317217, v74
	v_log_f32_e32 v93, v87
	v_mul_f32_e32 v87, 0x3f317217, v75
	v_fma_f32 v86, v74, s87, -v86
	v_mul_f32_e32 v94, 0x3f317217, v76
	v_fma_f32 v87, v75, s87, -v87
	v_fmac_f32_e32 v86, 0x3377d1cf, v74
	v_cndmask_b32_e32 v88, 0, v171, vcc
	v_mul_f32_e32 v95, 0x3f317217, v77
	v_fma_f32 v94, v76, s87, -v94
	v_fmac_f32_e32 v87, 0x3377d1cf, v75
	v_fmac_f32_e32 v86, 0x3f317217, v74
	v_cmp_lt_f32_e64 vcc, |v74|, s88
	v_mul_f32_e32 v98, 0x3f317217, v92
	v_fma_f32 v95, v77, s87, -v95
	v_fmac_f32_e32 v94, 0x3377d1cf, v76
	v_fmac_f32_e32 v87, 0x3f317217, v75
	v_cndmask_b32_e32 v74, v74, v86, vcc
	v_cmp_lt_f32_e64 vcc, |v75|, s88
	v_fma_f32 v98, v92, s87, -v98
	v_fmac_f32_e32 v95, 0x3377d1cf, v77
	v_fmac_f32_e32 v94, 0x3f317217, v76
	v_cndmask_b32_e32 v75, v75, v87, vcc
	v_cmp_lt_f32_e64 vcc, |v76|, s88
	v_fmac_f32_e32 v98, 0x3377d1cf, v92
	v_fmac_f32_e32 v95, 0x3f317217, v77
	v_cndmask_b32_e32 v76, v76, v94, vcc
	v_cmp_lt_f32_e64 vcc, |v77|, s88
	v_cndmask_b32_e64 v89, 0, v171, s[0:1]
	v_fmac_f32_e32 v98, 0x3f317217, v92
	v_cndmask_b32_e32 v77, v77, v95, vcc
	v_cmp_lt_f32_e64 vcc, |v92|, s88
	v_cndmask_b32_e64 v90, 0, v171, s[6:7]
	v_sub_f32_e32 v86, v74, v88
	v_sub_f32_e32 v87, v75, v89
	v_cndmask_b32_e32 v74, v92, v98, vcc
	v_cndmask_b32_e64 v75, 0, v171, s[10:11]
	v_sub_f32_e32 v88, v76, v90
	v_sub_f32_e32 v90, v74, v75
	v_mul_f32_e32 v75, 0xbfb8aa3b, v66
	v_mul_f32_e32 v76, 0xbfb8aa3b, v67
	v_exp_f32_e32 v75, v75
	v_exp_f32_e32 v76, v76
	v_cndmask_b32_e64 v91, 0, v171, s[8:9]
	v_mul_f32_e32 v74, 0x3f317217, v93
	v_sub_f32_e32 v89, v77, v91
	v_fma_f32 v91, v93, s87, -v74
	v_add_f32_e32 v74, 1.0, v75
	v_add_f32_e32 v75, 1.0, v76
	v_rcp_f32_e32 v74, v74
	v_rcp_f32_e32 v75, v75
	v_pk_add_f32 v[76:77], v[84:85], 1.0 op_sel_hi:[1,0] neg_lo:[1,0] neg_hi:[1,0]
	v_fmac_f32_e32 v91, 0x3377d1cf, v93
	v_fmac_f32_e32 v91, 0x3f317217, v93
	v_pk_fma_f32 v[74:75], v[74:75], v[76:77], v[84:85]
	v_cmp_lt_f32_e64 s[0:1], |v93|, s88
	v_cmp_gt_f32_e32 vcc, s86, v74
	v_cndmask_b32_e64 v84, 0, v171, s[12:13]
	v_cndmask_b32_e64 v77, v93, v91, s[0:1]
	v_cndmask_b32_e64 v76, 0, 32, vcc
	v_ldexp_f32 v76, v74, v76
	v_log_f32_e32 v76, v76
	v_sub_f32_e32 v91, v77, v84
	v_sub_f32_e32 v72, 1.0, v72
	v_sub_f32_e32 v73, 1.0, v73
	v_mul_f32_e32 v77, 0x3f317217, v76
	v_fma_f32 v77, v76, s87, -v77
	v_fmac_f32_e32 v77, 0x3377d1cf, v76
	v_fmac_f32_e32 v77, 0x3f317217, v76
	v_cmp_lt_f32_e64 s[0:1], |v76|, s88
	v_sub_f32_e32 v82, 1.0, v82
	v_sub_f32_e32 v83, 1.0, v83
	v_cndmask_b32_e64 v76, v76, v77, s[0:1]
	v_cndmask_b32_e32 v77, 0, v171, vcc
	v_cmp_gt_f32_e32 vcc, s86, v75
	v_sub_f32_e32 v92, v76, v77
	v_sub_f32_e32 v77, 1.0, v75
	v_cndmask_b32_e64 v84, 0, 32, vcc
	v_ldexp_f32 v75, v75, v84
	v_log_f32_e32 v84, v75
	v_sub_f32_e32 v76, 1.0, v74
	v_sub_f32_e32 v74, 1.0, v96
	v_sub_f32_e32 v75, 1.0, v97
	v_mul_f32_e32 v85, 0x3f317217, v84
	v_fma_f32 v85, v84, s87, -v85
	v_fmac_f32_e32 v85, 0x3377d1cf, v84
	v_fmac_f32_e32 v85, 0x3f317217, v84
	v_cmp_lt_f32_e64 s[0:1], |v84|, s88
	s_mov_b64 s[6:7], s[16:17]
	s_nop 0
	v_cndmask_b32_e64 v84, v84, v85, s[0:1]
	v_cndmask_b32_e32 v85, 0, v171, vcc
	v_sub_f32_e32 v93, v84, v85
	global_store_dwordx4 v[78:79], v[86:89], off
	global_store_dwordx4 v[78:79], v[90:93], off offset:16

;     __device__ __forceinline__ void operator()(const f32x4 (&acc)[2][2][4][2], const Unit& u, int wr, int wc, int fr, int fq, const Pre& P) const {
;     ...
;                     else if (sec == 1) { dst = KB; const f32x4 l0 = *(const f32x4*)(LBv + c), l1 = *(const f32x4*)(LBv + c + 4); float lf[8];
.LBB0_814:
	v_lshlrev_b32_e32 v67, 2, v138
	v_mov_b32_e32 v70, v238
	v_mov_b32_e32 v71, v239
	v_mov_b32_e32 v72, v240
	v_mov_b32_e32 v73, v241
	v_mov_b32_e32 v74, v242
	v_mov_b32_e32 v75, v243
	v_mov_b32_e32 v76, v244
	v_mov_b32_e32 v77, v245

; __device__ __forceinline__ float fexp(float x) { return __builtin_amdgcn_exp2f(x * 1.4426950408889634f); }
; __device__ __forceinline__ float sigmoidf_(float x) { return __builtin_amdgcn_rcpf(1.0f + fexp(-x)); }
;     __device__ __forceinline__ void operator()(const f32x4 (&acc)[2][2][4][2], const Unit& u, int wr, int wc, int fr, int fq, const Pre& P) const {
;     ...
;                         for (int j = 0; j < 8; ++j) { const float lb = j < 4 ? l0[j] : l1[j - 4]; const float fg = lb + (1.0f - lb) * sigmoidf_(x[j]); y[j] = 1.0f - fg; lf[j] = __logf(fg); }
	v_mul_f32_e32 v67, 0xbfb8aa3b, v60
	v_mul_f32_e32 v78, 0xbfb8aa3b, v61
	v_mul_f32_e32 v79, 0xbfb8aa3b, v62
	v_exp_f32_e32 v67, v67
	v_exp_f32_e32 v78, v78
	v_mul_f32_e32 v80, 0xbfb8aa3b, v63
	v_exp_f32_e32 v79, v79
	v_mul_f32_e32 v81, 0xbfb8aa3b, v68
	v_exp_f32_e32 v80, v80
	v_mul_f32_e32 v82, 0xbfb8aa3b, v69
	v_exp_f32_e32 v81, v81
	v_exp_f32_e32 v82, v82
	v_add_f32_e32 v67, 1.0, v67
	v_add_f32_e32 v83, 1.0, v78
	v_add_f32_e32 v84, 1.0, v79
	v_rcp_f32_e32 v78, v67
	v_rcp_f32_e32 v79, v83
	v_add_f32_e32 v85, 1.0, v80
	v_add_f32_e32 v86, 1.0, v81
	v_rcp_f32_e32 v80, v84
	v_rcp_f32_e32 v81, v85
	v_add_f32_e32 v87, 1.0, v82
	v_rcp_f32_e32 v82, v86
	v_rcp_f32_e32 v83, v87

; __device__ __forceinline__ float sigmoidf_(float x) { return __builtin_amdgcn_rcpf(1.0f + fexp(-x)); }
;     __device__ __forceinline__ void operator()(const f32x4 (&acc)[2][2][4][2], const Unit& u, int wr, int wc, int fr, int fq, const Pre& P) const {
;     ...
;                     else if (sec == 1) { dst = KB; const f32x4 l0 = *(const f32x4*)(LBv + c), l1 = *(const f32x4*)(LBv + c + 4); float lf[8];
; #pragma unroll
;                         for (int j = 0; j < 8; ++j) { const float lb = j < 4 ? l0[j] : l1[j - 4]; const float fg = lb + (1.0f - lb) * sigmoidf_(x[j]); y[j] = 1.0f - fg; lf[j] = __logf(fg); }
;                         *(f32x4*)(LF + off) = (f32x4){lf[0], lf[1], lf[2], lf[3]}; *(f32x4*)(LF + off + 4) = (f32x4){lf[4], lf[5], lf[6], lf[7]}; }
	v_pk_add_f32 v[84:85], v[70:71], 1.0 op_sel_hi:[1,0] neg_lo:[1,0] neg_hi:[1,0]
	s_nop 0
	v_pk_fma_f32 v[90:91], v[78:79], v[84:85], v[70:71]
	v_pk_add_f32 v[86:87], v[72:73], 1.0 op_sel_hi:[1,0] neg_lo:[1,0] neg_hi:[1,0]
	v_cmp_gt_f32_e32 vcc, s86, v90
	v_pk_fma_f32 v[70:71], v[80:81], v[86:87], v[72:73]
	v_cmp_gt_f32_e64 s[0:1], s86, v91
	v_cndmask_b32_e64 v67, 0, 32, vcc
	v_pk_add_f32 v[88:89], v[74:75], 1.0 op_sel_hi:[1,0] neg_lo:[1,0] neg_hi:[1,0]
	v_cndmask_b32_e64 v72, 0, 32, s[0:1]
	v_cmp_gt_f32_e64 s[6:7], s86, v70
	v_ldexp_f32 v67, v90, v67
	v_pk_fma_f32 v[86:87], v[82:83], v[88:89], v[74:75]
	v_cndmask_b32_e64 v73, 0, 32, s[6:7]
	v_ldexp_f32 v72, v91, v72
	v_log_f32_e32 v67, v67
	v_cmp_gt_f32_e64 s[12:13], s86, v87
	v_ldexp_f32 v73, v70, v73
	v_log_f32_e32 v72, v72
	v_cndmask_b32_e64 v78, 0, 32, s[12:13]
	v_log_f32_e32 v73, v73
	v_ldexp_f32 v78, v87, v78
	v_log_f32_e32 v83, v78
	v_mul_f32_e32 v78, 0x3f317217, v67
	v_mul_f32_e32 v84, 0x3f317217, v72
	v_fma_f32 v78, v67, s87, -v78
	v_mul_f32_e32 v85, 0x3f317217, v73
	v_fma_f32 v84, v72, s87, -v84
	v_fmac_f32_e32 v78, 0x3377d1cf, v67
	v_cmp_gt_f32_e64 s[8:9], s86, v71
	v_cndmask_b32_e32 v79, 0, v171, vcc
	v_fma_f32 v85, v73, s87, -v85
	v_fmac_f32_e32 v84, 0x3377d1cf, v72
	v_fmac_f32_e32 v78, 0x3f317217, v67
	v_cmp_lt_f32_e64 vcc, |v67|, s88
	v_cndmask_b32_e64 v74, 0, 32, s[8:9]
	v_cmp_gt_f32_e64 s[10:11], s86, v86
	v_fmac_f32_e32 v85, 0x3377d1cf, v73
	v_fmac_f32_e32 v84, 0x3f317217, v72
	v_cndmask_b32_e32 v67, v67, v78, vcc
	v_cmp_lt_f32_e64 vcc, |v72|, s88
	v_cndmask_b32_e64 v75, 0, 32, s[10:11]
	v_ldexp_f32 v74, v71, v74
	v_fmac_f32_e32 v85, 0x3f317217, v73
	v_cndmask_b32_e32 v72, v72, v84, vcc
	v_cmp_lt_f32_e64 vcc, |v73|, s88
	v_cndmask_b32_e64 v80, 0, v171, s[0:1]
	v_cndmask_b32_e64 v81, 0, v171, s[6:7]
	v_ldexp_f32 v75, v86, v75
	v_log_f32_e32 v74, v74
	v_cndmask_b32_e32 v73, v73, v85, vcc
	v_log_f32_e32 v75, v75
	v_sub_f32_e32 v78, v67, v79
	v_sub_f32_e32 v79, v72, v80
	v_sub_f32_e32 v80, v73, v81
	v_mul_f32_e32 v72, 0xbfb8aa3b, v58
	v_mul_f32_e32 v73, 0xbfb8aa3b, v59
	v_exp_f32_e32 v72, v72
	v_exp_f32_e32 v73, v73
	v_mul_f32_e32 v88, 0x3f317217, v74
	v_mul_f32_e32 v89, 0x3f317217, v75
	v_fma_f32 v88, v74, s87, -v88
	v_fma_f32 v89, v75, s87, -v89
	v_fmac_f32_e32 v88, 0x3377d1cf, v74
	v_add_f32_e32 v72, 1.0, v72
	v_add_f32_e32 v73, 1.0, v73
	v_fmac_f32_e32 v89, 0x3377d1cf, v75
	v_fmac_f32_e32 v88, 0x3f317217, v74
	v_cmp_lt_f32_e64 vcc, |v74|, s88
	v_rcp_f32_e32 v72, v72
	v_rcp_f32_e32 v73, v73
	v_fmac_f32_e32 v89, 0x3f317217, v75
	v_cndmask_b32_e32 v74, v74, v88, vcc
	v_cmp_lt_f32_e64 vcc, |v75|, s88
	v_cndmask_b32_e64 v82, 0, v171, s[8:9]
	v_cndmask_b32_e64 v67, 0, v171, s[10:11]
	v_cndmask_b32_e32 v75, v75, v89, vcc
	v_sub_f32_e32 v81, v74, v82
	v_sub_f32_e32 v82, v75, v67
	v_pk_add_f32 v[74:75], v[76:77], 1.0 op_sel_hi:[1,0] neg_lo:[1,0] neg_hi:[1,0]
	v_mul_f32_e32 v67, 0x3f317217, v83
	v_pk_fma_f32 v[72:73], v[72:73], v[74:75], v[76:77]
	v_fma_f32 v67, v83, s87, -v67
	v_cmp_gt_f32_e32 vcc, s86, v72
	v_fmac_f32_e32 v67, 0x3377d1cf, v83
	v_fmac_f32_e32 v67, 0x3f317217, v83
	v_cndmask_b32_e64 v74, 0, 32, vcc
	v_ldexp_f32 v74, v72, v74
	v_log_f32_e32 v74, v74
	v_cmp_lt_f32_e64 s[0:1], |v83|, s88
	v_cndmask_b32_e64 v75, 0, v171, s[12:13]
	v_sub_f32_e32 v70, 1.0, v70
	v_cndmask_b32_e64 v67, v83, v67, s[0:1]
	v_sub_f32_e32 v83, v67, v75
	v_mul_f32_e32 v67, 0x3f317217, v74
	v_fma_f32 v67, v74, s87, -v67
	v_fmac_f32_e32 v67, 0x3377d1cf, v74
	v_fmac_f32_e32 v67, 0x3f317217, v74
	v_cmp_lt_f32_e64 s[0:1], |v74|, s88
	v_sub_f32_e32 v71, 1.0, v71
	v_sub_f32_e32 v75, 1.0, v73
	v_cndmask_b32_e64 v67, v74, v67, s[0:1]
	v_cndmask_b32_e32 v74, 0, v171, vcc
	v_cmp_gt_f32_e32 vcc, s86, v73
	v_sub_f32_e32 v84, v67, v74
	v_sub_f32_e32 v74, 1.0, v72
	v_cndmask_b32_e64 v67, 0, 32, vcc
	v_ldexp_f32 v67, v73, v67
	v_log_f32_e32 v67, v67
	v_sub_f32_e32 v72, 1.0, v90
	v_sub_f32_e32 v73, 1.0, v91
	v_sub_f32_e32 v76, 1.0, v86
	v_mul_f32_e32 v85, 0x3f317217, v67
	v_fma_f32 v85, v67, s87, -v85
	v_fmac_f32_e32 v85, 0x3377d1cf, v67
	v_fmac_f32_e32 v85, 0x3f317217, v67
	v_cmp_lt_f32_e64 s[0:1], |v67|, s88
	v_sub_f32_e32 v77, 1.0, v87
	v_lshl_add_u64 v[86:87], v[56:57], 2, s[22:23]
	v_cndmask_b32_e64 v67, v67, v85, s[0:1]
	v_cndmask_b32_e32 v85, 0, v171, vcc
	s_mov_b64 s[6:7], s[16:17]
	v_sub_f32_e32 v85, v67, v85
	global_store_dwordx4 v[86:87], v[78:81], off
	global_store_dwordx4 v[86:87], v[82:85], off offset:16

;     __device__ __forceinline__ void operator()(const f32x4 (&acc)[2][2][4][2], const Unit& u, int wr, int wc, int fr, int fq, const Pre& P) const {
;     ...
;                     else if (sec == 1) { dst = KB; const f32x4 l0 = *(const f32x4*)(LBv + c), l1 = *(const f32x4*)(LBv + c + 4); float lf[8];
.LBB0_828:
	v_lshlrev_b32_e32 v60, 2, v154
	v_mov_b32_e32 v56, v246
	v_mov_b32_e32 v57, v247
	v_mov_b32_e32 v58, v248
	v_mov_b32_e32 v59, v249
	v_mov_b32_e32 v66, v250
	v_mov_b32_e32 v67, v251
	v_mov_b32_e32 v68, v252
	v_mov_b32_e32 v69, v253

; __device__ __forceinline__ float fexp(float x) { return __builtin_amdgcn_exp2f(x * 1.4426950408889634f); }
; __device__ __forceinline__ float sigmoidf_(float x) { return __builtin_amdgcn_rcpf(1.0f + fexp(-x)); }
;     __device__ __forceinline__ void operator()(const f32x4 (&acc)[2][2][4][2], const Unit& u, int wr, int wc, int fr, int fq, const Pre& P) const {
;     ...
;                         for (int j = 0; j < 8; ++j) { const float lb = j < 4 ? l0[j] : l1[j - 4]; const float fg = lb + (1.0f - lb) * sigmoidf_(x[j]); y[j] = 1.0f - fg; lf[j] = __logf(fg); }
;                         *(f32x4*)(LF + off) = (f32x4){lf[0], lf[1], lf[2], lf[3]}; *(f32x4*)(LF + off + 4) = (f32x4){lf[4], lf[5], lf[6], lf[7]}; }
	v_mul_f32_e32 v60, 0xbfb8aa3b, v52
	v_mul_f32_e32 v61, 0xbfb8aa3b, v53
	v_exp_f32_e32 v60, v60
	v_exp_f32_e32 v61, v61
	v_mul_f32_e32 v70, 0xbfb8aa3b, v54
	v_mul_f32_e32 v71, 0xbfb8aa3b, v55
	v_exp_f32_e32 v70, v70
	v_exp_f32_e32 v71, v71
	v_mul_f32_e32 v72, 0xbfb8aa3b, v48
	v_mul_f32_e32 v73, 0xbfb8aa3b, v49
	v_exp_f32_e32 v72, v72
	v_exp_f32_e32 v73, v73
	v_add_f32_e32 v60, 1.0, v60
	v_add_f32_e32 v61, 1.0, v61
	v_rcp_f32_e32 v60, v60
	v_rcp_f32_e32 v61, v61
	v_add_f32_e32 v70, 1.0, v70
	v_add_f32_e32 v71, 1.0, v71
	v_rcp_f32_e32 v70, v70
	v_rcp_f32_e32 v71, v71
	v_add_f32_e32 v72, 1.0, v72
	v_add_f32_e32 v73, 1.0, v73
	v_rcp_f32_e32 v72, v72
	v_rcp_f32_e32 v73, v73
	v_or_b32_e32 v62, v64, v154
	v_mov_b32_e32 v63, v65
	v_lshl_add_u64 v[62:63], v[62:63], 2, s[22:23]

; __device__ __forceinline__ float sigmoidf_(float x) { return __builtin_amdgcn_rcpf(1.0f + fexp(-x)); }
;     __device__ __forceinline__ void operator()(const f32x4 (&acc)[2][2][4][2], const Unit& u, int wr, int wc, int fr, int fq, const Pre& P) const {
;     ...
;                     else if (sec == 1) { dst = KB; const f32x4 l0 = *(const f32x4*)(LBv + c), l1 = *(const f32x4*)(LBv + c + 4); float lf[8];
; #pragma unroll
;                         for (int j = 0; j < 8; ++j) { const float lb = j < 4 ? l0[j] : l1[j - 4]; const float fg = lb + (1.0f - lb) * sigmoidf_(x[j]); y[j] = 1.0f - fg; lf[j] = __logf(fg); }
;                         *(f32x4*)(LF + off) = (f32x4){lf[0], lf[1], lf[2], lf[3]}; *(f32x4*)(LF + off + 4) = (f32x4){lf[4], lf[5], lf[6], lf[7]}; }
	v_pk_add_f32 v[74:75], v[56:57], 1.0 op_sel_hi:[1,0] neg_lo:[1,0] neg_hi:[1,0]
	s_nop 0
	v_pk_fma_f32 v[80:81], v[60:61], v[74:75], v[56:57]
	v_pk_add_f32 v[76:77], v[58:59], 1.0 op_sel_hi:[1,0] neg_lo:[1,0] neg_hi:[1,0]
	v_cmp_gt_f32_e32 vcc, s86, v80
	v_pk_fma_f32 v[56:57], v[70:71], v[76:77], v[58:59]
	v_cmp_gt_f32_e64 s[0:1], s86, v81
	v_cndmask_b32_e64 v58, 0, 32, vcc
	v_pk_add_f32 v[78:79], v[66:67], 1.0 op_sel_hi:[1,0] neg_lo:[1,0] neg_hi:[1,0]
	v_cndmask_b32_e64 v59, 0, 32, s[0:1]
	v_cmp_gt_f32_e64 s[6:7], s86, v56
	v_ldexp_f32 v58, v80, v58
	v_pk_fma_f32 v[66:67], v[72:73], v[78:79], v[66:67]
	v_cndmask_b32_e64 v60, 0, 32, s[6:7]
	v_cmp_gt_f32_e64 s[8:9], s86, v57
	v_ldexp_f32 v59, v81, v59
	v_log_f32_e32 v58, v58
	v_cndmask_b32_e64 v61, 0, 32, s[8:9]
	v_cmp_gt_f32_e64 s[10:11], s86, v66
	v_ldexp_f32 v60, v56, v60
	v_log_f32_e32 v59, v59
	v_cndmask_b32_e64 v70, 0, 32, s[10:11]
	v_cmp_gt_f32_e64 s[12:13], s86, v67
	v_ldexp_f32 v61, v57, v61
	v_log_f32_e32 v60, v60
	v_cndmask_b32_e64 v71, 0, 32, s[12:13]
	v_ldexp_f32 v70, v66, v70
	v_log_f32_e32 v61, v61
	v_ldexp_f32 v71, v67, v71
	v_log_f32_e32 v76, v70
	v_mul_f32_e32 v70, 0x3f317217, v58
	v_log_f32_e32 v77, v71
	v_mul_f32_e32 v71, 0x3f317217, v59
	v_fma_f32 v70, v58, s87, -v70
	v_mul_f32_e32 v78, 0x3f317217, v60
	v_fma_f32 v71, v59, s87, -v71
	v_fmac_f32_e32 v70, 0x3377d1cf, v58
	v_cndmask_b32_e32 v72, 0, v171, vcc
	v_mul_f32_e32 v79, 0x3f317217, v61
	v_fma_f32 v78, v60, s87, -v78
	v_fmac_f32_e32 v71, 0x3377d1cf, v59
	v_fmac_f32_e32 v70, 0x3f317217, v58
	v_cmp_lt_f32_e64 vcc, |v58|, s88
	v_mul_f32_e32 v82, 0x3f317217, v76
	v_fma_f32 v79, v61, s87, -v79
	v_fmac_f32_e32 v78, 0x3377d1cf, v60
	v_fmac_f32_e32 v71, 0x3f317217, v59
	v_cndmask_b32_e32 v58, v58, v70, vcc
	v_cmp_lt_f32_e64 vcc, |v59|, s88
	v_fma_f32 v82, v76, s87, -v82
	v_fmac_f32_e32 v79, 0x3377d1cf, v61
	v_fmac_f32_e32 v78, 0x3f317217, v60
	v_cndmask_b32_e32 v59, v59, v71, vcc
	v_cmp_lt_f32_e64 vcc, |v60|, s88
	v_fmac_f32_e32 v82, 0x3377d1cf, v76
	v_fmac_f32_e32 v79, 0x3f317217, v61
	v_cndmask_b32_e32 v60, v60, v78, vcc
	v_cmp_lt_f32_e64 vcc, |v61|, s88
	v_cndmask_b32_e64 v73, 0, v171, s[0:1]
	v_fmac_f32_e32 v82, 0x3f317217, v76
	v_cndmask_b32_e32 v61, v61, v79, vcc
	v_cmp_lt_f32_e64 vcc, |v76|, s88
	v_cndmask_b32_e64 v74, 0, v171, s[6:7]
	v_sub_f32_e32 v70, v58, v72
	v_sub_f32_e32 v71, v59, v73
	v_cndmask_b32_e32 v58, v76, v82, vcc
	v_cndmask_b32_e64 v59, 0, v171, s[10:11]
	v_sub_f32_e32 v72, v60, v74
	v_sub_f32_e32 v74, v58, v59
	v_mul_f32_e32 v59, 0xbfb8aa3b, v50
	v_mul_f32_e32 v60, 0xbfb8aa3b, v51
	v_exp_f32_e32 v59, v59
	v_exp_f32_e32 v60, v60
	v_cndmask_b32_e64 v75, 0, v171, s[8:9]
	v_mul_f32_e32 v58, 0x3f317217, v77
	v_sub_f32_e32 v73, v61, v75
	v_fma_f32 v75, v77, s87, -v58
	v_add_f32_e32 v58, 1.0, v59
	v_add_f32_e32 v59, 1.0, v60
	v_rcp_f32_e32 v58, v58
	v_rcp_f32_e32 v59, v59
	v_pk_add_f32 v[60:61], v[68:69], 1.0 op_sel_hi:[1,0] neg_lo:[1,0] neg_hi:[1,0]
	v_fmac_f32_e32 v75, 0x3377d1cf, v77
	v_fmac_f32_e32 v75, 0x3f317217, v77
	v_pk_fma_f32 v[58:59], v[58:59], v[60:61], v[68:69]
	v_cmp_lt_f32_e64 s[0:1], |v77|, s88
	v_cmp_gt_f32_e32 vcc, s86, v58
	v_cndmask_b32_e64 v68, 0, v171, s[12:13]
	v_cndmask_b32_e64 v61, v77, v75, s[0:1]
	v_cndmask_b32_e64 v60, 0, 32, vcc
	v_ldexp_f32 v60, v58, v60
	v_log_f32_e32 v60, v60
	v_sub_f32_e32 v75, v61, v68
	v_sub_f32_e32 v56, 1.0, v56
	v_sub_f32_e32 v57, 1.0, v57
	v_mul_f32_e32 v61, 0x3f317217, v60
	v_fma_f32 v61, v60, s87, -v61
	v_fmac_f32_e32 v61, 0x3377d1cf, v60
	v_fmac_f32_e32 v61, 0x3f317217, v60
	v_cmp_lt_f32_e64 s[0:1], |v60|, s88
	v_sub_f32_e32 v66, 1.0, v66
	v_sub_f32_e32 v67, 1.0, v67
	v_cndmask_b32_e64 v60, v60, v61, s[0:1]
	v_cndmask_b32_e32 v61, 0, v171, vcc
	v_cmp_gt_f32_e32 vcc, s86, v59
	v_sub_f32_e32 v76, v60, v61
	v_sub_f32_e32 v61, 1.0, v59
	v_cndmask_b32_e64 v68, 0, 32, vcc
	v_ldexp_f32 v59, v59, v68
	v_log_f32_e32 v68, v59
	v_sub_f32_e32 v60, 1.0, v58
	v_sub_f32_e32 v58, 1.0, v80
	v_sub_f32_e32 v59, 1.0, v81
	v_mul_f32_e32 v69, 0x3f317217, v68
	v_fma_f32 v69, v68, s87, -v69
	v_fmac_f32_e32 v69, 0x3377d1cf, v68
	v_fmac_f32_e32 v69, 0x3f317217, v68
	v_cmp_lt_f32_e64 s[0:1], |v68|, s88
	s_mov_b64 s[6:7], s[16:17]
	s_nop 0
	v_cndmask_b32_e64 v68, v68, v69, s[0:1]
	v_cndmask_b32_e32 v69, 0, v171, vcc
	v_sub_f32_e32 v77, v68, v69
	global_store_dwordx4 v[62:63], v[70:73], off
	global_store_dwordx4 v[62:63], v[74:77], off offset:16

;     __device__ __forceinline__ void operator()(const f32x4 (&acc)[2][2][4][2], const Unit& u, int wr, int wc, int fr, int fq, const Pre& P) const {
;     ...
;                     else if (sec == 1) { dst = KB; const f32x4 l0 = *(const f32x4*)(LBv + c), l1 = *(const f32x4*)(LBv + c + 4); float lf[8];
.LBB0_842:
	v_lshlrev_b32_e32 v51, 2, v138
	v_mov_b32_e32 v54, v238
	v_mov_b32_e32 v55, v239
	v_mov_b32_e32 v56, v240
	v_mov_b32_e32 v57, v241
	v_mov_b32_e32 v58, v242
	v_mov_b32_e32 v59, v243
	v_mov_b32_e32 v60, v244
	v_mov_b32_e32 v61, v245

; __device__ __forceinline__ float fexp(float x) { return __builtin_amdgcn_exp2f(x * 1.4426950408889634f); }
; __device__ __forceinline__ float sigmoidf_(float x) { return __builtin_amdgcn_rcpf(1.0f + fexp(-x)); }
;     __device__ __forceinline__ void operator()(const f32x4 (&acc)[2][2][4][2], const Unit& u, int wr, int wc, int fr, int fq, const Pre& P) const {
;     ...
;                         for (int j = 0; j < 8; ++j) { const float lb = j < 4 ? l0[j] : l1[j - 4]; const float fg = lb + (1.0f - lb) * sigmoidf_(x[j]); y[j] = 1.0f - fg; lf[j] = __logf(fg); }
	v_mul_f32_e32 v51, 0xbfb8aa3b, v44
	v_mul_f32_e32 v62, 0xbfb8aa3b, v45
	v_mul_f32_e32 v63, 0xbfb8aa3b, v46
	v_exp_f32_e32 v51, v51
	v_exp_f32_e32 v62, v62
	v_mul_f32_e32 v64, 0xbfb8aa3b, v47
	v_exp_f32_e32 v63, v63
	v_mul_f32_e32 v65, 0xbfb8aa3b, v52
	v_exp_f32_e32 v64, v64
	v_mul_f32_e32 v66, 0xbfb8aa3b, v53
	v_exp_f32_e32 v65, v65
	v_exp_f32_e32 v66, v66
	v_add_f32_e32 v51, 1.0, v51
	v_add_f32_e32 v67, 1.0, v62
	v_add_f32_e32 v68, 1.0, v63
	v_rcp_f32_e32 v62, v51
	v_rcp_f32_e32 v63, v67
	v_add_f32_e32 v69, 1.0, v64
	v_add_f32_e32 v70, 1.0, v65
	v_rcp_f32_e32 v64, v68
	v_rcp_f32_e32 v65, v69
	v_add_f32_e32 v71, 1.0, v66
	v_rcp_f32_e32 v66, v70
	v_rcp_f32_e32 v67, v71

; __device__ __forceinline__ float sigmoidf_(float x) { return __builtin_amdgcn_rcpf(1.0f + fexp(-x)); }
;     __device__ __forceinline__ void operator()(const f32x4 (&acc)[2][2][4][2], const Unit& u, int wr, int wc, int fr, int fq, const Pre& P) const {
;     ...
;                     else if (sec == 1) { dst = KB; const f32x4 l0 = *(const f32x4*)(LBv + c), l1 = *(const f32x4*)(LBv + c + 4); float lf[8];
; #pragma unroll
;                         for (int j = 0; j < 8; ++j) { const float lb = j < 4 ? l0[j] : l1[j - 4]; const float fg = lb + (1.0f - lb) * sigmoidf_(x[j]); y[j] = 1.0f - fg; lf[j] = __logf(fg); }
;                         *(f32x4*)(LF + off) = (f32x4){lf[0], lf[1], lf[2], lf[3]}; *(f32x4*)(LF + off + 4) = (f32x4){lf[4], lf[5], lf[6], lf[7]}; }
	v_pk_add_f32 v[68:69], v[54:55], 1.0 op_sel_hi:[1,0] neg_lo:[1,0] neg_hi:[1,0]
	s_nop 0
	v_pk_fma_f32 v[74:75], v[62:63], v[68:69], v[54:55]
	v_pk_add_f32 v[70:71], v[56:57], 1.0 op_sel_hi:[1,0] neg_lo:[1,0] neg_hi:[1,0]
	v_cmp_gt_f32_e32 vcc, s86, v74
	v_pk_fma_f32 v[54:55], v[64:65], v[70:71], v[56:57]
	v_cmp_gt_f32_e64 s[0:1], s86, v75
	v_cndmask_b32_e64 v51, 0, 32, vcc
	v_pk_add_f32 v[72:73], v[58:59], 1.0 op_sel_hi:[1,0] neg_lo:[1,0] neg_hi:[1,0]
	v_cndmask_b32_e64 v56, 0, 32, s[0:1]
	v_cmp_gt_f32_e64 s[6:7], s86, v54
	v_ldexp_f32 v51, v74, v51
	v_pk_fma_f32 v[70:71], v[66:67], v[72:73], v[58:59]
	v_cndmask_b32_e64 v57, 0, 32, s[6:7]
	v_ldexp_f32 v56, v75, v56
	v_log_f32_e32 v51, v51
	v_cmp_gt_f32_e64 s[12:13], s86, v71
	v_ldexp_f32 v57, v54, v57
	v_log_f32_e32 v56, v56
	v_cndmask_b32_e64 v62, 0, 32, s[12:13]
	v_log_f32_e32 v57, v57
	v_ldexp_f32 v62, v71, v62
	v_log_f32_e32 v67, v62
	v_mul_f32_e32 v62, 0x3f317217, v51
	v_mul_f32_e32 v68, 0x3f317217, v56
	v_fma_f32 v62, v51, s87, -v62
	v_mul_f32_e32 v69, 0x3f317217, v57
	v_fma_f32 v68, v56, s87, -v68
	v_fmac_f32_e32 v62, 0x3377d1cf, v51
	v_cmp_gt_f32_e64 s[8:9], s86, v55
	v_cndmask_b32_e32 v63, 0, v171, vcc
	v_fma_f32 v69, v57, s87, -v69
	v_fmac_f32_e32 v68, 0x3377d1cf, v56
	v_fmac_f32_e32 v62, 0x3f317217, v51
	v_cmp_lt_f32_e64 vcc, |v51|, s88
	v_cndmask_b32_e64 v58, 0, 32, s[8:9]
	v_cmp_gt_f32_e64 s[10:11], s86, v70
	v_fmac_f32_e32 v69, 0x3377d1cf, v57
	v_fmac_f32_e32 v68, 0x3f317217, v56
	v_cndmask_b32_e32 v51, v51, v62, vcc
	v_cmp_lt_f32_e64 vcc, |v56|, s88
	v_cndmask_b32_e64 v59, 0, 32, s[10:11]
	v_ldexp_f32 v58, v55, v58
	v_fmac_f32_e32 v69, 0x3f317217, v57
	v_cndmask_b32_e32 v56, v56, v68, vcc
	v_cmp_lt_f32_e64 vcc, |v57|, s88
	v_cndmask_b32_e64 v64, 0, v171, s[0:1]
	v_cndmask_b32_e64 v65, 0, v171, s[6:7]
	v_ldexp_f32 v59, v70, v59
	v_log_f32_e32 v58, v58
	v_cndmask_b32_e32 v57, v57, v69, vcc
	v_log_f32_e32 v59, v59
	v_sub_f32_e32 v62, v51, v63
	v_sub_f32_e32 v63, v56, v64
	v_sub_f32_e32 v64, v57, v65
	v_mul_f32_e32 v56, 0xbfb8aa3b, v42
	v_mul_f32_e32 v57, 0xbfb8aa3b, v43
	v_exp_f32_e32 v56, v56
	v_exp_f32_e32 v57, v57
	v_mul_f32_e32 v72, 0x3f317217, v58
	v_mul_f32_e32 v73, 0x3f317217, v59
	v_fma_f32 v72, v58, s87, -v72
	v_fma_f32 v73, v59, s87, -v73
	v_fmac_f32_e32 v72, 0x3377d1cf, v58
	v_add_f32_e32 v56, 1.0, v56
	v_add_f32_e32 v57, 1.0, v57
	v_fmac_f32_e32 v73, 0x3377d1cf, v59
	v_fmac_f32_e32 v72, 0x3f317217, v58
	v_cmp_lt_f32_e64 vcc, |v58|, s88
	v_rcp_f32_e32 v56, v56
	v_rcp_f32_e32 v57, v57
	v_fmac_f32_e32 v73, 0x3f317217, v59
	v_cndmask_b32_e32 v58, v58, v72, vcc
	v_cmp_lt_f32_e64 vcc, |v59|, s88
	v_cndmask_b32_e64 v66, 0, v171, s[8:9]
	v_cndmask_b32_e64 v51, 0, v171, s[10:11]
	v_cndmask_b32_e32 v59, v59, v73, vcc
	v_sub_f32_e32 v65, v58, v66
	v_sub_f32_e32 v66, v59, v51
	v_pk_add_f32 v[58:59], v[60:61], 1.0 op_sel_hi:[1,0] neg_lo:[1,0] neg_hi:[1,0]
	v_mul_f32_e32 v51, 0x3f317217, v67
	v_pk_fma_f32 v[56:57], v[56:57], v[58:59], v[60:61]
	v_fma_f32 v51, v67, s87, -v51
	v_cmp_gt_f32_e32 vcc, s86, v56
	v_fmac_f32_e32 v51, 0x3377d1cf, v67
	v_fmac_f32_e32 v51, 0x3f317217, v67
	v_cndmask_b32_e64 v58, 0, 32, vcc
	v_ldexp_f32 v58, v56, v58
	v_log_f32_e32 v58, v58
	v_cmp_lt_f32_e64 s[0:1], |v67|, s88
	v_cndmask_b32_e64 v59, 0, v171, s[12:13]
	v_sub_f32_e32 v54, 1.0, v54
	v_cndmask_b32_e64 v51, v67, v51, s[0:1]
	v_sub_f32_e32 v67, v51, v59
	v_mul_f32_e32 v51, 0x3f317217, v58
	v_fma_f32 v51, v58, s87, -v51
	v_fmac_f32_e32 v51, 0x3377d1cf, v58
	v_fmac_f32_e32 v51, 0x3f317217, v58
	v_cmp_lt_f32_e64 s[0:1], |v58|, s88
	v_sub_f32_e32 v55, 1.0, v55
	v_sub_f32_e32 v59, 1.0, v57
	v_cndmask_b32_e64 v51, v58, v51, s[0:1]
	v_cndmask_b32_e32 v58, 0, v171, vcc
	v_cmp_gt_f32_e32 vcc, s86, v57
	v_sub_f32_e32 v68, v51, v58
	v_sub_f32_e32 v58, 1.0, v56
	v_cndmask_b32_e64 v51, 0, 32, vcc
	v_ldexp_f32 v51, v57, v51
	v_log_f32_e32 v51, v51
	v_sub_f32_e32 v56, 1.0, v74
	v_sub_f32_e32 v57, 1.0, v75
	v_sub_f32_e32 v60, 1.0, v70
	v_mul_f32_e32 v69, 0x3f317217, v51
	v_fma_f32 v69, v51, s87, -v69
	v_fmac_f32_e32 v69, 0x3377d1cf, v51
	v_fmac_f32_e32 v69, 0x3f317217, v51
	v_cmp_lt_f32_e64 s[0:1], |v51|, s88
	v_sub_f32_e32 v61, 1.0, v71
	v_lshl_add_u64 v[70:71], v[40:41], 2, s[22:23]
	v_cndmask_b32_e64 v51, v51, v69, s[0:1]
	v_cndmask_b32_e32 v69, 0, v171, vcc
	s_mov_b64 s[6:7], s[16:17]
	v_sub_f32_e32 v69, v51, v69
	global_store_dwordx4 v[70:71], v[62:65], off
	global_store_dwordx4 v[70:71], v[66:69], off offset:16

;     __device__ __forceinline__ void operator()(const f32x4 (&acc)[2][2][4][2], const Unit& u, int wr, int wc, int fr, int fq, const Pre& P) const {
;     ...
;                     else if (sec == 1) { dst = KB; const f32x4 l0 = *(const f32x4*)(LBv + c), l1 = *(const f32x4*)(LBv + c + 4); float lf[8];
.LBB0_856:
	v_lshlrev_b32_e32 v44, 2, v154
	v_mov_b32_e32 v40, v246
	v_mov_b32_e32 v41, v247
	v_mov_b32_e32 v42, v248
	v_mov_b32_e32 v43, v249
	v_mov_b32_e32 v50, v250
	v_mov_b32_e32 v51, v251
	v_mov_b32_e32 v52, v252
	v_mov_b32_e32 v53, v253

; __device__ __forceinline__ float fexp(float x) { return __builtin_amdgcn_exp2f(x * 1.4426950408889634f); }
; __device__ __forceinline__ float sigmoidf_(float x) { return __builtin_amdgcn_rcpf(1.0f + fexp(-x)); }
;     __device__ __forceinline__ void operator()(const f32x4 (&acc)[2][2][4][2], const Unit& u, int wr, int wc, int fr, int fq, const Pre& P) const {
;     ...
;                         for (int j = 0; j < 8; ++j) { const float lb = j < 4 ? l0[j] : l1[j - 4]; const float fg = lb + (1.0f - lb) * sigmoidf_(x[j]); y[j] = 1.0f - fg; lf[j] = __logf(fg); }
;                         *(f32x4*)(LF + off) = (f32x4){lf[0], lf[1], lf[2], lf[3]}; *(f32x4*)(LF + off + 4) = (f32x4){lf[4], lf[5], lf[6], lf[7]}; }
	v_mul_f32_e32 v44, 0xbfb8aa3b, v36
	v_mul_f32_e32 v45, 0xbfb8aa3b, v37
	v_exp_f32_e32 v44, v44
	v_exp_f32_e32 v45, v45
	v_mul_f32_e32 v54, 0xbfb8aa3b, v38
	v_mul_f32_e32 v55, 0xbfb8aa3b, v39
	v_exp_f32_e32 v54, v54
	v_exp_f32_e32 v55, v55
	v_mul_f32_e32 v56, 0xbfb8aa3b, v32
	v_mul_f32_e32 v57, 0xbfb8aa3b, v33
	v_exp_f32_e32 v56, v56
	v_exp_f32_e32 v57, v57
	v_add_f32_e32 v44, 1.0, v44
	v_add_f32_e32 v45, 1.0, v45
	v_rcp_f32_e32 v44, v44
	v_rcp_f32_e32 v45, v45
	v_add_f32_e32 v54, 1.0, v54
	v_add_f32_e32 v55, 1.0, v55
	v_rcp_f32_e32 v54, v54
	v_rcp_f32_e32 v55, v55
	v_add_f32_e32 v56, 1.0, v56
	v_add_f32_e32 v57, 1.0, v57
	v_rcp_f32_e32 v56, v56
	v_rcp_f32_e32 v57, v57
	v_or_b32_e32 v46, v48, v154
	v_mov_b32_e32 v47, v49
	v_lshl_add_u64 v[46:47], v[46:47], 2, s[22:23]

; __device__ __forceinline__ float sigmoidf_(float x) { return __builtin_amdgcn_rcpf(1.0f + fexp(-x)); }
;     __device__ __forceinline__ void operator()(const f32x4 (&acc)[2][2][4][2], const Unit& u, int wr, int wc, int fr, int fq, const Pre& P) const {
;     ...
;                     else if (sec == 1) { dst = KB; const f32x4 l0 = *(const f32x4*)(LBv + c), l1 = *(const f32x4*)(LBv + c + 4); float lf[8];
; #pragma unroll
;                         for (int j = 0; j < 8; ++j) { const float lb = j < 4 ? l0[j] : l1[j - 4]; const float fg = lb + (1.0f - lb) * sigmoidf_(x[j]); y[j] = 1.0f - fg; lf[j] = __logf(fg); }
;                         *(f32x4*)(LF + off) = (f32x4){lf[0], lf[1], lf[2], lf[3]}; *(f32x4*)(LF + off + 4) = (f32x4){lf[4], lf[5], lf[6], lf[7]}; }
	v_pk_add_f32 v[58:59], v[40:41], 1.0 op_sel_hi:[1,0] neg_lo:[1,0] neg_hi:[1,0]
	s_nop 0
	v_pk_fma_f32 v[64:65], v[44:45], v[58:59], v[40:41]
	v_pk_add_f32 v[60:61], v[42:43], 1.0 op_sel_hi:[1,0] neg_lo:[1,0] neg_hi:[1,0]
	v_cmp_gt_f32_e32 vcc, s86, v64
	v_pk_fma_f32 v[40:41], v[54:55], v[60:61], v[42:43]
	v_cmp_gt_f32_e64 s[0:1], s86, v65
	v_cndmask_b32_e64 v42, 0, 32, vcc
	v_pk_add_f32 v[62:63], v[50:51], 1.0 op_sel_hi:[1,0] neg_lo:[1,0] neg_hi:[1,0]
	v_cndmask_b32_e64 v43, 0, 32, s[0:1]
	v_cmp_gt_f32_e64 s[6:7], s86, v40
	v_ldexp_f32 v42, v64, v42
	v_pk_fma_f32 v[50:51], v[56:57], v[62:63], v[50:51]
	v_cndmask_b32_e64 v44, 0, 32, s[6:7]
	v_cmp_gt_f32_e64 s[8:9], s86, v41
	v_ldexp_f32 v43, v65, v43
	v_log_f32_e32 v42, v42
	v_cndmask_b32_e64 v45, 0, 32, s[8:9]
	v_cmp_gt_f32_e64 s[10:11], s86, v50
	v_ldexp_f32 v44, v40, v44
	v_log_f32_e32 v43, v43
	v_cndmask_b32_e64 v54, 0, 32, s[10:11]
	v_cmp_gt_f32_e64 s[12:13], s86, v51
	v_ldexp_f32 v45, v41, v45
	v_log_f32_e32 v44, v44
	v_cndmask_b32_e64 v55, 0, 32, s[12:13]
	v_ldexp_f32 v54, v50, v54
	v_log_f32_e32 v45, v45
	v_ldexp_f32 v55, v51, v55
	v_log_f32_e32 v60, v54
	v_mul_f32_e32 v54, 0x3f317217, v42
	v_log_f32_e32 v61, v55
	v_mul_f32_e32 v55, 0x3f317217, v43
	v_fma_f32 v54, v42, s87, -v54
	v_mul_f32_e32 v62, 0x3f317217, v44
	v_fma_f32 v55, v43, s87, -v55
	v_fmac_f32_e32 v54, 0x3377d1cf, v42
	v_cndmask_b32_e32 v56, 0, v171, vcc
	v_mul_f32_e32 v63, 0x3f317217, v45
	v_fma_f32 v62, v44, s87, -v62
	v_fmac_f32_e32 v55, 0x3377d1cf, v43
	v_fmac_f32_e32 v54, 0x3f317217, v42
	v_cmp_lt_f32_e64 vcc, |v42|, s88
	v_mul_f32_e32 v66, 0x3f317217, v60
	v_fma_f32 v63, v45, s87, -v63
	v_fmac_f32_e32 v62, 0x3377d1cf, v44
	v_fmac_f32_e32 v55, 0x3f317217, v43
	v_cndmask_b32_e32 v42, v42, v54, vcc
	v_cmp_lt_f32_e64 vcc, |v43|, s88
	v_fma_f32 v66, v60, s87, -v66
	v_fmac_f32_e32 v63, 0x3377d1cf, v45
	v_fmac_f32_e32 v62, 0x3f317217, v44
	v_cndmask_b32_e32 v43, v43, v55, vcc
	v_cmp_lt_f32_e64 vcc, |v44|, s88
	v_fmac_f32_e32 v66, 0x3377d1cf, v60
	v_fmac_f32_e32 v63, 0x3f317217, v45
	v_cndmask_b32_e32 v44, v44, v62, vcc
	v_cmp_lt_f32_e64 vcc, |v45|, s88
	v_cndmask_b32_e64 v57, 0, v171, s[0:1]
	v_fmac_f32_e32 v66, 0x3f317217, v60
	v_cndmask_b32_e32 v45, v45, v63, vcc
	v_cmp_lt_f32_e64 vcc, |v60|, s88
	v_cndmask_b32_e64 v58, 0, v171, s[6:7]
	v_sub_f32_e32 v54, v42, v56
	v_sub_f32_e32 v55, v43, v57
	v_cndmask_b32_e32 v42, v60, v66, vcc
	v_cndmask_b32_e64 v43, 0, v171, s[10:11]
	v_sub_f32_e32 v56, v44, v58
	v_sub_f32_e32 v58, v42, v43
	v_mul_f32_e32 v43, 0xbfb8aa3b, v34
	v_mul_f32_e32 v44, 0xbfb8aa3b, v35
	v_exp_f32_e32 v43, v43
	v_exp_f32_e32 v44, v44
	v_cndmask_b32_e64 v59, 0, v171, s[8:9]
	v_mul_f32_e32 v42, 0x3f317217, v61
	v_sub_f32_e32 v57, v45, v59
	v_fma_f32 v59, v61, s87, -v42
	v_add_f32_e32 v42, 1.0, v43
	v_add_f32_e32 v43, 1.0, v44
	v_rcp_f32_e32 v42, v42
	v_rcp_f32_e32 v43, v43
	v_pk_add_f32 v[44:45], v[52:53], 1.0 op_sel_hi:[1,0] neg_lo:[1,0] neg_hi:[1,0]
	v_fmac_f32_e32 v59, 0x3377d1cf, v61
	v_fmac_f32_e32 v59, 0x3f317217, v61
	v_pk_fma_f32 v[42:43], v[42:43], v[44:45], v[52:53]
	v_cmp_lt_f32_e64 s[0:1], |v61|, s88
	v_cmp_gt_f32_e32 vcc, s86, v42
	v_cndmask_b32_e64 v52, 0, v171, s[12:13]
	v_cndmask_b32_e64 v45, v61, v59, s[0:1]
	v_cndmask_b32_e64 v44, 0, 32, vcc
	v_ldexp_f32 v44, v42, v44
	v_log_f32_e32 v44, v44
	v_sub_f32_e32 v59, v45, v52
	v_sub_f32_e32 v40, 1.0, v40
	v_sub_f32_e32 v41, 1.0, v41
	v_mul_f32_e32 v45, 0x3f317217, v44
	v_fma_f32 v45, v44, s87, -v45
	v_fmac_f32_e32 v45, 0x3377d1cf, v44
	v_fmac_f32_e32 v45, 0x3f317217, v44
	v_cmp_lt_f32_e64 s[0:1], |v44|, s88
	v_sub_f32_e32 v50, 1.0, v50
	v_sub_f32_e32 v51, 1.0, v51
	v_cndmask_b32_e64 v44, v44, v45, s[0:1]
	v_cndmask_b32_e32 v45, 0, v171, vcc
	v_cmp_gt_f32_e32 vcc, s86, v43
	v_sub_f32_e32 v60, v44, v45
	v_sub_f32_e32 v45, 1.0, v43
	v_cndmask_b32_e64 v52, 0, 32, vcc
	v_ldexp_f32 v43, v43, v52
	v_log_f32_e32 v52, v43
	v_sub_f32_e32 v44, 1.0, v42
	v_sub_f32_e32 v42, 1.0, v64
	v_sub_f32_e32 v43, 1.0, v65
	v_mul_f32_e32 v53, 0x3f317217, v52
	v_fma_f32 v53, v52, s87, -v53
	v_fmac_f32_e32 v53, 0x3377d1cf, v52
	v_fmac_f32_e32 v53, 0x3f317217, v52
	v_cmp_lt_f32_e64 s[0:1], |v52|, s88
	s_mov_b64 s[6:7], s[16:17]
	s_nop 0
	v_cndmask_b32_e64 v52, v52, v53, s[0:1]
	v_cndmask_b32_e32 v53, 0, v171, vcc
	v_sub_f32_e32 v61, v52, v53
	global_store_dwordx4 v[46:47], v[54:57], off
	global_store_dwordx4 v[46:47], v[58:61], off offset:16

;     __device__ __forceinline__ void operator()(const f32x4 (&acc)[2][2][4][2], const Unit& u, int wr, int wc, int fr, int fq, const Pre& P) const {
;     ...
;                     else if (sec == 1) { dst = KB; const f32x4 l0 = *(const f32x4*)(LBv + c), l1 = *(const f32x4*)(LBv + c + 4); float lf[8];
.LBB0_870:
	v_lshlrev_b32_e32 v35, 2, v138
	v_mov_b32_e32 v38, v238
	v_mov_b32_e32 v39, v239
	v_mov_b32_e32 v40, v240
	v_mov_b32_e32 v41, v241
	v_mov_b32_e32 v42, v242
	v_mov_b32_e32 v43, v243
	v_mov_b32_e32 v44, v244
	v_mov_b32_e32 v45, v245

; __device__ __forceinline__ float fexp(float x) { return __builtin_amdgcn_exp2f(x * 1.4426950408889634f); }
; __device__ __forceinline__ float sigmoidf_(float x) { return __builtin_amdgcn_rcpf(1.0f + fexp(-x)); }
;     __device__ __forceinline__ void operator()(const f32x4 (&acc)[2][2][4][2], const Unit& u, int wr, int wc, int fr, int fq, const Pre& P) const {
;     ...
;                         for (int j = 0; j < 8; ++j) { const float lb = j < 4 ? l0[j] : l1[j - 4]; const float fg = lb + (1.0f - lb) * sigmoidf_(x[j]); y[j] = 1.0f - fg; lf[j] = __logf(fg); }
	v_mul_f32_e32 v35, 0xbfb8aa3b, v28
	v_mul_f32_e32 v46, 0xbfb8aa3b, v29
	v_mul_f32_e32 v47, 0xbfb8aa3b, v30
	v_exp_f32_e32 v35, v35
	v_exp_f32_e32 v46, v46
	v_mul_f32_e32 v48, 0xbfb8aa3b, v31
	v_exp_f32_e32 v47, v47
	v_mul_f32_e32 v49, 0xbfb8aa3b, v36
	v_exp_f32_e32 v48, v48
	v_mul_f32_e32 v50, 0xbfb8aa3b, v37
	v_exp_f32_e32 v49, v49
	v_exp_f32_e32 v50, v50
	v_add_f32_e32 v35, 1.0, v35
	v_add_f32_e32 v51, 1.0, v46
	v_add_f32_e32 v52, 1.0, v47
	v_rcp_f32_e32 v46, v35
	v_rcp_f32_e32 v47, v51
	v_add_f32_e32 v53, 1.0, v48
	v_add_f32_e32 v54, 1.0, v49
	v_rcp_f32_e32 v48, v52
	v_rcp_f32_e32 v49, v53
	v_add_f32_e32 v55, 1.0, v50
	v_rcp_f32_e32 v50, v54
	v_rcp_f32_e32 v51, v55

; __device__ __forceinline__ float sigmoidf_(float x) { return __builtin_amdgcn_rcpf(1.0f + fexp(-x)); }
;     __device__ __forceinline__ void operator()(const f32x4 (&acc)[2][2][4][2], const Unit& u, int wr, int wc, int fr, int fq, const Pre& P) const {
;     ...
;                     else if (sec == 1) { dst = KB; const f32x4 l0 = *(const f32x4*)(LBv + c), l1 = *(const f32x4*)(LBv + c + 4); float lf[8];
; #pragma unroll
;                         for (int j = 0; j < 8; ++j) { const float lb = j < 4 ? l0[j] : l1[j - 4]; const float fg = lb + (1.0f - lb) * sigmoidf_(x[j]); y[j] = 1.0f - fg; lf[j] = __logf(fg); }
;                         *(f32x4*)(LF + off) = (f32x4){lf[0], lf[1], lf[2], lf[3]}; *(f32x4*)(LF + off + 4) = (f32x4){lf[4], lf[5], lf[6], lf[7]}; }
	v_pk_add_f32 v[52:53], v[38:39], 1.0 op_sel_hi:[1,0] neg_lo:[1,0] neg_hi:[1,0]
	s_nop 0
	v_pk_fma_f32 v[58:59], v[46:47], v[52:53], v[38:39]
	v_pk_add_f32 v[54:55], v[40:41], 1.0 op_sel_hi:[1,0] neg_lo:[1,0] neg_hi:[1,0]
	v_cmp_gt_f32_e32 vcc, s86, v58
	v_pk_fma_f32 v[38:39], v[48:49], v[54:55], v[40:41]
	v_cmp_gt_f32_e64 s[0:1], s86, v59
	v_cndmask_b32_e64 v35, 0, 32, vcc
	v_pk_add_f32 v[56:57], v[42:43], 1.0 op_sel_hi:[1,0] neg_lo:[1,0] neg_hi:[1,0]
	v_cndmask_b32_e64 v40, 0, 32, s[0:1]
	v_cmp_gt_f32_e64 s[6:7], s86, v38
	v_ldexp_f32 v35, v58, v35
	v_pk_fma_f32 v[54:55], v[50:51], v[56:57], v[42:43]
	v_cndmask_b32_e64 v41, 0, 32, s[6:7]
	v_ldexp_f32 v40, v59, v40
	v_log_f32_e32 v35, v35
	v_cmp_gt_f32_e64 s[12:13], s86, v55
	v_ldexp_f32 v41, v38, v41
	v_log_f32_e32 v40, v40
	v_cndmask_b32_e64 v46, 0, 32, s[12:13]
	v_log_f32_e32 v41, v41
	v_ldexp_f32 v46, v55, v46
	v_log_f32_e32 v51, v46
	v_mul_f32_e32 v46, 0x3f317217, v35
	v_mul_f32_e32 v52, 0x3f317217, v40
	v_fma_f32 v46, v35, s87, -v46
	v_mul_f32_e32 v53, 0x3f317217, v41
	v_fma_f32 v52, v40, s87, -v52
	v_fmac_f32_e32 v46, 0x3377d1cf, v35
	v_cmp_gt_f32_e64 s[8:9], s86, v39
	v_cndmask_b32_e32 v47, 0, v171, vcc
	v_fma_f32 v53, v41, s87, -v53
	v_fmac_f32_e32 v52, 0x3377d1cf, v40
	v_fmac_f32_e32 v46, 0x3f317217, v35
	v_cmp_lt_f32_e64 vcc, |v35|, s88
	v_cndmask_b32_e64 v42, 0, 32, s[8:9]
	v_cmp_gt_f32_e64 s[10:11], s86, v54
	v_fmac_f32_e32 v53, 0x3377d1cf, v41
	v_fmac_f32_e32 v52, 0x3f317217, v40
	v_cndmask_b32_e32 v35, v35, v46, vcc
	v_cmp_lt_f32_e64 vcc, |v40|, s88
	v_cndmask_b32_e64 v43, 0, 32, s[10:11]
	v_ldexp_f32 v42, v39, v42
	v_fmac_f32_e32 v53, 0x3f317217, v41
	v_cndmask_b32_e32 v40, v40, v52, vcc
	v_cmp_lt_f32_e64 vcc, |v41|, s88
	v_cndmask_b32_e64 v48, 0, v171, s[0:1]
	v_cndmask_b32_e64 v49, 0, v171, s[6:7]
	v_ldexp_f32 v43, v54, v43
	v_log_f32_e32 v42, v42
	v_cndmask_b32_e32 v41, v41, v53, vcc
	v_log_f32_e32 v43, v43
	v_sub_f32_e32 v46, v35, v47
	v_sub_f32_e32 v47, v40, v48
	v_sub_f32_e32 v48, v41, v49
	v_mul_f32_e32 v40, 0xbfb8aa3b, v26
	v_mul_f32_e32 v41, 0xbfb8aa3b, v27
	v_exp_f32_e32 v40, v40
	v_exp_f32_e32 v41, v41
	v_mul_f32_e32 v56, 0x3f317217, v42
	v_mul_f32_e32 v57, 0x3f317217, v43
	v_fma_f32 v56, v42, s87, -v56
	v_fma_f32 v57, v43, s87, -v57
	v_fmac_f32_e32 v56, 0x3377d1cf, v42
	v_add_f32_e32 v40, 1.0, v40
	v_add_f32_e32 v41, 1.0, v41
	v_fmac_f32_e32 v57, 0x3377d1cf, v43
	v_fmac_f32_e32 v56, 0x3f317217, v42
	v_cmp_lt_f32_e64 vcc, |v42|, s88
	v_rcp_f32_e32 v40, v40
	v_rcp_f32_e32 v41, v41
	v_fmac_f32_e32 v57, 0x3f317217, v43
	v_cndmask_b32_e32 v42, v42, v56, vcc
	v_cmp_lt_f32_e64 vcc, |v43|, s88
	v_cndmask_b32_e64 v50, 0, v171, s[8:9]
	v_cndmask_b32_e64 v35, 0, v171, s[10:11]
	v_cndmask_b32_e32 v43, v43, v57, vcc
	v_sub_f32_e32 v49, v42, v50
	v_sub_f32_e32 v50, v43, v35
	v_pk_add_f32 v[42:43], v[44:45], 1.0 op_sel_hi:[1,0] neg_lo:[1,0] neg_hi:[1,0]
	v_mul_f32_e32 v35, 0x3f317217, v51
	v_pk_fma_f32 v[40:41], v[40:41], v[42:43], v[44:45]
	v_fma_f32 v35, v51, s87, -v35
	v_cmp_gt_f32_e32 vcc, s86, v40
	v_fmac_f32_e32 v35, 0x3377d1cf, v51
	v_fmac_f32_e32 v35, 0x3f317217, v51
	v_cndmask_b32_e64 v42, 0, 32, vcc
	v_ldexp_f32 v42, v40, v42
	v_log_f32_e32 v42, v42
	v_cmp_lt_f32_e64 s[0:1], |v51|, s88
	v_cndmask_b32_e64 v43, 0, v171, s[12:13]
	v_sub_f32_e32 v38, 1.0, v38
	v_cndmask_b32_e64 v35, v51, v35, s[0:1]
	v_sub_f32_e32 v51, v35, v43
	v_mul_f32_e32 v35, 0x3f317217, v42
	v_fma_f32 v35, v42, s87, -v35
	v_fmac_f32_e32 v35, 0x3377d1cf, v42
	v_fmac_f32_e32 v35, 0x3f317217, v42
	v_cmp_lt_f32_e64 s[0:1], |v42|, s88
	v_sub_f32_e32 v39, 1.0, v39
	v_sub_f32_e32 v43, 1.0, v41
	v_cndmask_b32_e64 v35, v42, v35, s[0:1]
	v_cndmask_b32_e32 v42, 0, v171, vcc
	v_cmp_gt_f32_e32 vcc, s86, v41
	v_sub_f32_e32 v52, v35, v42
	v_sub_f32_e32 v42, 1.0, v40
	v_cndmask_b32_e64 v35, 0, 32, vcc
	v_ldexp_f32 v35, v41, v35
	v_log_f32_e32 v35, v35
	v_sub_f32_e32 v40, 1.0, v58
	v_sub_f32_e32 v41, 1.0, v59
	v_sub_f32_e32 v44, 1.0, v54
	v_mul_f32_e32 v53, 0x3f317217, v35
	v_fma_f32 v53, v35, s87, -v53
	v_fmac_f32_e32 v53, 0x3377d1cf, v35
	v_fmac_f32_e32 v53, 0x3f317217, v35
	v_cmp_lt_f32_e64 s[0:1], |v35|, s88
	v_sub_f32_e32 v45, 1.0, v55
	v_lshl_add_u64 v[54:55], v[24:25], 2, s[22:23]
	v_cndmask_b32_e64 v35, v35, v53, s[0:1]
	v_cndmask_b32_e32 v53, 0, v171, vcc
	s_mov_b64 s[6:7], s[16:17]
	v_sub_f32_e32 v53, v35, v53
	global_store_dwordx4 v[54:55], v[46:49], off
	global_store_dwordx4 v[54:55], v[50:53], off offset:16

;     __device__ __forceinline__ void operator()(const f32x4 (&acc)[2][2][4][2], const Unit& u, int wr, int wc, int fr, int fq, const Pre& P) const {
;     ...
;                     else if (sec == 1) { dst = KB; const f32x4 l0 = *(const f32x4*)(LBv + c), l1 = *(const f32x4*)(LBv + c + 4); float lf[8];
.LBB0_884:
	v_lshlrev_b32_e32 v28, 2, v154
	v_mov_b32_e32 v24, v246
	v_mov_b32_e32 v25, v247
	v_mov_b32_e32 v26, v248
	v_mov_b32_e32 v27, v249
	v_mov_b32_e32 v34, v250
	v_mov_b32_e32 v35, v251
	v_mov_b32_e32 v36, v252
	v_mov_b32_e32 v37, v253

; __device__ __forceinline__ float fexp(float x) { return __builtin_amdgcn_exp2f(x * 1.4426950408889634f); }
; __device__ __forceinline__ float sigmoidf_(float x) { return __builtin_amdgcn_rcpf(1.0f + fexp(-x)); }
;     __device__ __forceinline__ void operator()(const f32x4 (&acc)[2][2][4][2], const Unit& u, int wr, int wc, int fr, int fq, const Pre& P) const {
;     ...
;                         for (int j = 0; j < 8; ++j) { const float lb = j < 4 ? l0[j] : l1[j - 4]; const float fg = lb + (1.0f - lb) * sigmoidf_(x[j]); y[j] = 1.0f - fg; lf[j] = __logf(fg); }
;                         *(f32x4*)(LF + off) = (f32x4){lf[0], lf[1], lf[2], lf[3]}; *(f32x4*)(LF + off + 4) = (f32x4){lf[4], lf[5], lf[6], lf[7]}; }
	v_mul_f32_e32 v28, 0xbfb8aa3b, v20
	v_mul_f32_e32 v29, 0xbfb8aa3b, v21
	v_exp_f32_e32 v28, v28
	v_exp_f32_e32 v29, v29
	v_mul_f32_e32 v38, 0xbfb8aa3b, v22
	v_mul_f32_e32 v39, 0xbfb8aa3b, v23
	v_exp_f32_e32 v38, v38
	v_exp_f32_e32 v39, v39
	v_mul_f32_e32 v40, 0xbfb8aa3b, v16
	v_mul_f32_e32 v41, 0xbfb8aa3b, v17
	v_exp_f32_e32 v40, v40
	v_exp_f32_e32 v41, v41
	v_add_f32_e32 v28, 1.0, v28
	v_add_f32_e32 v29, 1.0, v29
	v_rcp_f32_e32 v28, v28
	v_rcp_f32_e32 v29, v29
	v_add_f32_e32 v38, 1.0, v38
	v_add_f32_e32 v39, 1.0, v39
	v_rcp_f32_e32 v38, v38
	v_rcp_f32_e32 v39, v39
	v_add_f32_e32 v40, 1.0, v40
	v_add_f32_e32 v41, 1.0, v41
	v_rcp_f32_e32 v40, v40
	v_rcp_f32_e32 v41, v41
	v_or_b32_e32 v30, v32, v154
	v_mov_b32_e32 v31, v33
	v_lshl_add_u64 v[30:31], v[30:31], 2, s[22:23]

; __device__ __forceinline__ float sigmoidf_(float x) { return __builtin_amdgcn_rcpf(1.0f + fexp(-x)); }
;     __device__ __forceinline__ void operator()(const f32x4 (&acc)[2][2][4][2], const Unit& u, int wr, int wc, int fr, int fq, const Pre& P) const {
;     ...
;                     else if (sec == 1) { dst = KB; const f32x4 l0 = *(const f32x4*)(LBv + c), l1 = *(const f32x4*)(LBv + c + 4); float lf[8];
; #pragma unroll
;                         for (int j = 0; j < 8; ++j) { const float lb = j < 4 ? l0[j] : l1[j - 4]; const float fg = lb + (1.0f - lb) * sigmoidf_(x[j]); y[j] = 1.0f - fg; lf[j] = __logf(fg); }
;                         *(f32x4*)(LF + off) = (f32x4){lf[0], lf[1], lf[2], lf[3]}; *(f32x4*)(LF + off + 4) = (f32x4){lf[4], lf[5], lf[6], lf[7]}; }
	v_pk_add_f32 v[42:43], v[24:25], 1.0 op_sel_hi:[1,0] neg_lo:[1,0] neg_hi:[1,0]
	s_nop 0
	v_pk_fma_f32 v[48:49], v[28:29], v[42:43], v[24:25]
	v_pk_add_f32 v[44:45], v[26:27], 1.0 op_sel_hi:[1,0] neg_lo:[1,0] neg_hi:[1,0]
	v_cmp_gt_f32_e32 vcc, s86, v48
	v_pk_fma_f32 v[24:25], v[38:39], v[44:45], v[26:27]
	v_cmp_gt_f32_e64 s[0:1], s86, v49
	v_cndmask_b32_e64 v26, 0, 32, vcc
	v_pk_add_f32 v[46:47], v[34:35], 1.0 op_sel_hi:[1,0] neg_lo:[1,0] neg_hi:[1,0]
	v_cndmask_b32_e64 v27, 0, 32, s[0:1]
	v_cmp_gt_f32_e64 s[6:7], s86, v24
	v_ldexp_f32 v26, v48, v26
	v_pk_fma_f32 v[34:35], v[40:41], v[46:47], v[34:35]
	v_cndmask_b32_e64 v28, 0, 32, s[6:7]
	v_cmp_gt_f32_e64 s[8:9], s86, v25
	v_ldexp_f32 v27, v49, v27
	v_log_f32_e32 v26, v26
	v_cndmask_b32_e64 v29, 0, 32, s[8:9]
	v_cmp_gt_f32_e64 s[10:11], s86, v34
	v_ldexp_f32 v28, v24, v28
	v_log_f32_e32 v27, v27
	v_cndmask_b32_e64 v38, 0, 32, s[10:11]
	v_cmp_gt_f32_e64 s[12:13], s86, v35
	v_ldexp_f32 v29, v25, v29
	v_log_f32_e32 v28, v28
	v_cndmask_b32_e64 v39, 0, 32, s[12:13]
	v_ldexp_f32 v38, v34, v38
	v_log_f32_e32 v29, v29
	v_ldexp_f32 v39, v35, v39
	v_log_f32_e32 v44, v38
	v_mul_f32_e32 v38, 0x3f317217, v26
	v_log_f32_e32 v45, v39
	v_mul_f32_e32 v39, 0x3f317217, v27
	v_fma_f32 v38, v26, s87, -v38
	v_mul_f32_e32 v46, 0x3f317217, v28
	v_fma_f32 v39, v27, s87, -v39
	v_fmac_f32_e32 v38, 0x3377d1cf, v26
	v_cndmask_b32_e32 v40, 0, v171, vcc
	v_mul_f32_e32 v47, 0x3f317217, v29
	v_fma_f32 v46, v28, s87, -v46
	v_fmac_f32_e32 v39, 0x3377d1cf, v27
	v_fmac_f32_e32 v38, 0x3f317217, v26
	v_cmp_lt_f32_e64 vcc, |v26|, s88
	v_mul_f32_e32 v50, 0x3f317217, v44
	v_fma_f32 v47, v29, s87, -v47
	v_fmac_f32_e32 v46, 0x3377d1cf, v28
	v_fmac_f32_e32 v39, 0x3f317217, v27
	v_cndmask_b32_e32 v26, v26, v38, vcc
	v_cmp_lt_f32_e64 vcc, |v27|, s88
	v_fma_f32 v50, v44, s87, -v50
	v_fmac_f32_e32 v47, 0x3377d1cf, v29
	v_fmac_f32_e32 v46, 0x3f317217, v28
	v_cndmask_b32_e32 v27, v27, v39, vcc
	v_cmp_lt_f32_e64 vcc, |v28|, s88
	v_fmac_f32_e32 v50, 0x3377d1cf, v44
	v_fmac_f32_e32 v47, 0x3f317217, v29
	v_cndmask_b32_e32 v28, v28, v46, vcc
	v_cmp_lt_f32_e64 vcc, |v29|, s88
	v_cndmask_b32_e64 v41, 0, v171, s[0:1]
	v_fmac_f32_e32 v50, 0x3f317217, v44
	v_cndmask_b32_e32 v29, v29, v47, vcc
	v_cmp_lt_f32_e64 vcc, |v44|, s88
	v_cndmask_b32_e64 v42, 0, v171, s[6:7]
	v_sub_f32_e32 v38, v26, v40
	v_sub_f32_e32 v39, v27, v41
	v_cndmask_b32_e32 v26, v44, v50, vcc
	v_cndmask_b32_e64 v27, 0, v171, s[10:11]
	v_sub_f32_e32 v40, v28, v42
	v_sub_f32_e32 v42, v26, v27
	v_mul_f32_e32 v27, 0xbfb8aa3b, v18
	v_mul_f32_e32 v28, 0xbfb8aa3b, v19
	v_exp_f32_e32 v27, v27
	v_exp_f32_e32 v28, v28
	v_cndmask_b32_e64 v43, 0, v171, s[8:9]
	v_mul_f32_e32 v26, 0x3f317217, v45
	v_sub_f32_e32 v41, v29, v43
	v_fma_f32 v43, v45, s87, -v26
	v_add_f32_e32 v26, 1.0, v27
	v_add_f32_e32 v27, 1.0, v28
	v_rcp_f32_e32 v26, v26
	v_rcp_f32_e32 v27, v27
	v_pk_add_f32 v[28:29], v[36:37], 1.0 op_sel_hi:[1,0] neg_lo:[1,0] neg_hi:[1,0]
	v_fmac_f32_e32 v43, 0x3377d1cf, v45
	v_fmac_f32_e32 v43, 0x3f317217, v45
	v_pk_fma_f32 v[26:27], v[26:27], v[28:29], v[36:37]
	v_cmp_lt_f32_e64 s[0:1], |v45|, s88
	v_cmp_gt_f32_e32 vcc, s86, v26
	v_cndmask_b32_e64 v36, 0, v171, s[12:13]
	v_cndmask_b32_e64 v29, v45, v43, s[0:1]
	v_cndmask_b32_e64 v28, 0, 32, vcc
	v_ldexp_f32 v28, v26, v28
	v_log_f32_e32 v28, v28
	v_sub_f32_e32 v43, v29, v36
	v_sub_f32_e32 v24, 1.0, v24
	v_sub_f32_e32 v25, 1.0, v25
	v_mul_f32_e32 v29, 0x3f317217, v28
	v_fma_f32 v29, v28, s87, -v29
	v_fmac_f32_e32 v29, 0x3377d1cf, v28
	v_fmac_f32_e32 v29, 0x3f317217, v28
	v_cmp_lt_f32_e64 s[0:1], |v28|, s88
	v_sub_f32_e32 v34, 1.0, v34
	v_sub_f32_e32 v35, 1.0, v35
	v_cndmask_b32_e64 v28, v28, v29, s[0:1]
	v_cndmask_b32_e32 v29, 0, v171, vcc
	v_cmp_gt_f32_e32 vcc, s86, v27
	v_sub_f32_e32 v44, v28, v29
	v_sub_f32_e32 v29, 1.0, v27
	v_cndmask_b32_e64 v36, 0, 32, vcc
	v_ldexp_f32 v27, v27, v36
	v_log_f32_e32 v36, v27
	v_sub_f32_e32 v28, 1.0, v26
	v_sub_f32_e32 v26, 1.0, v48
	v_sub_f32_e32 v27, 1.0, v49
	v_mul_f32_e32 v37, 0x3f317217, v36
	v_fma_f32 v37, v36, s87, -v37
	v_fmac_f32_e32 v37, 0x3377d1cf, v36
	v_fmac_f32_e32 v37, 0x3f317217, v36
	v_cmp_lt_f32_e64 s[0:1], |v36|, s88
	s_mov_b64 s[6:7], s[16:17]
	s_nop 0
	v_cndmask_b32_e64 v36, v36, v37, s[0:1]
	v_cndmask_b32_e32 v37, 0, v171, vcc
	v_sub_f32_e32 v45, v36, v37
	global_store_dwordx4 v[30:31], v[38:41], off
	global_store_dwordx4 v[30:31], v[42:45], off offset:16

;     __device__ __forceinline__ void operator()(const f32x4 (&acc)[2][2][4][2], const Unit& u, int wr, int wc, int fr, int fq, const Pre& P) const {
;     ...
;                     else if (sec == 1) { dst = KB; const f32x4 l0 = *(const f32x4*)(LBv + c), l1 = *(const f32x4*)(LBv + c + 4); float lf[8];
.LBB0_898:
	v_lshlrev_b32_e32 v19, 2, v138
	v_mov_b32_e32 v22, v238
	v_mov_b32_e32 v23, v239
	v_mov_b32_e32 v24, v240
	v_mov_b32_e32 v25, v241
	v_mov_b32_e32 v26, v242
	v_mov_b32_e32 v27, v243
	v_mov_b32_e32 v28, v244
	v_mov_b32_e32 v29, v245

; __device__ __forceinline__ float fexp(float x) { return __builtin_amdgcn_exp2f(x * 1.4426950408889634f); }
; __device__ __forceinline__ float sigmoidf_(float x) { return __builtin_amdgcn_rcpf(1.0f + fexp(-x)); }
;     __device__ __forceinline__ void operator()(const f32x4 (&acc)[2][2][4][2], const Unit& u, int wr, int wc, int fr, int fq, const Pre& P) const {
;     ...
;                         for (int j = 0; j < 8; ++j) { const float lb = j < 4 ? l0[j] : l1[j - 4]; const float fg = lb + (1.0f - lb) * sigmoidf_(x[j]); y[j] = 1.0f - fg; lf[j] = __logf(fg); }
	v_mul_f32_e32 v19, 0xbfb8aa3b, v12
	v_mul_f32_e32 v30, 0xbfb8aa3b, v13
	v_mul_f32_e32 v31, 0xbfb8aa3b, v14
	v_exp_f32_e32 v19, v19
	v_exp_f32_e32 v30, v30
	v_mul_f32_e32 v32, 0xbfb8aa3b, v15
	v_exp_f32_e32 v31, v31
	v_mul_f32_e32 v33, 0xbfb8aa3b, v20
	v_exp_f32_e32 v32, v32
	v_mul_f32_e32 v34, 0xbfb8aa3b, v21
	v_exp_f32_e32 v33, v33
	v_exp_f32_e32 v34, v34
	v_add_f32_e32 v19, 1.0, v19
	v_add_f32_e32 v35, 1.0, v30
	v_add_f32_e32 v36, 1.0, v31
	v_rcp_f32_e32 v30, v19
	v_rcp_f32_e32 v31, v35
	v_add_f32_e32 v37, 1.0, v32
	v_add_f32_e32 v38, 1.0, v33
	v_rcp_f32_e32 v32, v36
	v_rcp_f32_e32 v33, v37
	v_add_f32_e32 v39, 1.0, v34
	v_rcp_f32_e32 v34, v38
	v_rcp_f32_e32 v35, v39

; __device__ __forceinline__ float sigmoidf_(float x) { return __builtin_amdgcn_rcpf(1.0f + fexp(-x)); }
;     __device__ __forceinline__ void operator()(const f32x4 (&acc)[2][2][4][2], const Unit& u, int wr, int wc, int fr, int fq, const Pre& P) const {
;     ...
;                     else if (sec == 1) { dst = KB; const f32x4 l0 = *(const f32x4*)(LBv + c), l1 = *(const f32x4*)(LBv + c + 4); float lf[8];
; #pragma unroll
;                         for (int j = 0; j < 8; ++j) { const float lb = j < 4 ? l0[j] : l1[j - 4]; const float fg = lb + (1.0f - lb) * sigmoidf_(x[j]); y[j] = 1.0f - fg; lf[j] = __logf(fg); }
;                         *(f32x4*)(LF + off) = (f32x4){lf[0], lf[1], lf[2], lf[3]}; *(f32x4*)(LF + off + 4) = (f32x4){lf[4], lf[5], lf[6], lf[7]}; }
	v_pk_add_f32 v[36:37], v[22:23], 1.0 op_sel_hi:[1,0] neg_lo:[1,0] neg_hi:[1,0]
	s_nop 0
	v_pk_fma_f32 v[42:43], v[30:31], v[36:37], v[22:23]
	v_pk_add_f32 v[38:39], v[24:25], 1.0 op_sel_hi:[1,0] neg_lo:[1,0] neg_hi:[1,0]
	v_cmp_gt_f32_e32 vcc, s86, v42
	v_pk_fma_f32 v[22:23], v[32:33], v[38:39], v[24:25]
	v_cmp_gt_f32_e64 s[0:1], s86, v43
	v_cndmask_b32_e64 v19, 0, 32, vcc
	v_pk_add_f32 v[40:41], v[26:27], 1.0 op_sel_hi:[1,0] neg_lo:[1,0] neg_hi:[1,0]
	v_cndmask_b32_e64 v24, 0, 32, s[0:1]
	v_cmp_gt_f32_e64 s[6:7], s86, v22
	v_ldexp_f32 v19, v42, v19
	v_pk_fma_f32 v[38:39], v[34:35], v[40:41], v[26:27]
	v_cndmask_b32_e64 v25, 0, 32, s[6:7]
	v_ldexp_f32 v24, v43, v24
	v_log_f32_e32 v19, v19
	v_cmp_gt_f32_e64 s[12:13], s86, v39
	v_ldexp_f32 v25, v22, v25
	v_log_f32_e32 v24, v24
	v_cndmask_b32_e64 v30, 0, 32, s[12:13]
	v_log_f32_e32 v25, v25
	v_ldexp_f32 v30, v39, v30
	v_log_f32_e32 v35, v30
	v_mul_f32_e32 v30, 0x3f317217, v19
	v_mul_f32_e32 v36, 0x3f317217, v24
	v_fma_f32 v30, v19, s87, -v30
	v_mul_f32_e32 v37, 0x3f317217, v25
	v_fma_f32 v36, v24, s87, -v36
	v_fmac_f32_e32 v30, 0x3377d1cf, v19
	v_cmp_gt_f32_e64 s[8:9], s86, v23
	v_cndmask_b32_e32 v31, 0, v171, vcc
	v_fma_f32 v37, v25, s87, -v37
	v_fmac_f32_e32 v36, 0x3377d1cf, v24
	v_fmac_f32_e32 v30, 0x3f317217, v19
	v_cmp_lt_f32_e64 vcc, |v19|, s88
	v_cndmask_b32_e64 v26, 0, 32, s[8:9]
	v_cmp_gt_f32_e64 s[10:11], s86, v38
	v_fmac_f32_e32 v37, 0x3377d1cf, v25
	v_fmac_f32_e32 v36, 0x3f317217, v24
	v_cndmask_b32_e32 v19, v19, v30, vcc
	v_cmp_lt_f32_e64 vcc, |v24|, s88
	v_cndmask_b32_e64 v27, 0, 32, s[10:11]
	v_ldexp_f32 v26, v23, v26
	v_fmac_f32_e32 v37, 0x3f317217, v25
	v_cndmask_b32_e32 v24, v24, v36, vcc
	v_cmp_lt_f32_e64 vcc, |v25|, s88
	v_cndmask_b32_e64 v32, 0, v171, s[0:1]
	v_cndmask_b32_e64 v33, 0, v171, s[6:7]
	v_ldexp_f32 v27, v38, v27
	v_log_f32_e32 v26, v26
	v_cndmask_b32_e32 v25, v25, v37, vcc
	v_log_f32_e32 v27, v27
	v_sub_f32_e32 v30, v19, v31
	v_sub_f32_e32 v31, v24, v32
	v_sub_f32_e32 v32, v25, v33
	v_mul_f32_e32 v24, 0xbfb8aa3b, v10
	v_mul_f32_e32 v25, 0xbfb8aa3b, v11
	v_exp_f32_e32 v24, v24
	v_exp_f32_e32 v25, v25
	v_mul_f32_e32 v40, 0x3f317217, v26
	v_mul_f32_e32 v41, 0x3f317217, v27
	v_fma_f32 v40, v26, s87, -v40
	v_fma_f32 v41, v27, s87, -v41
	v_fmac_f32_e32 v40, 0x3377d1cf, v26
	v_add_f32_e32 v24, 1.0, v24
	v_add_f32_e32 v25, 1.0, v25
	v_fmac_f32_e32 v41, 0x3377d1cf, v27
	v_fmac_f32_e32 v40, 0x3f317217, v26
	v_cmp_lt_f32_e64 vcc, |v26|, s88
	v_rcp_f32_e32 v24, v24
	v_rcp_f32_e32 v25, v25
	v_fmac_f32_e32 v41, 0x3f317217, v27
	v_cndmask_b32_e32 v26, v26, v40, vcc
	v_cmp_lt_f32_e64 vcc, |v27|, s88
	v_cndmask_b32_e64 v34, 0, v171, s[8:9]
	v_cndmask_b32_e64 v19, 0, v171, s[10:11]
	v_cndmask_b32_e32 v27, v27, v41, vcc
	v_sub_f32_e32 v33, v26, v34
	v_sub_f32_e32 v34, v27, v19
	v_pk_add_f32 v[26:27], v[28:29], 1.0 op_sel_hi:[1,0] neg_lo:[1,0] neg_hi:[1,0]
	v_mul_f32_e32 v19, 0x3f317217, v35
	v_pk_fma_f32 v[24:25], v[24:25], v[26:27], v[28:29]
	v_fma_f32 v19, v35, s87, -v19
	v_cmp_gt_f32_e32 vcc, s86, v24
	v_fmac_f32_e32 v19, 0x3377d1cf, v35
	v_fmac_f32_e32 v19, 0x3f317217, v35
	v_cndmask_b32_e64 v26, 0, 32, vcc
	v_ldexp_f32 v26, v24, v26
	v_log_f32_e32 v26, v26
	v_cmp_lt_f32_e64 s[0:1], |v35|, s88
	v_cndmask_b32_e64 v27, 0, v171, s[12:13]
	v_sub_f32_e32 v22, 1.0, v22
	v_cndmask_b32_e64 v19, v35, v19, s[0:1]
	v_sub_f32_e32 v35, v19, v27
	v_mul_f32_e32 v19, 0x3f317217, v26
	v_fma_f32 v19, v26, s87, -v19
	v_fmac_f32_e32 v19, 0x3377d1cf, v26
	v_fmac_f32_e32 v19, 0x3f317217, v26
	v_cmp_lt_f32_e64 s[0:1], |v26|, s88
	v_sub_f32_e32 v23, 1.0, v23
	v_sub_f32_e32 v27, 1.0, v25
	v_cndmask_b32_e64 v19, v26, v19, s[0:1]
	v_cndmask_b32_e32 v26, 0, v171, vcc
	v_cmp_gt_f32_e32 vcc, s86, v25
	v_sub_f32_e32 v36, v19, v26
	v_sub_f32_e32 v26, 1.0, v24
	v_cndmask_b32_e64 v19, 0, 32, vcc
	v_ldexp_f32 v19, v25, v19
	v_log_f32_e32 v19, v19
	v_sub_f32_e32 v24, 1.0, v42
	v_sub_f32_e32 v25, 1.0, v43
	v_sub_f32_e32 v28, 1.0, v38
	v_mul_f32_e32 v37, 0x3f317217, v19
	v_fma_f32 v37, v19, s87, -v37
	v_fmac_f32_e32 v37, 0x3377d1cf, v19
	v_fmac_f32_e32 v37, 0x3f317217, v19
	v_cmp_lt_f32_e64 s[0:1], |v19|, s88
	v_sub_f32_e32 v29, 1.0, v39
	v_lshl_add_u64 v[38:39], v[8:9], 2, s[22:23]
	v_cndmask_b32_e64 v19, v19, v37, s[0:1]
	v_cndmask_b32_e32 v37, 0, v171, vcc
	s_mov_b64 s[6:7], s[16:17]
	v_sub_f32_e32 v37, v19, v37
	global_store_dwordx4 v[38:39], v[30:33], off
	global_store_dwordx4 v[38:39], v[34:37], off offset:16

;     __device__ __forceinline__ void operator()(const f32x4 (&acc)[2][2][4][2], const Unit& u, int wr, int wc, int fr, int fq, const Pre& P) const {
;     ...
;                     else if (sec == 1) { dst = KB; const f32x4 l0 = *(const f32x4*)(LBv + c), l1 = *(const f32x4*)(LBv + c + 4); float lf[8];
.LBB0_912:
	v_lshlrev_b32_e32 v12, 2, v154
	v_mov_b32_e32 v8, v246
	v_mov_b32_e32 v9, v247
	v_mov_b32_e32 v10, v248
	v_mov_b32_e32 v11, v249
	v_mov_b32_e32 v18, v250
	v_mov_b32_e32 v19, v251
	v_mov_b32_e32 v20, v252
	v_mov_b32_e32 v21, v253

; __device__ __forceinline__ float fexp(float x) { return __builtin_amdgcn_exp2f(x * 1.4426950408889634f); }
; __device__ __forceinline__ float sigmoidf_(float x) { return __builtin_amdgcn_rcpf(1.0f + fexp(-x)); }
;     __device__ __forceinline__ void operator()(const f32x4 (&acc)[2][2][4][2], const Unit& u, int wr, int wc, int fr, int fq, const Pre& P) const {
;     ...
;                         for (int j = 0; j < 8; ++j) { const float lb = j < 4 ? l0[j] : l1[j - 4]; const float fg = lb + (1.0f - lb) * sigmoidf_(x[j]); y[j] = 1.0f - fg; lf[j] = __logf(fg); }
;                         *(f32x4*)(LF + off) = (f32x4){lf[0], lf[1], lf[2], lf[3]}; *(f32x4*)(LF + off + 4) = (f32x4){lf[4], lf[5], lf[6], lf[7]}; }
	v_mul_f32_e32 v12, 0xbfb8aa3b, v4
	v_mul_f32_e32 v13, 0xbfb8aa3b, v5
	v_exp_f32_e32 v12, v12
	v_exp_f32_e32 v13, v13
	v_mul_f32_e32 v22, 0xbfb8aa3b, v6
	v_mul_f32_e32 v23, 0xbfb8aa3b, v7
	v_exp_f32_e32 v22, v22
	v_exp_f32_e32 v23, v23
	v_mul_f32_e32 v24, 0xbfb8aa3b, v0
	v_mul_f32_e32 v25, 0xbfb8aa3b, v1
	v_exp_f32_e32 v24, v24
	v_exp_f32_e32 v25, v25
	v_add_f32_e32 v12, 1.0, v12
	v_add_f32_e32 v13, 1.0, v13
	v_rcp_f32_e32 v12, v12
	v_rcp_f32_e32 v13, v13
	v_add_f32_e32 v22, 1.0, v22
	v_add_f32_e32 v23, 1.0, v23
	v_rcp_f32_e32 v22, v22
	v_rcp_f32_e32 v23, v23
	v_add_f32_e32 v24, 1.0, v24
	v_add_f32_e32 v25, 1.0, v25
	v_rcp_f32_e32 v24, v24
	v_rcp_f32_e32 v25, v25
	v_or_b32_e32 v14, v16, v154
	v_mov_b32_e32 v15, v17
	v_lshl_add_u64 v[14:15], v[14:15], 2, s[22:23]

; __device__ __forceinline__ float sigmoidf_(float x) { return __builtin_amdgcn_rcpf(1.0f + fexp(-x)); }
;     __device__ __forceinline__ void operator()(const f32x4 (&acc)[2][2][4][2], const Unit& u, int wr, int wc, int fr, int fq, const Pre& P) const {
;     ...
;                     else if (sec == 1) { dst = KB; const f32x4 l0 = *(const f32x4*)(LBv + c), l1 = *(const f32x4*)(LBv + c + 4); float lf[8];
; #pragma unroll
;                         for (int j = 0; j < 8; ++j) { const float lb = j < 4 ? l0[j] : l1[j - 4]; const float fg = lb + (1.0f - lb) * sigmoidf_(x[j]); y[j] = 1.0f - fg; lf[j] = __logf(fg); }
;                         *(f32x4*)(LF + off) = (f32x4){lf[0], lf[1], lf[2], lf[3]}; *(f32x4*)(LF + off + 4) = (f32x4){lf[4], lf[5], lf[6], lf[7]}; }
	v_pk_add_f32 v[26:27], v[8:9], 1.0 op_sel_hi:[1,0] neg_lo:[1,0] neg_hi:[1,0]
	s_nop 0
	v_pk_fma_f32 v[32:33], v[12:13], v[26:27], v[8:9]
	v_pk_add_f32 v[28:29], v[10:11], 1.0 op_sel_hi:[1,0] neg_lo:[1,0] neg_hi:[1,0]
	v_cmp_gt_f32_e32 vcc, s86, v32
	v_pk_fma_f32 v[8:9], v[22:23], v[28:29], v[10:11]
	v_cmp_gt_f32_e64 s[0:1], s86, v33
	v_cndmask_b32_e64 v10, 0, 32, vcc
	v_pk_add_f32 v[30:31], v[18:19], 1.0 op_sel_hi:[1,0] neg_lo:[1,0] neg_hi:[1,0]
	v_cndmask_b32_e64 v11, 0, 32, s[0:1]
	v_cmp_gt_f32_e64 s[4:5], s86, v8
	v_ldexp_f32 v10, v32, v10
	v_pk_fma_f32 v[18:19], v[24:25], v[30:31], v[18:19]
	v_cndmask_b32_e64 v12, 0, 32, s[4:5]
	v_cmp_gt_f32_e64 s[6:7], s86, v9
	v_ldexp_f32 v11, v33, v11
	v_log_f32_e32 v10, v10
	v_cndmask_b32_e64 v13, 0, 32, s[6:7]
	v_cmp_gt_f32_e64 s[8:9], s86, v18
	v_ldexp_f32 v12, v8, v12
	v_log_f32_e32 v11, v11
	v_cndmask_b32_e64 v22, 0, 32, s[8:9]
	v_cmp_gt_f32_e64 s[10:11], s86, v19
	v_ldexp_f32 v13, v9, v13
	v_log_f32_e32 v12, v12
	v_cndmask_b32_e64 v23, 0, 32, s[10:11]
	v_ldexp_f32 v22, v18, v22
	v_log_f32_e32 v13, v13
	v_ldexp_f32 v23, v19, v23
	v_log_f32_e32 v28, v22
	v_mul_f32_e32 v22, 0x3f317217, v10
	v_log_f32_e32 v29, v23
	v_mul_f32_e32 v23, 0x3f317217, v11
	v_fma_f32 v22, v10, s87, -v22
	v_mul_f32_e32 v30, 0x3f317217, v12
	v_fma_f32 v23, v11, s87, -v23
	v_fmac_f32_e32 v22, 0x3377d1cf, v10
	v_cndmask_b32_e32 v24, 0, v171, vcc
	v_mul_f32_e32 v31, 0x3f317217, v13
	v_fma_f32 v30, v12, s87, -v30
	v_fmac_f32_e32 v23, 0x3377d1cf, v11
	v_fmac_f32_e32 v22, 0x3f317217, v10
	v_cmp_lt_f32_e64 vcc, |v10|, s88
	v_mul_f32_e32 v34, 0x3f317217, v28
	v_fma_f32 v31, v13, s87, -v31
	v_fmac_f32_e32 v30, 0x3377d1cf, v12
	v_fmac_f32_e32 v23, 0x3f317217, v11
	v_cndmask_b32_e32 v10, v10, v22, vcc
	v_cmp_lt_f32_e64 vcc, |v11|, s88
	v_fma_f32 v34, v28, s87, -v34
	v_fmac_f32_e32 v31, 0x3377d1cf, v13
	v_fmac_f32_e32 v30, 0x3f317217, v12
	v_cndmask_b32_e32 v11, v11, v23, vcc
	v_cmp_lt_f32_e64 vcc, |v12|, s88
	v_fmac_f32_e32 v34, 0x3377d1cf, v28
	v_fmac_f32_e32 v31, 0x3f317217, v13
	v_cndmask_b32_e32 v12, v12, v30, vcc
	v_cmp_lt_f32_e64 vcc, |v13|, s88
	v_cndmask_b32_e64 v25, 0, v171, s[0:1]
	v_fmac_f32_e32 v34, 0x3f317217, v28
	v_cndmask_b32_e32 v13, v13, v31, vcc
	v_cmp_lt_f32_e64 vcc, |v28|, s88
	v_cndmask_b32_e64 v26, 0, v171, s[4:5]
	v_sub_f32_e32 v22, v10, v24
	v_sub_f32_e32 v23, v11, v25
	v_cndmask_b32_e32 v10, v28, v34, vcc
	v_cndmask_b32_e64 v11, 0, v171, s[8:9]
	v_sub_f32_e32 v24, v12, v26
	v_sub_f32_e32 v26, v10, v11
	v_mul_f32_e32 v11, 0xbfb8aa3b, v2
	v_mul_f32_e32 v12, 0xbfb8aa3b, v3
	v_exp_f32_e32 v11, v11
	v_exp_f32_e32 v12, v12
	v_cndmask_b32_e64 v27, 0, v171, s[6:7]
	v_mul_f32_e32 v10, 0x3f317217, v29
	v_sub_f32_e32 v25, v13, v27
	v_fma_f32 v27, v29, s87, -v10
	v_add_f32_e32 v10, 1.0, v11
	v_add_f32_e32 v11, 1.0, v12
	v_rcp_f32_e32 v10, v10
	v_rcp_f32_e32 v11, v11
	v_pk_add_f32 v[12:13], v[20:21], 1.0 op_sel_hi:[1,0] neg_lo:[1,0] neg_hi:[1,0]
	v_fmac_f32_e32 v27, 0x3377d1cf, v29
	v_fmac_f32_e32 v27, 0x3f317217, v29
	v_pk_fma_f32 v[10:11], v[10:11], v[12:13], v[20:21]
	v_cmp_lt_f32_e64 s[0:1], |v29|, s88
	v_cmp_gt_f32_e32 vcc, s86, v10
	v_cndmask_b32_e64 v20, 0, v171, s[10:11]
	v_cndmask_b32_e64 v13, v29, v27, s[0:1]
	v_cndmask_b32_e64 v12, 0, 32, vcc
	v_ldexp_f32 v12, v10, v12
	v_log_f32_e32 v12, v12
	v_sub_f32_e32 v27, v13, v20
	v_sub_f32_e32 v8, 1.0, v8
	v_sub_f32_e32 v9, 1.0, v9
	v_mul_f32_e32 v13, 0x3f317217, v12
	v_fma_f32 v13, v12, s87, -v13
	v_fmac_f32_e32 v13, 0x3377d1cf, v12
	v_fmac_f32_e32 v13, 0x3f317217, v12
	v_cmp_lt_f32_e64 s[0:1], |v12|, s88
	v_sub_f32_e32 v18, 1.0, v18
	v_sub_f32_e32 v19, 1.0, v19
	v_cndmask_b32_e64 v12, v12, v13, s[0:1]
	v_cndmask_b32_e32 v13, 0, v171, vcc
	v_cmp_gt_f32_e32 vcc, s86, v11
	v_sub_f32_e32 v28, v12, v13
	v_sub_f32_e32 v13, 1.0, v11
	v_cndmask_b32_e64 v20, 0, 32, vcc
	v_ldexp_f32 v11, v11, v20
	v_log_f32_e32 v20, v11
	v_sub_f32_e32 v12, 1.0, v10
	v_sub_f32_e32 v10, 1.0, v32
	v_sub_f32_e32 v11, 1.0, v33
	v_mul_f32_e32 v21, 0x3f317217, v20
	v_fma_f32 v21, v20, s87, -v21
	v_fmac_f32_e32 v21, 0x3377d1cf, v20
	v_fmac_f32_e32 v21, 0x3f317217, v20
	v_cmp_lt_f32_e64 s[0:1], |v20|, s88
	s_mov_b64 s[4:5], s[16:17]
	s_nop 0
	v_cndmask_b32_e64 v20, v20, v21, s[0:1]
	v_cndmask_b32_e32 v21, 0, v171, vcc
	v_sub_f32_e32 v29, v20, v21
	global_store_dwordx4 v[14:15], v[22:25], off
	global_store_dwordx4 v[14:15], v[26:29], off offset:16
